# K-loop iteration counter folded into the K-offset compare (2 fewer scalar instructions per iteration) on top of v96
# speedup vs baseline: 1.0068x; 1.0003x over previous
.LBB0_161:
	s_add_u32 s86, s69, s6
	s_addc_u32 s87, s70, s7
	s_add_u32 s88, s71, s8
	s_addc_u32 s89, s72, s9
	s_ashr_i32 s23, s22, 31
	s_lshl_b64 s[6:7], s[22:23], 19
	s_add_u32 s24, s34, s6
	s_addc_u32 s25, s35, s7
	s_and_b64 s[8:9], s[0:1], exec
	s_cselect_b32 s23, s25, s43
	s_cselect_b32 s90, s24, s42
	s_ashr_i32 s21, s20, 31
	s_lshl_b64 s[8:9], s[20:21], 19
	s_add_u32 s26, s17, s8
	s_addc_u32 s27, s19, s9
	s_and_b64 s[48:49], s[0:1], exec
	s_cselect_b32 s21, s27, s39
	s_cselect_b32 s91, s26, s38
	s_add_u32 s48, s90, 0x80
	s_addc_u32 s49, s23, 0
	s_add_u32 s54, s91, 0x80
	s_addc_u32 s55, s21, 0
	v_lshl_add_u64 v[128:129], s[42:43], 0, v[150:151]
	v_lshl_add_u64 v[130:131], s[42:43], 0, v[152:153]
	s_mov_b32 s92, 0
	s_mov_b64 s[56:57], 0
	v_add_u32_e32 v232, 0x10000, v171
	s_add_u32 s64, s42, s56
	s_addc_u32 s65, s43, s57
	s_mov_b64 s[100:101], s[64:65]
	s_add_u32 s94, s38, s56
	s_addc_u32 s93, s39, s57
	s_add_u32 s58, s64, 0x180
	s_addc_u32 s59, s65, 0
	s_add_u32 s60, s94, 0x180
	s_addc_u32 s61, s93, 0
	s_add_u32 s64, s64, 0x100
	s_addc_u32 s65, s65, 0
	s_add_u32 s62, s94, 0x100
	s_addc_u32 s63, s93, 0
	s_cmpk_eq_i32 s56, 0x700
	s_cselect_b32 s58, s48, s58
	s_cselect_b32 s59, s49, s59
	s_cselect_b32 s60, s54, s60
	s_cselect_b32 s61, s55, s61
	s_cselect_b32 s64, s90, s64
	s_cselect_b32 s65, s23, s65
	s_cselect_b32 s62, s91, s62
	s_cselect_b32 s63, s21, s63
	ds_read_b128 v[132:135], v232
	ds_read_b128 v[158:161], v232 offset:1024
	ds_read_b128 v[162:165], v232 offset:2048
	ds_read_b128 v[166:169], v232 offset:3072
	ds_read_b128 v[184:187], v232 offset:16384
	ds_read_b128 v[188:191], v232 offset:17408
	ds_read_b128 v[192:195], v232 offset:18432
	ds_read_b128 v[196:199], v232 offset:19456
	s_add_i32 m0, s29, 0xc000
	ds_read_b128 v[200:203], v181
	ds_read_b128 v[204:207], v181 offset:1024
	ds_read_b128 v[208:211], v181 offset:2048
	ds_read_b128 v[212:215], v181 offset:3072
	ds_read_b128 v[216:219], v181 offset:4096
	ds_read_b128 v[220:223], v181 offset:5120
	ds_read_b128 v[224:227], v181 offset:6144
	global_load_lds_dwordx4 v150, s[100:101]
	s_add_i32 m0, s29, 0xe000
	ds_read_b128 v[228:231], v181 offset:7168
	global_load_lds_dwordx4 v152, s[100:101]
	s_waitcnt vmcnt(8)
	s_waitcnt lgkmcnt(0)
	s_setprio 1
	s_barrier
	v_mfma_f32_16x16x32_bf16 v[124:127], v[132:135], v[200:203], 0
	v_mfma_f32_16x16x32_bf16 v[120:123], v[162:165], v[200:203], 0
	v_mfma_f32_16x16x32_bf16 v[108:111], v[132:135], v[208:211], 0
	v_mfma_f32_16x16x32_bf16 v[104:107], v[162:165], v[208:211], 0
	v_mfma_f32_16x16x32_bf16 v[92:95], v[132:135], v[216:219], 0
	v_mfma_f32_16x16x32_bf16 v[88:91], v[162:165], v[216:219], 0
	v_mfma_f32_16x16x32_bf16 v[76:79], v[132:135], v[224:227], 0
	v_mfma_f32_16x16x32_bf16 v[72:75], v[162:165], v[224:227], 0
	v_mfma_f32_16x16x32_bf16 v[124:127], v[158:161], v[204:207], v[124:127]
	v_mfma_f32_16x16x32_bf16 v[120:123], v[166:169], v[204:207], v[120:123]
	v_mfma_f32_16x16x32_bf16 v[108:111], v[158:161], v[212:215], v[108:111]
	v_mfma_f32_16x16x32_bf16 v[104:107], v[166:169], v[212:215], v[104:107]
	v_mfma_f32_16x16x32_bf16 v[92:95], v[158:161], v[220:223], v[92:95]
	v_mfma_f32_16x16x32_bf16 v[88:91], v[166:169], v[220:223], v[88:91]
	v_mfma_f32_16x16x32_bf16 v[76:79], v[158:161], v[228:231], v[76:79]
	v_mfma_f32_16x16x32_bf16 v[72:75], v[166:169], v[228:231], v[72:75]
	s_setprio 0
	s_setprio 1
	v_mfma_f32_16x16x32_bf16 v[116:119], v[184:187], v[200:203], 0
	v_mfma_f32_16x16x32_bf16 v[112:115], v[192:195], v[200:203], 0
	v_mfma_f32_16x16x32_bf16 v[100:103], v[184:187], v[208:211], 0
	v_mfma_f32_16x16x32_bf16 v[96:99], v[192:195], v[208:211], 0
	v_mfma_f32_16x16x32_bf16 v[84:87], v[184:187], v[216:219], 0
	v_mfma_f32_16x16x32_bf16 v[80:83], v[192:195], v[216:219], 0
	v_mfma_f32_16x16x32_bf16 v[68:71], v[184:187], v[224:227], 0
	v_mfma_f32_16x16x32_bf16 v[64:67], v[192:195], v[224:227], 0
	v_mfma_f32_16x16x32_bf16 v[116:119], v[188:191], v[204:207], v[116:119]
	v_mfma_f32_16x16x32_bf16 v[112:115], v[196:199], v[204:207], v[112:115]
	v_mfma_f32_16x16x32_bf16 v[100:103], v[188:191], v[212:215], v[100:103]
	v_mfma_f32_16x16x32_bf16 v[96:99], v[196:199], v[212:215], v[96:99]
	v_mfma_f32_16x16x32_bf16 v[84:87], v[188:191], v[220:223], v[84:87]
	v_mfma_f32_16x16x32_bf16 v[80:83], v[196:199], v[220:223], v[80:83]
	v_mfma_f32_16x16x32_bf16 v[68:71], v[188:191], v[228:231], v[68:71]
	v_mfma_f32_16x16x32_bf16 v[64:67], v[196:199], v[228:231], v[64:67]
	s_barrier
	s_setprio 0
	s_add_i32 s10, s82, s66
	s_mov_b32 m0, s10
	ds_read_b128 v[200:203], v181 offset:16384
	ds_read_b128 v[204:207], v181 offset:17408
	ds_read_b128 v[208:211], v181 offset:18432
	global_load_lds_dwordx4 v138, s[62:63]
	s_add_i32 m0, s10, 0x2000
	ds_read_b128 v[212:215], v181 offset:19456
	global_load_lds_dwordx4 v142, s[62:63]
	s_add_u32 s62, s62, 0x40000
	s_addc_u32 s63, s63, 0
	s_add_i32 s10, s83, s66
	s_mov_b32 m0, s10
	ds_read_b128 v[216:219], v181 offset:20480
	global_load_lds_dwordx4 v138, s[62:63]
	s_add_i32 m0, s10, 0x2000
	ds_read_b128 v[220:223], v181 offset:21504
	global_load_lds_dwordx4 v142, s[62:63]
	s_mov_b32 m0, s29
	ds_read_b128 v[224:227], v181 offset:22528
	global_load_lds_dwordx4 v136, s[64:65]
	s_mov_b32 m0, s31
	ds_read_b128 v[228:231], v181 offset:23552
	global_load_lds_dwordx4 v140, s[64:65]
	s_waitcnt vmcnt(8)
	s_waitcnt lgkmcnt(0)
	s_setprio 1
	s_barrier
	v_mfma_f32_16x16x32_bf16 v[60:63], v[132:135], v[200:203], 0
	v_mfma_f32_16x16x32_bf16 v[56:59], v[162:165], v[200:203], 0
	v_mfma_f32_16x16x32_bf16 v[44:47], v[132:135], v[208:211], 0
	v_mfma_f32_16x16x32_bf16 v[40:43], v[162:165], v[208:211], 0
	v_mfma_f32_16x16x32_bf16 v[28:31], v[132:135], v[216:219], 0
	v_mfma_f32_16x16x32_bf16 v[24:27], v[162:165], v[216:219], 0
	v_mfma_f32_16x16x32_bf16 v[12:15], v[132:135], v[224:227], 0
	v_mfma_f32_16x16x32_bf16 v[8:11], v[162:165], v[224:227], 0
	v_mfma_f32_16x16x32_bf16 v[60:63], v[158:161], v[204:207], v[60:63]
	v_mfma_f32_16x16x32_bf16 v[56:59], v[166:169], v[204:207], v[56:59]
	v_mfma_f32_16x16x32_bf16 v[44:47], v[158:161], v[212:215], v[44:47]
	v_mfma_f32_16x16x32_bf16 v[40:43], v[166:169], v[212:215], v[40:43]
	v_mfma_f32_16x16x32_bf16 v[28:31], v[158:161], v[220:223], v[28:31]
	v_mfma_f32_16x16x32_bf16 v[24:27], v[166:169], v[220:223], v[24:27]
	v_mfma_f32_16x16x32_bf16 v[12:15], v[158:161], v[228:231], v[12:15]
	v_mfma_f32_16x16x32_bf16 v[8:11], v[166:169], v[228:231], v[8:11]
	s_setprio 0
	s_setprio 1
	v_mfma_f32_16x16x32_bf16 v[52:55], v[184:187], v[200:203], 0
	v_mfma_f32_16x16x32_bf16 v[48:51], v[192:195], v[200:203], 0
	v_mfma_f32_16x16x32_bf16 v[36:39], v[184:187], v[208:211], 0
	v_mfma_f32_16x16x32_bf16 v[32:35], v[192:195], v[208:211], 0
	v_mfma_f32_16x16x32_bf16 v[20:23], v[184:187], v[216:219], 0
	v_mfma_f32_16x16x32_bf16 v[16:19], v[192:195], v[216:219], 0
	v_mfma_f32_16x16x32_bf16 v[4:7], v[184:187], v[224:227], 0
	v_mfma_f32_16x16x32_bf16 v[0:3], v[192:195], v[224:227], 0
	v_mfma_f32_16x16x32_bf16 v[52:55], v[188:191], v[204:207], v[52:55]
	v_mfma_f32_16x16x32_bf16 v[48:51], v[196:199], v[204:207], v[48:51]
	v_mfma_f32_16x16x32_bf16 v[36:39], v[188:191], v[212:215], v[36:39]
	v_mfma_f32_16x16x32_bf16 v[32:35], v[196:199], v[212:215], v[32:35]
	v_mfma_f32_16x16x32_bf16 v[20:23], v[188:191], v[220:223], v[20:23]
	v_mfma_f32_16x16x32_bf16 v[16:19], v[196:199], v[220:223], v[16:19]
	v_mfma_f32_16x16x32_bf16 v[4:7], v[188:191], v[228:231], v[4:7]
	v_mfma_f32_16x16x32_bf16 v[0:3], v[196:199], v[228:231], v[0:3]
	s_barrier
	s_setprio 0
	s_add_i32 s10, 0, 0x18000
	s_add_i32 s93, 0, 0x1c000
	ds_read_b128 v[132:135], v232 offset:32768
	ds_read_b128 v[158:161], v232 offset:33792
	ds_read_b128 v[162:165], v232 offset:34816
	ds_read_b128 v[166:169], v232 offset:35840
	ds_read_b128 v[184:187], v232 offset:49152
	ds_read_b128 v[188:191], v232 offset:50176
	ds_read_b128 v[192:195], v232 offset:51200
	ds_read_b128 v[196:199], v232 offset:52224
	s_add_u32 s62, s64, 0x40000
	s_addc_u32 s63, s65, 0
	s_mov_b32 m0, s67
	ds_read_b128 v[200:203], v181 offset:32768
	ds_read_b128 v[204:207], v181 offset:33792
	ds_read_b128 v[208:211], v181 offset:34816
	ds_read_b128 v[212:215], v181 offset:35840
	ds_read_b128 v[216:219], v181 offset:36864
	ds_read_b128 v[220:223], v181 offset:37888
	ds_read_b128 v[224:227], v181 offset:38912
	global_load_lds_dwordx4 v136, s[62:63]
	s_mov_b32 m0, s68
	ds_read_b128 v[228:231], v181 offset:39936
	global_load_lds_dwordx4 v140, s[62:63]
	s_waitcnt vmcnt(8)
	s_waitcnt lgkmcnt(0)
	s_setprio 1
	s_barrier
	v_mfma_f32_16x16x32_bf16 v[124:127], v[132:135], v[200:203], v[124:127]
	v_mfma_f32_16x16x32_bf16 v[120:123], v[162:165], v[200:203], v[120:123]
	v_mfma_f32_16x16x32_bf16 v[108:111], v[132:135], v[208:211], v[108:111]
	v_mfma_f32_16x16x32_bf16 v[104:107], v[162:165], v[208:211], v[104:107]
	v_mfma_f32_16x16x32_bf16 v[92:95], v[132:135], v[216:219], v[92:95]
	v_mfma_f32_16x16x32_bf16 v[88:91], v[162:165], v[216:219], v[88:91]
	v_mfma_f32_16x16x32_bf16 v[76:79], v[132:135], v[224:227], v[76:79]
	v_mfma_f32_16x16x32_bf16 v[72:75], v[162:165], v[224:227], v[72:75]
	v_mfma_f32_16x16x32_bf16 v[124:127], v[158:161], v[204:207], v[124:127]
	v_mfma_f32_16x16x32_bf16 v[120:123], v[166:169], v[204:207], v[120:123]
	v_mfma_f32_16x16x32_bf16 v[108:111], v[158:161], v[212:215], v[108:111]
	v_mfma_f32_16x16x32_bf16 v[104:107], v[166:169], v[212:215], v[104:107]
	v_mfma_f32_16x16x32_bf16 v[92:95], v[158:161], v[220:223], v[92:95]
	v_mfma_f32_16x16x32_bf16 v[88:91], v[166:169], v[220:223], v[88:91]
	v_mfma_f32_16x16x32_bf16 v[76:79], v[158:161], v[228:231], v[76:79]
	v_mfma_f32_16x16x32_bf16 v[72:75], v[166:169], v[228:231], v[72:75]
	s_setprio 0
	s_setprio 1
	v_mfma_f32_16x16x32_bf16 v[116:119], v[184:187], v[200:203], v[116:119]
	v_mfma_f32_16x16x32_bf16 v[112:115], v[192:195], v[200:203], v[112:115]
	v_mfma_f32_16x16x32_bf16 v[100:103], v[184:187], v[208:211], v[100:103]
	v_mfma_f32_16x16x32_bf16 v[96:99], v[192:195], v[208:211], v[96:99]
	v_mfma_f32_16x16x32_bf16 v[84:87], v[184:187], v[216:219], v[84:87]
	v_mfma_f32_16x16x32_bf16 v[80:83], v[192:195], v[216:219], v[80:83]
	v_mfma_f32_16x16x32_bf16 v[68:71], v[184:187], v[224:227], v[68:71]
	v_mfma_f32_16x16x32_bf16 v[64:67], v[192:195], v[224:227], v[64:67]
	v_mfma_f32_16x16x32_bf16 v[116:119], v[188:191], v[204:207], v[116:119]
	v_mfma_f32_16x16x32_bf16 v[112:115], v[196:199], v[204:207], v[112:115]
	v_mfma_f32_16x16x32_bf16 v[100:103], v[188:191], v[212:215], v[100:103]
	v_mfma_f32_16x16x32_bf16 v[96:99], v[196:199], v[212:215], v[96:99]
	v_mfma_f32_16x16x32_bf16 v[84:87], v[188:191], v[220:223], v[84:87]
	v_mfma_f32_16x16x32_bf16 v[80:83], v[196:199], v[220:223], v[80:83]
	v_mfma_f32_16x16x32_bf16 v[68:71], v[188:191], v[228:231], v[68:71]
	v_mfma_f32_16x16x32_bf16 v[64:67], v[196:199], v[228:231], v[64:67]
	s_barrier
	s_setprio 0
	s_add_i32 s10, s10, s66
	s_mov_b32 m0, s10
	ds_read_b128 v[200:203], v181 offset:49152
	ds_read_b128 v[204:207], v181 offset:50176
	ds_read_b128 v[208:211], v181 offset:51200
	global_load_lds_dwordx4 v138, s[60:61]
	s_add_i32 m0, s10, 0x2000
	ds_read_b128 v[212:215], v181 offset:52224
	global_load_lds_dwordx4 v142, s[60:61]
	s_add_u32 s60, s60, 0x40000
	s_addc_u32 s61, s61, 0
	s_add_i32 s10, s93, s66
	s_mov_b32 m0, s10
	ds_read_b128 v[216:219], v181 offset:53248
	global_load_lds_dwordx4 v138, s[60:61]
	s_add_i32 m0, s10, 0x2000
	ds_read_b128 v[220:223], v181 offset:54272
	global_load_lds_dwordx4 v142, s[60:61]
	s_mov_b32 m0, s73
	ds_read_b128 v[224:227], v181 offset:55296
	global_load_lds_dwordx4 v136, s[58:59]
	s_mov_b32 m0, s78
	ds_read_b128 v[228:231], v181 offset:56320
	global_load_lds_dwordx4 v140, s[58:59]
	s_waitcnt vmcnt(8)
	s_waitcnt lgkmcnt(0)
	s_setprio 1
	s_barrier
	v_mfma_f32_16x16x32_bf16 v[60:63], v[132:135], v[200:203], v[60:63]
	v_mfma_f32_16x16x32_bf16 v[56:59], v[162:165], v[200:203], v[56:59]
	v_mfma_f32_16x16x32_bf16 v[44:47], v[132:135], v[208:211], v[44:47]
	v_mfma_f32_16x16x32_bf16 v[40:43], v[162:165], v[208:211], v[40:43]
	v_mfma_f32_16x16x32_bf16 v[28:31], v[132:135], v[216:219], v[28:31]
	v_mfma_f32_16x16x32_bf16 v[24:27], v[162:165], v[216:219], v[24:27]
	v_mfma_f32_16x16x32_bf16 v[12:15], v[132:135], v[224:227], v[12:15]
	v_mfma_f32_16x16x32_bf16 v[8:11], v[162:165], v[224:227], v[8:11]
	v_mfma_f32_16x16x32_bf16 v[60:63], v[158:161], v[204:207], v[60:63]
	v_mfma_f32_16x16x32_bf16 v[56:59], v[166:169], v[204:207], v[56:59]
	v_mfma_f32_16x16x32_bf16 v[44:47], v[158:161], v[212:215], v[44:47]
	v_mfma_f32_16x16x32_bf16 v[40:43], v[166:169], v[212:215], v[40:43]
	v_mfma_f32_16x16x32_bf16 v[28:31], v[158:161], v[220:223], v[28:31]
	v_mfma_f32_16x16x32_bf16 v[24:27], v[166:169], v[220:223], v[24:27]
	v_mfma_f32_16x16x32_bf16 v[12:15], v[158:161], v[228:231], v[12:15]
	v_mfma_f32_16x16x32_bf16 v[8:11], v[166:169], v[228:231], v[8:11]
	s_setprio 0
	s_setprio 1
	v_mfma_f32_16x16x32_bf16 v[52:55], v[184:187], v[200:203], v[52:55]
	v_mfma_f32_16x16x32_bf16 v[48:51], v[192:195], v[200:203], v[48:51]
	v_mfma_f32_16x16x32_bf16 v[36:39], v[184:187], v[208:211], v[36:39]
	v_mfma_f32_16x16x32_bf16 v[32:35], v[192:195], v[208:211], v[32:35]
	v_mfma_f32_16x16x32_bf16 v[20:23], v[184:187], v[216:219], v[20:23]
	v_mfma_f32_16x16x32_bf16 v[16:19], v[192:195], v[216:219], v[16:19]
	v_mfma_f32_16x16x32_bf16 v[4:7], v[184:187], v[224:227], v[4:7]
	v_mfma_f32_16x16x32_bf16 v[0:3], v[192:195], v[224:227], v[0:3]
	v_mfma_f32_16x16x32_bf16 v[52:55], v[188:191], v[204:207], v[52:55]
	v_mfma_f32_16x16x32_bf16 v[48:51], v[196:199], v[204:207], v[48:51]
	v_mfma_f32_16x16x32_bf16 v[36:39], v[188:191], v[212:215], v[36:39]
	v_mfma_f32_16x16x32_bf16 v[32:35], v[196:199], v[212:215], v[32:35]
	v_mfma_f32_16x16x32_bf16 v[20:23], v[188:191], v[220:223], v[20:23]
	v_mfma_f32_16x16x32_bf16 v[16:19], v[196:199], v[220:223], v[16:19]
	v_mfma_f32_16x16x32_bf16 v[4:7], v[188:191], v[228:231], v[4:7]
	v_mfma_f32_16x16x32_bf16 v[0:3], v[196:199], v[228:231], v[0:3]
	s_barrier
	s_setprio 0
	s_add_u32 s56, s56, 0x100
	s_addc_u32 s57, s57, 0
	s_cmpk_eq_i32 s56, 0x800
	s_cbranch_scc1 .LBB0_169
	s_branch .LBB0_163
.LBB0_162:
	ds_read_b128 v[132:135], v232
	ds_read_b128 v[158:161], v232 offset:1024
	ds_read_b128 v[162:165], v232 offset:2048
	ds_read_b128 v[166:169], v232 offset:3072
	ds_read_b128 v[184:187], v232 offset:16384
	ds_read_b128 v[188:191], v232 offset:17408
	ds_read_b128 v[192:195], v232 offset:18432
	ds_read_b128 v[196:199], v232 offset:19456
	s_add_i32 m0, s29, 0xc000
	ds_read_b128 v[200:203], v181
	ds_read_b128 v[204:207], v181 offset:1024
	ds_read_b128 v[208:211], v181 offset:2048
	ds_read_b128 v[212:215], v181 offset:3072
	ds_read_b128 v[216:219], v181 offset:4096
	ds_read_b128 v[220:223], v181 offset:5120
	ds_read_b128 v[224:227], v181 offset:6144
	global_load_lds_dwordx4 v150, s[100:101]
	s_add_i32 m0, s29, 0xe000
	ds_read_b128 v[228:231], v181 offset:7168
	global_load_lds_dwordx4 v152, s[100:101]
	s_waitcnt vmcnt(8)
	s_waitcnt lgkmcnt(0)
	s_setprio 1
	s_barrier
	v_mfma_f32_16x16x32_bf16 v[124:127], v[132:135], v[200:203], v[124:127]
	v_mfma_f32_16x16x32_bf16 v[120:123], v[162:165], v[200:203], v[120:123]
	v_mfma_f32_16x16x32_bf16 v[108:111], v[132:135], v[208:211], v[108:111]
	v_mfma_f32_16x16x32_bf16 v[104:107], v[162:165], v[208:211], v[104:107]
	v_mfma_f32_16x16x32_bf16 v[92:95], v[132:135], v[216:219], v[92:95]
	v_mfma_f32_16x16x32_bf16 v[88:91], v[162:165], v[216:219], v[88:91]
	v_mfma_f32_16x16x32_bf16 v[76:79], v[132:135], v[224:227], v[76:79]
	v_mfma_f32_16x16x32_bf16 v[72:75], v[162:165], v[224:227], v[72:75]
	v_mfma_f32_16x16x32_bf16 v[124:127], v[158:161], v[204:207], v[124:127]
	v_mfma_f32_16x16x32_bf16 v[120:123], v[166:169], v[204:207], v[120:123]
	v_mfma_f32_16x16x32_bf16 v[108:111], v[158:161], v[212:215], v[108:111]
	v_mfma_f32_16x16x32_bf16 v[104:107], v[166:169], v[212:215], v[104:107]
	v_mfma_f32_16x16x32_bf16 v[92:95], v[158:161], v[220:223], v[92:95]
	v_mfma_f32_16x16x32_bf16 v[88:91], v[166:169], v[220:223], v[88:91]
	v_mfma_f32_16x16x32_bf16 v[76:79], v[158:161], v[228:231], v[76:79]
	v_mfma_f32_16x16x32_bf16 v[72:75], v[166:169], v[228:231], v[72:75]
	s_setprio 0
	s_setprio 1
	v_mfma_f32_16x16x32_bf16 v[116:119], v[184:187], v[200:203], v[116:119]
	v_mfma_f32_16x16x32_bf16 v[112:115], v[192:195], v[200:203], v[112:115]
	v_mfma_f32_16x16x32_bf16 v[100:103], v[184:187], v[208:211], v[100:103]
	v_mfma_f32_16x16x32_bf16 v[96:99], v[192:195], v[208:211], v[96:99]
	v_mfma_f32_16x16x32_bf16 v[84:87], v[184:187], v[216:219], v[84:87]
	v_mfma_f32_16x16x32_bf16 v[80:83], v[192:195], v[216:219], v[80:83]
	v_mfma_f32_16x16x32_bf16 v[68:71], v[184:187], v[224:227], v[68:71]
	v_mfma_f32_16x16x32_bf16 v[64:67], v[192:195], v[224:227], v[64:67]
	v_mfma_f32_16x16x32_bf16 v[116:119], v[188:191], v[204:207], v[116:119]
	v_mfma_f32_16x16x32_bf16 v[112:115], v[196:199], v[204:207], v[112:115]
	v_mfma_f32_16x16x32_bf16 v[100:103], v[188:191], v[212:215], v[100:103]
	v_mfma_f32_16x16x32_bf16 v[96:99], v[196:199], v[212:215], v[96:99]
	v_mfma_f32_16x16x32_bf16 v[84:87], v[188:191], v[220:223], v[84:87]
	v_mfma_f32_16x16x32_bf16 v[80:83], v[196:199], v[220:223], v[80:83]
	v_mfma_f32_16x16x32_bf16 v[68:71], v[188:191], v[228:231], v[68:71]
	v_mfma_f32_16x16x32_bf16 v[64:67], v[196:199], v[228:231], v[64:67]
	s_barrier
	s_setprio 0
	s_add_i32 s10, s82, s66
	s_mov_b32 m0, s10
	ds_read_b128 v[200:203], v181 offset:16384
	ds_read_b128 v[204:207], v181 offset:17408
	ds_read_b128 v[208:211], v181 offset:18432
	global_load_lds_dwordx4 v138, s[62:63]
	s_add_i32 m0, s10, 0x2000
	ds_read_b128 v[212:215], v181 offset:19456
	global_load_lds_dwordx4 v142, s[62:63]
	s_add_u32 s62, s62, 0x40000
	s_addc_u32 s63, s63, 0
	s_add_i32 s10, s83, s66
	s_mov_b32 m0, s10
	ds_read_b128 v[216:219], v181 offset:20480
	global_load_lds_dwordx4 v138, s[62:63]
	s_add_i32 m0, s10, 0x2000
	ds_read_b128 v[220:223], v181 offset:21504
	global_load_lds_dwordx4 v142, s[62:63]
	s_mov_b32 m0, s29
	ds_read_b128 v[224:227], v181 offset:22528
	global_load_lds_dwordx4 v136, s[64:65]
	s_mov_b32 m0, s31
	ds_read_b128 v[228:231], v181 offset:23552
	global_load_lds_dwordx4 v140, s[64:65]
	s_waitcnt vmcnt(8)
	s_waitcnt lgkmcnt(0)
	s_setprio 1
	s_barrier
	v_mfma_f32_16x16x32_bf16 v[60:63], v[132:135], v[200:203], v[60:63]
	v_mfma_f32_16x16x32_bf16 v[56:59], v[162:165], v[200:203], v[56:59]
	v_mfma_f32_16x16x32_bf16 v[44:47], v[132:135], v[208:211], v[44:47]
	v_mfma_f32_16x16x32_bf16 v[40:43], v[162:165], v[208:211], v[40:43]
	v_mfma_f32_16x16x32_bf16 v[28:31], v[132:135], v[216:219], v[28:31]
	v_mfma_f32_16x16x32_bf16 v[24:27], v[162:165], v[216:219], v[24:27]
	v_mfma_f32_16x16x32_bf16 v[12:15], v[132:135], v[224:227], v[12:15]
	v_mfma_f32_16x16x32_bf16 v[8:11], v[162:165], v[224:227], v[8:11]
	v_mfma_f32_16x16x32_bf16 v[60:63], v[158:161], v[204:207], v[60:63]
	v_mfma_f32_16x16x32_bf16 v[56:59], v[166:169], v[204:207], v[56:59]
	v_mfma_f32_16x16x32_bf16 v[44:47], v[158:161], v[212:215], v[44:47]
	v_mfma_f32_16x16x32_bf16 v[40:43], v[166:169], v[212:215], v[40:43]
	v_mfma_f32_16x16x32_bf16 v[28:31], v[158:161], v[220:223], v[28:31]
	v_mfma_f32_16x16x32_bf16 v[24:27], v[166:169], v[220:223], v[24:27]
	v_mfma_f32_16x16x32_bf16 v[12:15], v[158:161], v[228:231], v[12:15]
	v_mfma_f32_16x16x32_bf16 v[8:11], v[166:169], v[228:231], v[8:11]
	s_setprio 0
	s_setprio 1
	v_mfma_f32_16x16x32_bf16 v[52:55], v[184:187], v[200:203], v[52:55]
	v_mfma_f32_16x16x32_bf16 v[48:51], v[192:195], v[200:203], v[48:51]
	v_mfma_f32_16x16x32_bf16 v[36:39], v[184:187], v[208:211], v[36:39]
	v_mfma_f32_16x16x32_bf16 v[32:35], v[192:195], v[208:211], v[32:35]
	v_mfma_f32_16x16x32_bf16 v[20:23], v[184:187], v[216:219], v[20:23]
	v_mfma_f32_16x16x32_bf16 v[16:19], v[192:195], v[216:219], v[16:19]
	v_mfma_f32_16x16x32_bf16 v[4:7], v[184:187], v[224:227], v[4:7]
	v_mfma_f32_16x16x32_bf16 v[0:3], v[192:195], v[224:227], v[0:3]
	v_mfma_f32_16x16x32_bf16 v[52:55], v[188:191], v[204:207], v[52:55]
	v_mfma_f32_16x16x32_bf16 v[48:51], v[196:199], v[204:207], v[48:51]
	v_mfma_f32_16x16x32_bf16 v[36:39], v[188:191], v[212:215], v[36:39]
	v_mfma_f32_16x16x32_bf16 v[32:35], v[196:199], v[212:215], v[32:35]
	v_mfma_f32_16x16x32_bf16 v[20:23], v[188:191], v[220:223], v[20:23]
	v_mfma_f32_16x16x32_bf16 v[16:19], v[196:199], v[220:223], v[16:19]
	v_mfma_f32_16x16x32_bf16 v[4:7], v[188:191], v[228:231], v[4:7]
	v_mfma_f32_16x16x32_bf16 v[0:3], v[196:199], v[228:231], v[0:3]
	s_barrier
	s_setprio 0
	s_add_i32 s10, 0, 0x18000
	s_add_i32 s93, 0, 0x1c000
	ds_read_b128 v[132:135], v232 offset:32768
	ds_read_b128 v[158:161], v232 offset:33792
	ds_read_b128 v[162:165], v232 offset:34816
	ds_read_b128 v[166:169], v232 offset:35840
	ds_read_b128 v[184:187], v232 offset:49152
	ds_read_b128 v[188:191], v232 offset:50176
	ds_read_b128 v[192:195], v232 offset:51200
	ds_read_b128 v[196:199], v232 offset:52224
	s_add_u32 s62, s64, 0x40000
	s_addc_u32 s63, s65, 0
	s_mov_b32 m0, s67
	ds_read_b128 v[200:203], v181 offset:32768
	ds_read_b128 v[204:207], v181 offset:33792
	ds_read_b128 v[208:211], v181 offset:34816
	ds_read_b128 v[212:215], v181 offset:35840
	ds_read_b128 v[216:219], v181 offset:36864
	ds_read_b128 v[220:223], v181 offset:37888
	ds_read_b128 v[224:227], v181 offset:38912
	global_load_lds_dwordx4 v136, s[62:63]
	s_mov_b32 m0, s68
	ds_read_b128 v[228:231], v181 offset:39936
	global_load_lds_dwordx4 v140, s[62:63]
	s_waitcnt vmcnt(8)
	s_waitcnt lgkmcnt(0)
	s_setprio 1
	s_barrier
	v_mfma_f32_16x16x32_bf16 v[124:127], v[132:135], v[200:203], v[124:127]
	v_mfma_f32_16x16x32_bf16 v[120:123], v[162:165], v[200:203], v[120:123]
	v_mfma_f32_16x16x32_bf16 v[108:111], v[132:135], v[208:211], v[108:111]
	v_mfma_f32_16x16x32_bf16 v[104:107], v[162:165], v[208:211], v[104:107]
	v_mfma_f32_16x16x32_bf16 v[92:95], v[132:135], v[216:219], v[92:95]
	v_mfma_f32_16x16x32_bf16 v[88:91], v[162:165], v[216:219], v[88:91]
	v_mfma_f32_16x16x32_bf16 v[76:79], v[132:135], v[224:227], v[76:79]
	v_mfma_f32_16x16x32_bf16 v[72:75], v[162:165], v[224:227], v[72:75]
	v_mfma_f32_16x16x32_bf16 v[124:127], v[158:161], v[204:207], v[124:127]
	v_mfma_f32_16x16x32_bf16 v[120:123], v[166:169], v[204:207], v[120:123]
	v_mfma_f32_16x16x32_bf16 v[108:111], v[158:161], v[212:215], v[108:111]
	v_mfma_f32_16x16x32_bf16 v[104:107], v[166:169], v[212:215], v[104:107]
	v_mfma_f32_16x16x32_bf16 v[92:95], v[158:161], v[220:223], v[92:95]
	v_mfma_f32_16x16x32_bf16 v[88:91], v[166:169], v[220:223], v[88:91]
	v_mfma_f32_16x16x32_bf16 v[76:79], v[158:161], v[228:231], v[76:79]
	v_mfma_f32_16x16x32_bf16 v[72:75], v[166:169], v[228:231], v[72:75]
	s_setprio 0
	s_setprio 1
	v_mfma_f32_16x16x32_bf16 v[116:119], v[184:187], v[200:203], v[116:119]
	v_mfma_f32_16x16x32_bf16 v[112:115], v[192:195], v[200:203], v[112:115]
	v_mfma_f32_16x16x32_bf16 v[100:103], v[184:187], v[208:211], v[100:103]
	v_mfma_f32_16x16x32_bf16 v[96:99], v[192:195], v[208:211], v[96:99]
	v_mfma_f32_16x16x32_bf16 v[84:87], v[184:187], v[216:219], v[84:87]
	v_mfma_f32_16x16x32_bf16 v[80:83], v[192:195], v[216:219], v[80:83]
	v_mfma_f32_16x16x32_bf16 v[68:71], v[184:187], v[224:227], v[68:71]
	v_mfma_f32_16x16x32_bf16 v[64:67], v[192:195], v[224:227], v[64:67]
	v_mfma_f32_16x16x32_bf16 v[116:119], v[188:191], v[204:207], v[116:119]
	v_mfma_f32_16x16x32_bf16 v[112:115], v[196:199], v[204:207], v[112:115]
	v_mfma_f32_16x16x32_bf16 v[100:103], v[188:191], v[212:215], v[100:103]
	v_mfma_f32_16x16x32_bf16 v[96:99], v[196:199], v[212:215], v[96:99]
	v_mfma_f32_16x16x32_bf16 v[84:87], v[188:191], v[220:223], v[84:87]
	v_mfma_f32_16x16x32_bf16 v[80:83], v[196:199], v[220:223], v[80:83]
	v_mfma_f32_16x16x32_bf16 v[68:71], v[188:191], v[228:231], v[68:71]
	v_mfma_f32_16x16x32_bf16 v[64:67], v[196:199], v[228:231], v[64:67]
	s_barrier
	s_setprio 0
	s_add_i32 s10, s10, s66
	s_mov_b32 m0, s10
	ds_read_b128 v[200:203], v181 offset:49152
	ds_read_b128 v[204:207], v181 offset:50176
	ds_read_b128 v[208:211], v181 offset:51200
	global_load_lds_dwordx4 v138, s[60:61]
	s_add_i32 m0, s10, 0x2000
	ds_read_b128 v[212:215], v181 offset:52224
	global_load_lds_dwordx4 v142, s[60:61]
	s_add_u32 s60, s60, 0x40000
	s_addc_u32 s61, s61, 0
	s_add_i32 s10, s93, s66
	s_mov_b32 m0, s10
	ds_read_b128 v[216:219], v181 offset:53248
	global_load_lds_dwordx4 v138, s[60:61]
	s_add_i32 m0, s10, 0x2000
	ds_read_b128 v[220:223], v181 offset:54272
	global_load_lds_dwordx4 v142, s[60:61]
	s_mov_b32 m0, s73
	ds_read_b128 v[224:227], v181 offset:55296
	global_load_lds_dwordx4 v136, s[58:59]
	s_mov_b32 m0, s78
	ds_read_b128 v[228:231], v181 offset:56320
	global_load_lds_dwordx4 v140, s[58:59]
	s_waitcnt vmcnt(8)
	s_waitcnt lgkmcnt(0)
	s_setprio 1
	s_barrier
	v_mfma_f32_16x16x32_bf16 v[60:63], v[132:135], v[200:203], v[60:63]
	v_mfma_f32_16x16x32_bf16 v[56:59], v[162:165], v[200:203], v[56:59]
	v_mfma_f32_16x16x32_bf16 v[44:47], v[132:135], v[208:211], v[44:47]
	v_mfma_f32_16x16x32_bf16 v[40:43], v[162:165], v[208:211], v[40:43]
	v_mfma_f32_16x16x32_bf16 v[28:31], v[132:135], v[216:219], v[28:31]
	v_mfma_f32_16x16x32_bf16 v[24:27], v[162:165], v[216:219], v[24:27]
	v_mfma_f32_16x16x32_bf16 v[12:15], v[132:135], v[224:227], v[12:15]
	v_mfma_f32_16x16x32_bf16 v[8:11], v[162:165], v[224:227], v[8:11]
	v_mfma_f32_16x16x32_bf16 v[60:63], v[158:161], v[204:207], v[60:63]
	v_mfma_f32_16x16x32_bf16 v[56:59], v[166:169], v[204:207], v[56:59]
	v_mfma_f32_16x16x32_bf16 v[44:47], v[158:161], v[212:215], v[44:47]
	v_mfma_f32_16x16x32_bf16 v[40:43], v[166:169], v[212:215], v[40:43]
	v_mfma_f32_16x16x32_bf16 v[28:31], v[158:161], v[220:223], v[28:31]
	v_mfma_f32_16x16x32_bf16 v[24:27], v[166:169], v[220:223], v[24:27]
	v_mfma_f32_16x16x32_bf16 v[12:15], v[158:161], v[228:231], v[12:15]
	v_mfma_f32_16x16x32_bf16 v[8:11], v[166:169], v[228:231], v[8:11]
	s_setprio 0
	s_setprio 1
	v_mfma_f32_16x16x32_bf16 v[52:55], v[184:187], v[200:203], v[52:55]
	v_mfma_f32_16x16x32_bf16 v[48:51], v[192:195], v[200:203], v[48:51]
	v_mfma_f32_16x16x32_bf16 v[36:39], v[184:187], v[208:211], v[36:39]
	v_mfma_f32_16x16x32_bf16 v[32:35], v[192:195], v[208:211], v[32:35]
	v_mfma_f32_16x16x32_bf16 v[20:23], v[184:187], v[216:219], v[20:23]
	v_mfma_f32_16x16x32_bf16 v[16:19], v[192:195], v[216:219], v[16:19]
	v_mfma_f32_16x16x32_bf16 v[4:7], v[184:187], v[224:227], v[4:7]
	v_mfma_f32_16x16x32_bf16 v[0:3], v[192:195], v[224:227], v[0:3]
	v_mfma_f32_16x16x32_bf16 v[52:55], v[188:191], v[204:207], v[52:55]
	v_mfma_f32_16x16x32_bf16 v[48:51], v[196:199], v[204:207], v[48:51]
	v_mfma_f32_16x16x32_bf16 v[36:39], v[188:191], v[212:215], v[36:39]
	v_mfma_f32_16x16x32_bf16 v[32:35], v[196:199], v[212:215], v[32:35]
	v_mfma_f32_16x16x32_bf16 v[20:23], v[188:191], v[220:223], v[20:23]
	v_mfma_f32_16x16x32_bf16 v[16:19], v[196:199], v[220:223], v[16:19]
	v_mfma_f32_16x16x32_bf16 v[4:7], v[188:191], v[228:231], v[4:7]
	v_mfma_f32_16x16x32_bf16 v[0:3], v[196:199], v[228:231], v[0:3]
	s_barrier
	s_setprio 0
	s_add_u32 s56, s56, 0x100
	s_addc_u32 s57, s57, 0
	s_cmpk_eq_i32 s56, 0x800
	s_cbranch_scc1 .LBB0_169

.LBB0_713:
	s_add_u32 s19, s63, s6
	s_addc_u32 s29, s64, s7
	s_add_u32 s31, s65, s8
	s_addc_u32 s79, s66, s9
	s_ashr_i32 s23, s22, 31
	s_lshl_b64 s[6:7], s[22:23], 19
	s_add_u32 s24, s34, s6
	s_addc_u32 s25, s35, s7
	s_and_b64 s[8:9], s[4:5], exec
	s_cselect_b32 s23, s25, s45
	s_cselect_b32 s80, s24, s44
	s_ashr_i32 s21, s20, 31
	s_lshl_b64 s[8:9], s[20:21], 19
	s_add_u32 s26, s42, s8
	s_addc_u32 s27, s43, s9
	s_and_b64 s[36:37], s[4:5], exec
	s_cselect_b32 s21, s27, s39
	s_cselect_b32 s81, s26, s38
	s_add_u32 s36, s80, 0x80
	s_addc_u32 s37, s23, 0
	s_add_u32 s46, s81, 0x80
	s_addc_u32 s47, s21, 0
	v_lshl_add_u64 v[128:129], s[44:45], 0, v[156:157]
	v_lshl_add_u64 v[130:131], s[44:45], 0, v[158:159]
	s_mov_b32 s82, 0
	s_mov_b64 s[48:49], 0
	v_add_u32_e32 v168, 0x10000, v171
	s_add_u32 s56, s44, s48
	s_addc_u32 s57, s45, s49
	s_mov_b64 s[100:101], s[56:57]
	s_add_u32 s84, s38, s48
	s_addc_u32 s83, s39, s49
	s_add_u32 s50, s56, 0x180
	s_addc_u32 s51, s57, 0
	s_add_u32 s52, s84, 0x180
	s_addc_u32 s53, s83, 0
	s_add_u32 s56, s56, 0x100
	s_addc_u32 s57, s57, 0
	s_add_u32 s54, s84, 0x100
	s_addc_u32 s55, s83, 0
	s_cmpk_eq_i32 s48, 0x700
	s_cselect_b32 s50, s36, s50
	s_cselect_b32 s51, s37, s51
	s_cselect_b32 s52, s46, s52
	s_cselect_b32 s53, s47, s53
	s_cselect_b32 s56, s80, s56
	s_cselect_b32 s57, s23, s57
	s_cselect_b32 s54, s81, s54
	s_cselect_b32 s55, s21, s55
	ds_read_b128 v[132:135], v168
	ds_read_b128 v[136:139], v168 offset:1024
	ds_read_b128 v[140:143], v168 offset:2048
	ds_read_b128 v[164:167], v168 offset:3072
	ds_read_b128 v[174:177], v168 offset:16384
	ds_read_b128 v[178:181], v168 offset:17408
	ds_read_b128 v[182:185], v168 offset:18432
	ds_read_b128 v[186:189], v168 offset:19456
	s_add_i32 m0, s59, 0xc000
	ds_read_b128 v[190:193], v172
	ds_read_b128 v[194:197], v172 offset:1024
	ds_read_b128 v[198:201], v172 offset:2048
	ds_read_b128 v[202:205], v172 offset:3072
	ds_read_b128 v[206:209], v172 offset:4096
	ds_read_b128 v[210:213], v172 offset:5120
	ds_read_b128 v[214:217], v172 offset:6144
	global_load_lds_dwordx4 v156, s[100:101]
	s_add_i32 m0, s59, 0xe000
	ds_read_b128 v[218:221], v172 offset:7168
	global_load_lds_dwordx4 v158, s[100:101]
	s_waitcnt vmcnt(8)
	s_waitcnt lgkmcnt(0)
	s_setprio 1
	s_barrier
	v_mfma_f32_16x16x32_bf16 v[124:127], v[132:135], v[190:193], 0
	v_mfma_f32_16x16x32_bf16 v[120:123], v[140:143], v[190:193], 0
	v_mfma_f32_16x16x32_bf16 v[108:111], v[132:135], v[198:201], 0
	v_mfma_f32_16x16x32_bf16 v[104:107], v[140:143], v[198:201], 0
	v_mfma_f32_16x16x32_bf16 v[92:95], v[132:135], v[206:209], 0
	v_mfma_f32_16x16x32_bf16 v[88:91], v[140:143], v[206:209], 0
	v_mfma_f32_16x16x32_bf16 v[76:79], v[132:135], v[214:217], 0
	v_mfma_f32_16x16x32_bf16 v[72:75], v[140:143], v[214:217], 0
	v_mfma_f32_16x16x32_bf16 v[124:127], v[136:139], v[194:197], v[124:127]
	v_mfma_f32_16x16x32_bf16 v[120:123], v[164:167], v[194:197], v[120:123]
	v_mfma_f32_16x16x32_bf16 v[108:111], v[136:139], v[202:205], v[108:111]
	v_mfma_f32_16x16x32_bf16 v[104:107], v[164:167], v[202:205], v[104:107]
	v_mfma_f32_16x16x32_bf16 v[92:95], v[136:139], v[210:213], v[92:95]
	v_mfma_f32_16x16x32_bf16 v[88:91], v[164:167], v[210:213], v[88:91]
	v_mfma_f32_16x16x32_bf16 v[76:79], v[136:139], v[218:221], v[76:79]
	v_mfma_f32_16x16x32_bf16 v[72:75], v[164:167], v[218:221], v[72:75]
	s_setprio 0
	s_setprio 1
	v_mfma_f32_16x16x32_bf16 v[116:119], v[174:177], v[190:193], 0
	v_mfma_f32_16x16x32_bf16 v[112:115], v[182:185], v[190:193], 0
	v_mfma_f32_16x16x32_bf16 v[100:103], v[174:177], v[198:201], 0
	v_mfma_f32_16x16x32_bf16 v[96:99], v[182:185], v[198:201], 0
	v_mfma_f32_16x16x32_bf16 v[84:87], v[174:177], v[206:209], 0
	v_mfma_f32_16x16x32_bf16 v[80:83], v[182:185], v[206:209], 0
	v_mfma_f32_16x16x32_bf16 v[68:71], v[174:177], v[214:217], 0
	v_mfma_f32_16x16x32_bf16 v[64:67], v[182:185], v[214:217], 0
	v_mfma_f32_16x16x32_bf16 v[116:119], v[178:181], v[194:197], v[116:119]
	v_mfma_f32_16x16x32_bf16 v[112:115], v[186:189], v[194:197], v[112:115]
	v_mfma_f32_16x16x32_bf16 v[100:103], v[178:181], v[202:205], v[100:103]
	v_mfma_f32_16x16x32_bf16 v[96:99], v[186:189], v[202:205], v[96:99]
	v_mfma_f32_16x16x32_bf16 v[84:87], v[178:181], v[210:213], v[84:87]
	v_mfma_f32_16x16x32_bf16 v[80:83], v[186:189], v[210:213], v[80:83]
	v_mfma_f32_16x16x32_bf16 v[68:71], v[178:181], v[218:221], v[68:71]
	v_mfma_f32_16x16x32_bf16 v[64:67], v[186:189], v[218:221], v[64:67]
	s_barrier
	s_setprio 0
	s_add_i32 s10, s72, s58
	s_mov_b32 m0, s10
	ds_read_b128 v[190:193], v172 offset:16384
	ds_read_b128 v[194:197], v172 offset:17408
	ds_read_b128 v[198:201], v172 offset:18432
	global_load_lds_dwordx4 v146, s[54:55]
	s_add_i32 m0, s10, 0x2000
	ds_read_b128 v[202:205], v172 offset:19456
	global_load_lds_dwordx4 v150, s[54:55]
	s_add_u32 s54, s54, 0x40000
	s_addc_u32 s55, s55, 0
	s_add_i32 s10, s73, s58
	s_mov_b32 m0, s10
	ds_read_b128 v[206:209], v172 offset:20480
	global_load_lds_dwordx4 v146, s[54:55]
	s_add_i32 m0, s10, 0x2000
	ds_read_b128 v[210:213], v172 offset:21504
	global_load_lds_dwordx4 v150, s[54:55]
	s_mov_b32 m0, s59
	ds_read_b128 v[214:217], v172 offset:22528
	global_load_lds_dwordx4 v144, s[56:57]
	s_mov_b32 m0, s60
	ds_read_b128 v[218:221], v172 offset:23552
	global_load_lds_dwordx4 v148, s[56:57]
	s_waitcnt vmcnt(8)
	s_waitcnt lgkmcnt(0)
	s_setprio 1
	s_barrier
	v_mfma_f32_16x16x32_bf16 v[60:63], v[132:135], v[190:193], 0
	v_mfma_f32_16x16x32_bf16 v[56:59], v[140:143], v[190:193], 0
	v_mfma_f32_16x16x32_bf16 v[44:47], v[132:135], v[198:201], 0
	v_mfma_f32_16x16x32_bf16 v[40:43], v[140:143], v[198:201], 0
	v_mfma_f32_16x16x32_bf16 v[28:31], v[132:135], v[206:209], 0
	v_mfma_f32_16x16x32_bf16 v[24:27], v[140:143], v[206:209], 0
	v_mfma_f32_16x16x32_bf16 v[12:15], v[132:135], v[214:217], 0
	v_mfma_f32_16x16x32_bf16 v[8:11], v[140:143], v[214:217], 0
	v_mfma_f32_16x16x32_bf16 v[60:63], v[136:139], v[194:197], v[60:63]
	v_mfma_f32_16x16x32_bf16 v[56:59], v[164:167], v[194:197], v[56:59]
	v_mfma_f32_16x16x32_bf16 v[44:47], v[136:139], v[202:205], v[44:47]
	v_mfma_f32_16x16x32_bf16 v[40:43], v[164:167], v[202:205], v[40:43]
	v_mfma_f32_16x16x32_bf16 v[28:31], v[136:139], v[210:213], v[28:31]
	v_mfma_f32_16x16x32_bf16 v[24:27], v[164:167], v[210:213], v[24:27]
	v_mfma_f32_16x16x32_bf16 v[12:15], v[136:139], v[218:221], v[12:15]
	v_mfma_f32_16x16x32_bf16 v[8:11], v[164:167], v[218:221], v[8:11]
	s_setprio 0
	s_setprio 1
	v_mfma_f32_16x16x32_bf16 v[52:55], v[174:177], v[190:193], 0
	v_mfma_f32_16x16x32_bf16 v[48:51], v[182:185], v[190:193], 0
	v_mfma_f32_16x16x32_bf16 v[36:39], v[174:177], v[198:201], 0
	v_mfma_f32_16x16x32_bf16 v[32:35], v[182:185], v[198:201], 0
	v_mfma_f32_16x16x32_bf16 v[20:23], v[174:177], v[206:209], 0
	v_mfma_f32_16x16x32_bf16 v[16:19], v[182:185], v[206:209], 0
	v_mfma_f32_16x16x32_bf16 v[4:7], v[174:177], v[214:217], 0
	v_mfma_f32_16x16x32_bf16 v[0:3], v[182:185], v[214:217], 0
	v_mfma_f32_16x16x32_bf16 v[52:55], v[178:181], v[194:197], v[52:55]
	v_mfma_f32_16x16x32_bf16 v[48:51], v[186:189], v[194:197], v[48:51]
	v_mfma_f32_16x16x32_bf16 v[36:39], v[178:181], v[202:205], v[36:39]
	v_mfma_f32_16x16x32_bf16 v[32:35], v[186:189], v[202:205], v[32:35]
	v_mfma_f32_16x16x32_bf16 v[20:23], v[178:181], v[210:213], v[20:23]
	v_mfma_f32_16x16x32_bf16 v[16:19], v[186:189], v[210:213], v[16:19]
	v_mfma_f32_16x16x32_bf16 v[4:7], v[178:181], v[218:221], v[4:7]
	v_mfma_f32_16x16x32_bf16 v[0:3], v[186:189], v[218:221], v[0:3]
	s_barrier
	s_setprio 0
	s_add_i32 s10, 0, 0x18000
	s_add_i32 s83, 0, 0x1c000
	ds_read_b128 v[132:135], v168 offset:32768
	ds_read_b128 v[136:139], v168 offset:33792
	ds_read_b128 v[140:143], v168 offset:34816
	ds_read_b128 v[164:167], v168 offset:35840
	ds_read_b128 v[174:177], v168 offset:49152
	ds_read_b128 v[178:181], v168 offset:50176
	ds_read_b128 v[182:185], v168 offset:51200
	ds_read_b128 v[186:189], v168 offset:52224
	s_add_u32 s54, s56, 0x40000
	s_addc_u32 s55, s57, 0
	s_mov_b32 m0, s61
	ds_read_b128 v[190:193], v172 offset:32768
	ds_read_b128 v[194:197], v172 offset:33792
	ds_read_b128 v[198:201], v172 offset:34816
	ds_read_b128 v[202:205], v172 offset:35840
	ds_read_b128 v[206:209], v172 offset:36864
	ds_read_b128 v[210:213], v172 offset:37888
	ds_read_b128 v[214:217], v172 offset:38912
	global_load_lds_dwordx4 v144, s[54:55]
	s_mov_b32 m0, s62
	ds_read_b128 v[218:221], v172 offset:39936
	global_load_lds_dwordx4 v148, s[54:55]
	s_waitcnt vmcnt(8)
	s_waitcnt lgkmcnt(0)
	s_setprio 1
	s_barrier
	v_mfma_f32_16x16x32_bf16 v[124:127], v[132:135], v[190:193], v[124:127]
	v_mfma_f32_16x16x32_bf16 v[120:123], v[140:143], v[190:193], v[120:123]
	v_mfma_f32_16x16x32_bf16 v[108:111], v[132:135], v[198:201], v[108:111]
	v_mfma_f32_16x16x32_bf16 v[104:107], v[140:143], v[198:201], v[104:107]
	v_mfma_f32_16x16x32_bf16 v[92:95], v[132:135], v[206:209], v[92:95]
	v_mfma_f32_16x16x32_bf16 v[88:91], v[140:143], v[206:209], v[88:91]
	v_mfma_f32_16x16x32_bf16 v[76:79], v[132:135], v[214:217], v[76:79]
	v_mfma_f32_16x16x32_bf16 v[72:75], v[140:143], v[214:217], v[72:75]
	v_mfma_f32_16x16x32_bf16 v[124:127], v[136:139], v[194:197], v[124:127]
	v_mfma_f32_16x16x32_bf16 v[120:123], v[164:167], v[194:197], v[120:123]
	v_mfma_f32_16x16x32_bf16 v[108:111], v[136:139], v[202:205], v[108:111]
	v_mfma_f32_16x16x32_bf16 v[104:107], v[164:167], v[202:205], v[104:107]
	v_mfma_f32_16x16x32_bf16 v[92:95], v[136:139], v[210:213], v[92:95]
	v_mfma_f32_16x16x32_bf16 v[88:91], v[164:167], v[210:213], v[88:91]
	v_mfma_f32_16x16x32_bf16 v[76:79], v[136:139], v[218:221], v[76:79]
	v_mfma_f32_16x16x32_bf16 v[72:75], v[164:167], v[218:221], v[72:75]
	s_setprio 0
	s_setprio 1
	v_mfma_f32_16x16x32_bf16 v[116:119], v[174:177], v[190:193], v[116:119]
	v_mfma_f32_16x16x32_bf16 v[112:115], v[182:185], v[190:193], v[112:115]
	v_mfma_f32_16x16x32_bf16 v[100:103], v[174:177], v[198:201], v[100:103]
	v_mfma_f32_16x16x32_bf16 v[96:99], v[182:185], v[198:201], v[96:99]
	v_mfma_f32_16x16x32_bf16 v[84:87], v[174:177], v[206:209], v[84:87]
	v_mfma_f32_16x16x32_bf16 v[80:83], v[182:185], v[206:209], v[80:83]
	v_mfma_f32_16x16x32_bf16 v[68:71], v[174:177], v[214:217], v[68:71]
	v_mfma_f32_16x16x32_bf16 v[64:67], v[182:185], v[214:217], v[64:67]
	v_mfma_f32_16x16x32_bf16 v[116:119], v[178:181], v[194:197], v[116:119]
	v_mfma_f32_16x16x32_bf16 v[112:115], v[186:189], v[194:197], v[112:115]
	v_mfma_f32_16x16x32_bf16 v[100:103], v[178:181], v[202:205], v[100:103]
	v_mfma_f32_16x16x32_bf16 v[96:99], v[186:189], v[202:205], v[96:99]
	v_mfma_f32_16x16x32_bf16 v[84:87], v[178:181], v[210:213], v[84:87]
	v_mfma_f32_16x16x32_bf16 v[80:83], v[186:189], v[210:213], v[80:83]
	v_mfma_f32_16x16x32_bf16 v[68:71], v[178:181], v[218:221], v[68:71]
	v_mfma_f32_16x16x32_bf16 v[64:67], v[186:189], v[218:221], v[64:67]
	s_barrier
	s_setprio 0
	s_add_i32 s10, s10, s58
	s_mov_b32 m0, s10
	ds_read_b128 v[190:193], v172 offset:49152
	ds_read_b128 v[194:197], v172 offset:50176
	ds_read_b128 v[198:201], v172 offset:51200
	global_load_lds_dwordx4 v146, s[52:53]
	s_add_i32 m0, s10, 0x2000
	ds_read_b128 v[202:205], v172 offset:52224
	global_load_lds_dwordx4 v150, s[52:53]
	s_add_u32 s52, s52, 0x40000
	s_addc_u32 s53, s53, 0
	s_add_i32 s10, s83, s58
	s_mov_b32 m0, s10
	ds_read_b128 v[206:209], v172 offset:53248
	global_load_lds_dwordx4 v146, s[52:53]
	s_add_i32 m0, s10, 0x2000
	ds_read_b128 v[210:213], v172 offset:54272
	global_load_lds_dwordx4 v150, s[52:53]
	s_mov_b32 m0, s68
	ds_read_b128 v[214:217], v172 offset:55296
	global_load_lds_dwordx4 v144, s[50:51]
	s_mov_b32 m0, s69
	ds_read_b128 v[218:221], v172 offset:56320
	global_load_lds_dwordx4 v148, s[50:51]
	s_waitcnt vmcnt(8)
	s_waitcnt lgkmcnt(0)
	s_setprio 1
	s_barrier
	v_mfma_f32_16x16x32_bf16 v[60:63], v[132:135], v[190:193], v[60:63]
	v_mfma_f32_16x16x32_bf16 v[56:59], v[140:143], v[190:193], v[56:59]
	v_mfma_f32_16x16x32_bf16 v[44:47], v[132:135], v[198:201], v[44:47]
	v_mfma_f32_16x16x32_bf16 v[40:43], v[140:143], v[198:201], v[40:43]
	v_mfma_f32_16x16x32_bf16 v[28:31], v[132:135], v[206:209], v[28:31]
	v_mfma_f32_16x16x32_bf16 v[24:27], v[140:143], v[206:209], v[24:27]
	v_mfma_f32_16x16x32_bf16 v[12:15], v[132:135], v[214:217], v[12:15]
	v_mfma_f32_16x16x32_bf16 v[8:11], v[140:143], v[214:217], v[8:11]
	v_mfma_f32_16x16x32_bf16 v[60:63], v[136:139], v[194:197], v[60:63]
	v_mfma_f32_16x16x32_bf16 v[56:59], v[164:167], v[194:197], v[56:59]
	v_mfma_f32_16x16x32_bf16 v[44:47], v[136:139], v[202:205], v[44:47]
	v_mfma_f32_16x16x32_bf16 v[40:43], v[164:167], v[202:205], v[40:43]
	v_mfma_f32_16x16x32_bf16 v[28:31], v[136:139], v[210:213], v[28:31]
	v_mfma_f32_16x16x32_bf16 v[24:27], v[164:167], v[210:213], v[24:27]
	v_mfma_f32_16x16x32_bf16 v[12:15], v[136:139], v[218:221], v[12:15]
	v_mfma_f32_16x16x32_bf16 v[8:11], v[164:167], v[218:221], v[8:11]
	s_setprio 0
	s_setprio 1
	v_mfma_f32_16x16x32_bf16 v[52:55], v[174:177], v[190:193], v[52:55]
	v_mfma_f32_16x16x32_bf16 v[48:51], v[182:185], v[190:193], v[48:51]
	v_mfma_f32_16x16x32_bf16 v[36:39], v[174:177], v[198:201], v[36:39]
	v_mfma_f32_16x16x32_bf16 v[32:35], v[182:185], v[198:201], v[32:35]
	v_mfma_f32_16x16x32_bf16 v[20:23], v[174:177], v[206:209], v[20:23]
	v_mfma_f32_16x16x32_bf16 v[16:19], v[182:185], v[206:209], v[16:19]
	v_mfma_f32_16x16x32_bf16 v[4:7], v[174:177], v[214:217], v[4:7]
	v_mfma_f32_16x16x32_bf16 v[0:3], v[182:185], v[214:217], v[0:3]
	v_mfma_f32_16x16x32_bf16 v[52:55], v[178:181], v[194:197], v[52:55]
	v_mfma_f32_16x16x32_bf16 v[48:51], v[186:189], v[194:197], v[48:51]
	v_mfma_f32_16x16x32_bf16 v[36:39], v[178:181], v[202:205], v[36:39]
	v_mfma_f32_16x16x32_bf16 v[32:35], v[186:189], v[202:205], v[32:35]
	v_mfma_f32_16x16x32_bf16 v[20:23], v[178:181], v[210:213], v[20:23]
	v_mfma_f32_16x16x32_bf16 v[16:19], v[186:189], v[210:213], v[16:19]
	v_mfma_f32_16x16x32_bf16 v[4:7], v[178:181], v[218:221], v[4:7]
	v_mfma_f32_16x16x32_bf16 v[0:3], v[186:189], v[218:221], v[0:3]
	s_barrier
	s_setprio 0
	s_add_u32 s48, s48, 0x100
	s_addc_u32 s49, s49, 0
	s_cmpk_eq_i32 s48, 0x800
	s_cbranch_scc1 .LBB0_721
	s_branch .LBB0_715
.LBB0_714:
	ds_read_b128 v[132:135], v168
	ds_read_b128 v[136:139], v168 offset:1024
	ds_read_b128 v[140:143], v168 offset:2048
	ds_read_b128 v[164:167], v168 offset:3072
	ds_read_b128 v[174:177], v168 offset:16384
	ds_read_b128 v[178:181], v168 offset:17408
	ds_read_b128 v[182:185], v168 offset:18432
	ds_read_b128 v[186:189], v168 offset:19456
	s_add_i32 m0, s59, 0xc000
	ds_read_b128 v[190:193], v172
	ds_read_b128 v[194:197], v172 offset:1024
	ds_read_b128 v[198:201], v172 offset:2048
	ds_read_b128 v[202:205], v172 offset:3072
	ds_read_b128 v[206:209], v172 offset:4096
	ds_read_b128 v[210:213], v172 offset:5120
	ds_read_b128 v[214:217], v172 offset:6144
	global_load_lds_dwordx4 v156, s[100:101]
	s_add_i32 m0, s59, 0xe000
	ds_read_b128 v[218:221], v172 offset:7168
	global_load_lds_dwordx4 v158, s[100:101]
	s_waitcnt vmcnt(8)
	s_waitcnt lgkmcnt(0)
	s_setprio 1
	s_barrier
	v_mfma_f32_16x16x32_bf16 v[124:127], v[132:135], v[190:193], v[124:127]
	v_mfma_f32_16x16x32_bf16 v[120:123], v[140:143], v[190:193], v[120:123]
	v_mfma_f32_16x16x32_bf16 v[108:111], v[132:135], v[198:201], v[108:111]
	v_mfma_f32_16x16x32_bf16 v[104:107], v[140:143], v[198:201], v[104:107]
	v_mfma_f32_16x16x32_bf16 v[92:95], v[132:135], v[206:209], v[92:95]
	v_mfma_f32_16x16x32_bf16 v[88:91], v[140:143], v[206:209], v[88:91]
	v_mfma_f32_16x16x32_bf16 v[76:79], v[132:135], v[214:217], v[76:79]
	v_mfma_f32_16x16x32_bf16 v[72:75], v[140:143], v[214:217], v[72:75]
	v_mfma_f32_16x16x32_bf16 v[124:127], v[136:139], v[194:197], v[124:127]
	v_mfma_f32_16x16x32_bf16 v[120:123], v[164:167], v[194:197], v[120:123]
	v_mfma_f32_16x16x32_bf16 v[108:111], v[136:139], v[202:205], v[108:111]
	v_mfma_f32_16x16x32_bf16 v[104:107], v[164:167], v[202:205], v[104:107]
	v_mfma_f32_16x16x32_bf16 v[92:95], v[136:139], v[210:213], v[92:95]
	v_mfma_f32_16x16x32_bf16 v[88:91], v[164:167], v[210:213], v[88:91]
	v_mfma_f32_16x16x32_bf16 v[76:79], v[136:139], v[218:221], v[76:79]
	v_mfma_f32_16x16x32_bf16 v[72:75], v[164:167], v[218:221], v[72:75]
	s_setprio 0
	s_setprio 1
	v_mfma_f32_16x16x32_bf16 v[116:119], v[174:177], v[190:193], v[116:119]
	v_mfma_f32_16x16x32_bf16 v[112:115], v[182:185], v[190:193], v[112:115]
	v_mfma_f32_16x16x32_bf16 v[100:103], v[174:177], v[198:201], v[100:103]
	v_mfma_f32_16x16x32_bf16 v[96:99], v[182:185], v[198:201], v[96:99]
	v_mfma_f32_16x16x32_bf16 v[84:87], v[174:177], v[206:209], v[84:87]
	v_mfma_f32_16x16x32_bf16 v[80:83], v[182:185], v[206:209], v[80:83]
	v_mfma_f32_16x16x32_bf16 v[68:71], v[174:177], v[214:217], v[68:71]
	v_mfma_f32_16x16x32_bf16 v[64:67], v[182:185], v[214:217], v[64:67]
	v_mfma_f32_16x16x32_bf16 v[116:119], v[178:181], v[194:197], v[116:119]
	v_mfma_f32_16x16x32_bf16 v[112:115], v[186:189], v[194:197], v[112:115]
	v_mfma_f32_16x16x32_bf16 v[100:103], v[178:181], v[202:205], v[100:103]
	v_mfma_f32_16x16x32_bf16 v[96:99], v[186:189], v[202:205], v[96:99]
	v_mfma_f32_16x16x32_bf16 v[84:87], v[178:181], v[210:213], v[84:87]
	v_mfma_f32_16x16x32_bf16 v[80:83], v[186:189], v[210:213], v[80:83]
	v_mfma_f32_16x16x32_bf16 v[68:71], v[178:181], v[218:221], v[68:71]
	v_mfma_f32_16x16x32_bf16 v[64:67], v[186:189], v[218:221], v[64:67]
	s_barrier
	s_setprio 0
	s_add_i32 s10, s72, s58
	s_mov_b32 m0, s10
	ds_read_b128 v[190:193], v172 offset:16384
	ds_read_b128 v[194:197], v172 offset:17408
	ds_read_b128 v[198:201], v172 offset:18432
	global_load_lds_dwordx4 v146, s[54:55]
	s_add_i32 m0, s10, 0x2000
	ds_read_b128 v[202:205], v172 offset:19456
	global_load_lds_dwordx4 v150, s[54:55]
	s_add_u32 s54, s54, 0x40000
	s_addc_u32 s55, s55, 0
	s_add_i32 s10, s73, s58
	s_mov_b32 m0, s10
	ds_read_b128 v[206:209], v172 offset:20480
	global_load_lds_dwordx4 v146, s[54:55]
	s_add_i32 m0, s10, 0x2000
	ds_read_b128 v[210:213], v172 offset:21504
	global_load_lds_dwordx4 v150, s[54:55]
	s_mov_b32 m0, s59
	ds_read_b128 v[214:217], v172 offset:22528
	global_load_lds_dwordx4 v144, s[56:57]
	s_mov_b32 m0, s60
	ds_read_b128 v[218:221], v172 offset:23552
	global_load_lds_dwordx4 v148, s[56:57]
	s_waitcnt vmcnt(8)
	s_waitcnt lgkmcnt(0)
	s_setprio 1
	s_barrier
	v_mfma_f32_16x16x32_bf16 v[60:63], v[132:135], v[190:193], v[60:63]
	v_mfma_f32_16x16x32_bf16 v[56:59], v[140:143], v[190:193], v[56:59]
	v_mfma_f32_16x16x32_bf16 v[44:47], v[132:135], v[198:201], v[44:47]
	v_mfma_f32_16x16x32_bf16 v[40:43], v[140:143], v[198:201], v[40:43]
	v_mfma_f32_16x16x32_bf16 v[28:31], v[132:135], v[206:209], v[28:31]
	v_mfma_f32_16x16x32_bf16 v[24:27], v[140:143], v[206:209], v[24:27]
	v_mfma_f32_16x16x32_bf16 v[12:15], v[132:135], v[214:217], v[12:15]
	v_mfma_f32_16x16x32_bf16 v[8:11], v[140:143], v[214:217], v[8:11]
	v_mfma_f32_16x16x32_bf16 v[60:63], v[136:139], v[194:197], v[60:63]
	v_mfma_f32_16x16x32_bf16 v[56:59], v[164:167], v[194:197], v[56:59]
	v_mfma_f32_16x16x32_bf16 v[44:47], v[136:139], v[202:205], v[44:47]
	v_mfma_f32_16x16x32_bf16 v[40:43], v[164:167], v[202:205], v[40:43]
	v_mfma_f32_16x16x32_bf16 v[28:31], v[136:139], v[210:213], v[28:31]
	v_mfma_f32_16x16x32_bf16 v[24:27], v[164:167], v[210:213], v[24:27]
	v_mfma_f32_16x16x32_bf16 v[12:15], v[136:139], v[218:221], v[12:15]
	v_mfma_f32_16x16x32_bf16 v[8:11], v[164:167], v[218:221], v[8:11]
	s_setprio 0
	s_setprio 1
	v_mfma_f32_16x16x32_bf16 v[52:55], v[174:177], v[190:193], v[52:55]
	v_mfma_f32_16x16x32_bf16 v[48:51], v[182:185], v[190:193], v[48:51]
	v_mfma_f32_16x16x32_bf16 v[36:39], v[174:177], v[198:201], v[36:39]
	v_mfma_f32_16x16x32_bf16 v[32:35], v[182:185], v[198:201], v[32:35]
	v_mfma_f32_16x16x32_bf16 v[20:23], v[174:177], v[206:209], v[20:23]
	v_mfma_f32_16x16x32_bf16 v[16:19], v[182:185], v[206:209], v[16:19]
	v_mfma_f32_16x16x32_bf16 v[4:7], v[174:177], v[214:217], v[4:7]
	v_mfma_f32_16x16x32_bf16 v[0:3], v[182:185], v[214:217], v[0:3]
	v_mfma_f32_16x16x32_bf16 v[52:55], v[178:181], v[194:197], v[52:55]
	v_mfma_f32_16x16x32_bf16 v[48:51], v[186:189], v[194:197], v[48:51]
	v_mfma_f32_16x16x32_bf16 v[36:39], v[178:181], v[202:205], v[36:39]
	v_mfma_f32_16x16x32_bf16 v[32:35], v[186:189], v[202:205], v[32:35]
	v_mfma_f32_16x16x32_bf16 v[20:23], v[178:181], v[210:213], v[20:23]
	v_mfma_f32_16x16x32_bf16 v[16:19], v[186:189], v[210:213], v[16:19]
	v_mfma_f32_16x16x32_bf16 v[4:7], v[178:181], v[218:221], v[4:7]
	v_mfma_f32_16x16x32_bf16 v[0:3], v[186:189], v[218:221], v[0:3]
	s_barrier
	s_setprio 0
	s_add_i32 s10, 0, 0x18000
	s_add_i32 s83, 0, 0x1c000
	ds_read_b128 v[132:135], v168 offset:32768
	ds_read_b128 v[136:139], v168 offset:33792
	ds_read_b128 v[140:143], v168 offset:34816
	ds_read_b128 v[164:167], v168 offset:35840
	ds_read_b128 v[174:177], v168 offset:49152
	ds_read_b128 v[178:181], v168 offset:50176
	ds_read_b128 v[182:185], v168 offset:51200
	ds_read_b128 v[186:189], v168 offset:52224
	s_add_u32 s54, s56, 0x40000
	s_addc_u32 s55, s57, 0
	s_mov_b32 m0, s61
	ds_read_b128 v[190:193], v172 offset:32768
	ds_read_b128 v[194:197], v172 offset:33792
	ds_read_b128 v[198:201], v172 offset:34816
	ds_read_b128 v[202:205], v172 offset:35840
	ds_read_b128 v[206:209], v172 offset:36864
	ds_read_b128 v[210:213], v172 offset:37888
	ds_read_b128 v[214:217], v172 offset:38912
	global_load_lds_dwordx4 v144, s[54:55]
	s_mov_b32 m0, s62
	ds_read_b128 v[218:221], v172 offset:39936
	global_load_lds_dwordx4 v148, s[54:55]
	s_waitcnt vmcnt(8)
	s_waitcnt lgkmcnt(0)
	s_setprio 1
	s_barrier
	v_mfma_f32_16x16x32_bf16 v[124:127], v[132:135], v[190:193], v[124:127]
	v_mfma_f32_16x16x32_bf16 v[120:123], v[140:143], v[190:193], v[120:123]
	v_mfma_f32_16x16x32_bf16 v[108:111], v[132:135], v[198:201], v[108:111]
	v_mfma_f32_16x16x32_bf16 v[104:107], v[140:143], v[198:201], v[104:107]
	v_mfma_f32_16x16x32_bf16 v[92:95], v[132:135], v[206:209], v[92:95]
	v_mfma_f32_16x16x32_bf16 v[88:91], v[140:143], v[206:209], v[88:91]
	v_mfma_f32_16x16x32_bf16 v[76:79], v[132:135], v[214:217], v[76:79]
	v_mfma_f32_16x16x32_bf16 v[72:75], v[140:143], v[214:217], v[72:75]
	v_mfma_f32_16x16x32_bf16 v[124:127], v[136:139], v[194:197], v[124:127]
	v_mfma_f32_16x16x32_bf16 v[120:123], v[164:167], v[194:197], v[120:123]
	v_mfma_f32_16x16x32_bf16 v[108:111], v[136:139], v[202:205], v[108:111]
	v_mfma_f32_16x16x32_bf16 v[104:107], v[164:167], v[202:205], v[104:107]
	v_mfma_f32_16x16x32_bf16 v[92:95], v[136:139], v[210:213], v[92:95]
	v_mfma_f32_16x16x32_bf16 v[88:91], v[164:167], v[210:213], v[88:91]
	v_mfma_f32_16x16x32_bf16 v[76:79], v[136:139], v[218:221], v[76:79]
	v_mfma_f32_16x16x32_bf16 v[72:75], v[164:167], v[218:221], v[72:75]
	s_setprio 0
	s_setprio 1
	v_mfma_f32_16x16x32_bf16 v[116:119], v[174:177], v[190:193], v[116:119]
	v_mfma_f32_16x16x32_bf16 v[112:115], v[182:185], v[190:193], v[112:115]
	v_mfma_f32_16x16x32_bf16 v[100:103], v[174:177], v[198:201], v[100:103]
	v_mfma_f32_16x16x32_bf16 v[96:99], v[182:185], v[198:201], v[96:99]
	v_mfma_f32_16x16x32_bf16 v[84:87], v[174:177], v[206:209], v[84:87]
	v_mfma_f32_16x16x32_bf16 v[80:83], v[182:185], v[206:209], v[80:83]
	v_mfma_f32_16x16x32_bf16 v[68:71], v[174:177], v[214:217], v[68:71]
	v_mfma_f32_16x16x32_bf16 v[64:67], v[182:185], v[214:217], v[64:67]
	v_mfma_f32_16x16x32_bf16 v[116:119], v[178:181], v[194:197], v[116:119]
	v_mfma_f32_16x16x32_bf16 v[112:115], v[186:189], v[194:197], v[112:115]
	v_mfma_f32_16x16x32_bf16 v[100:103], v[178:181], v[202:205], v[100:103]
	v_mfma_f32_16x16x32_bf16 v[96:99], v[186:189], v[202:205], v[96:99]
	v_mfma_f32_16x16x32_bf16 v[84:87], v[178:181], v[210:213], v[84:87]
	v_mfma_f32_16x16x32_bf16 v[80:83], v[186:189], v[210:213], v[80:83]
	v_mfma_f32_16x16x32_bf16 v[68:71], v[178:181], v[218:221], v[68:71]
	v_mfma_f32_16x16x32_bf16 v[64:67], v[186:189], v[218:221], v[64:67]
	s_barrier
	s_setprio 0
	s_add_i32 s10, s10, s58
	s_mov_b32 m0, s10
	ds_read_b128 v[190:193], v172 offset:49152
	ds_read_b128 v[194:197], v172 offset:50176
	ds_read_b128 v[198:201], v172 offset:51200
	global_load_lds_dwordx4 v146, s[52:53]
	s_add_i32 m0, s10, 0x2000
	ds_read_b128 v[202:205], v172 offset:52224
	global_load_lds_dwordx4 v150, s[52:53]
	s_add_u32 s52, s52, 0x40000
	s_addc_u32 s53, s53, 0
	s_add_i32 s10, s83, s58
	s_mov_b32 m0, s10
	ds_read_b128 v[206:209], v172 offset:53248
	global_load_lds_dwordx4 v146, s[52:53]
	s_add_i32 m0, s10, 0x2000
	ds_read_b128 v[210:213], v172 offset:54272
	global_load_lds_dwordx4 v150, s[52:53]
	s_mov_b32 m0, s68
	ds_read_b128 v[214:217], v172 offset:55296
	global_load_lds_dwordx4 v144, s[50:51]
	s_mov_b32 m0, s69
	ds_read_b128 v[218:221], v172 offset:56320
	global_load_lds_dwordx4 v148, s[50:51]
	s_waitcnt vmcnt(8)
	s_waitcnt lgkmcnt(0)
	s_setprio 1
	s_barrier
	v_mfma_f32_16x16x32_bf16 v[60:63], v[132:135], v[190:193], v[60:63]
	v_mfma_f32_16x16x32_bf16 v[56:59], v[140:143], v[190:193], v[56:59]
	v_mfma_f32_16x16x32_bf16 v[44:47], v[132:135], v[198:201], v[44:47]
	v_mfma_f32_16x16x32_bf16 v[40:43], v[140:143], v[198:201], v[40:43]
	v_mfma_f32_16x16x32_bf16 v[28:31], v[132:135], v[206:209], v[28:31]
	v_mfma_f32_16x16x32_bf16 v[24:27], v[140:143], v[206:209], v[24:27]
	v_mfma_f32_16x16x32_bf16 v[12:15], v[132:135], v[214:217], v[12:15]
	v_mfma_f32_16x16x32_bf16 v[8:11], v[140:143], v[214:217], v[8:11]
	v_mfma_f32_16x16x32_bf16 v[60:63], v[136:139], v[194:197], v[60:63]
	v_mfma_f32_16x16x32_bf16 v[56:59], v[164:167], v[194:197], v[56:59]
	v_mfma_f32_16x16x32_bf16 v[44:47], v[136:139], v[202:205], v[44:47]
	v_mfma_f32_16x16x32_bf16 v[40:43], v[164:167], v[202:205], v[40:43]
	v_mfma_f32_16x16x32_bf16 v[28:31], v[136:139], v[210:213], v[28:31]
	v_mfma_f32_16x16x32_bf16 v[24:27], v[164:167], v[210:213], v[24:27]
	v_mfma_f32_16x16x32_bf16 v[12:15], v[136:139], v[218:221], v[12:15]
	v_mfma_f32_16x16x32_bf16 v[8:11], v[164:167], v[218:221], v[8:11]
	s_setprio 0
	s_setprio 1
	v_mfma_f32_16x16x32_bf16 v[52:55], v[174:177], v[190:193], v[52:55]
	v_mfma_f32_16x16x32_bf16 v[48:51], v[182:185], v[190:193], v[48:51]
	v_mfma_f32_16x16x32_bf16 v[36:39], v[174:177], v[198:201], v[36:39]
	v_mfma_f32_16x16x32_bf16 v[32:35], v[182:185], v[198:201], v[32:35]
	v_mfma_f32_16x16x32_bf16 v[20:23], v[174:177], v[206:209], v[20:23]
	v_mfma_f32_16x16x32_bf16 v[16:19], v[182:185], v[206:209], v[16:19]
	v_mfma_f32_16x16x32_bf16 v[4:7], v[174:177], v[214:217], v[4:7]
	v_mfma_f32_16x16x32_bf16 v[0:3], v[182:185], v[214:217], v[0:3]
	v_mfma_f32_16x16x32_bf16 v[52:55], v[178:181], v[194:197], v[52:55]
	v_mfma_f32_16x16x32_bf16 v[48:51], v[186:189], v[194:197], v[48:51]
	v_mfma_f32_16x16x32_bf16 v[36:39], v[178:181], v[202:205], v[36:39]
	v_mfma_f32_16x16x32_bf16 v[32:35], v[186:189], v[202:205], v[32:35]
	v_mfma_f32_16x16x32_bf16 v[20:23], v[178:181], v[210:213], v[20:23]
	v_mfma_f32_16x16x32_bf16 v[16:19], v[186:189], v[210:213], v[16:19]
	v_mfma_f32_16x16x32_bf16 v[4:7], v[178:181], v[218:221], v[4:7]
	v_mfma_f32_16x16x32_bf16 v[0:3], v[186:189], v[218:221], v[0:3]
	s_barrier
	s_setprio 0
	s_add_u32 s48, s48, 0x100
	s_addc_u32 s49, s49, 0
	s_cmpk_eq_i32 s48, 0x800
	s_cbranch_scc1 .LBB0_721

.LBB0_805:
	s_add_u32 s27, s61, s4
	s_addc_u32 s72, s62, s5
	s_add_u32 s73, s63, s6
	s_addc_u32 s78, s64, s7
	s_ashr_i32 s21, s20, 31
	s_lshl_b64 s[4:5], s[20:21], 19
	s_add_u32 s22, s40, s4
	s_addc_u32 s23, s41, s5
	s_and_b64 s[6:7], s[0:1], exec
	s_cselect_b32 s21, s23, s31
	s_cselect_b32 s79, s22, s30
	s_ashr_i32 s19, s18, 31
	s_lshl_b64 s[6:7], s[18:19], 19
	s_add_u32 s24, s42, s6
	s_addc_u32 s25, s43, s7
	s_and_b64 s[36:37], s[0:1], exec
	s_cselect_b32 s19, s25, s29
	s_cselect_b32 s80, s24, s28
	s_add_u32 s36, s79, 0x80
	s_addc_u32 s37, s21, 0
	s_add_u32 s38, s80, 0x80
	s_addc_u32 s39, s19, 0
	v_lshl_add_u64 v[148:149], s[30:31], 0, v[140:141]
	v_lshl_add_u64 v[150:151], s[30:31], 0, v[142:143]
	s_mov_b32 s81, 0
	s_mov_b64 s[44:45], 0
	v_add_u32_e32 v154, 0x10000, v157
	s_add_u32 s52, s30, s44
	s_addc_u32 s53, s31, s45
	s_mov_b64 s[100:101], s[52:53]
	s_add_u32 s83, s28, s44
	s_addc_u32 s82, s29, s45
	s_add_u32 s46, s52, 0x180
	s_addc_u32 s47, s53, 0
	s_add_u32 s48, s83, 0x180
	s_addc_u32 s49, s82, 0
	s_add_u32 s52, s52, 0x100
	s_addc_u32 s53, s53, 0
	s_add_u32 s50, s83, 0x100
	s_addc_u32 s51, s82, 0
	s_cmpk_eq_i32 s44, 0x700
	s_cselect_b32 s46, s36, s46
	s_cselect_b32 s47, s37, s47
	s_cselect_b32 s48, s38, s48
	s_cselect_b32 s49, s39, s49
	s_cselect_b32 s52, s79, s52
	s_cselect_b32 s53, s21, s53
	s_cselect_b32 s50, s80, s50
	s_cselect_b32 s51, s19, s51
	ds_read_b128 v[166:169], v154
	ds_read_b128 v[170:173], v154 offset:1024
	ds_read_b128 v[174:177], v154 offset:2048
	ds_read_b128 v[178:181], v154 offset:3072
	ds_read_b128 v[182:185], v154 offset:16384
	ds_read_b128 v[186:189], v154 offset:17408
	ds_read_b128 v[190:193], v154 offset:18432
	ds_read_b128 v[194:197], v154 offset:19456
	s_add_i32 m0, s57, 0xc000
	ds_read_b128 v[198:201], v161
	ds_read_b128 v[202:205], v161 offset:1024
	ds_read_b128 v[206:209], v161 offset:2048
	ds_read_b128 v[210:213], v161 offset:3072
	ds_read_b128 v[214:217], v161 offset:4096
	ds_read_b128 v[218:221], v161 offset:5120
	ds_read_b128 v[222:225], v161 offset:6144
	global_load_lds_dwordx4 v140, s[100:101]
	s_add_i32 m0, s57, 0xe000
	ds_read_b128 v[226:229], v161 offset:7168
	global_load_lds_dwordx4 v142, s[100:101]
	s_waitcnt vmcnt(8)
	s_waitcnt lgkmcnt(0)
	s_setprio 1
	s_barrier
	v_mfma_f32_16x16x32_bf16 v[124:127], v[166:169], v[198:201], 0
	v_mfma_f32_16x16x32_bf16 v[120:123], v[174:177], v[198:201], 0
	v_mfma_f32_16x16x32_bf16 v[108:111], v[166:169], v[206:209], 0
	v_mfma_f32_16x16x32_bf16 v[104:107], v[174:177], v[206:209], 0
	v_mfma_f32_16x16x32_bf16 v[92:95], v[166:169], v[214:217], 0
	v_mfma_f32_16x16x32_bf16 v[88:91], v[174:177], v[214:217], 0
	v_mfma_f32_16x16x32_bf16 v[76:79], v[166:169], v[222:225], 0
	v_mfma_f32_16x16x32_bf16 v[72:75], v[174:177], v[222:225], 0
	v_mfma_f32_16x16x32_bf16 v[124:127], v[170:173], v[202:205], v[124:127]
	v_mfma_f32_16x16x32_bf16 v[120:123], v[178:181], v[202:205], v[120:123]
	v_mfma_f32_16x16x32_bf16 v[108:111], v[170:173], v[210:213], v[108:111]
	v_mfma_f32_16x16x32_bf16 v[104:107], v[178:181], v[210:213], v[104:107]
	v_mfma_f32_16x16x32_bf16 v[92:95], v[170:173], v[218:221], v[92:95]
	v_mfma_f32_16x16x32_bf16 v[88:91], v[178:181], v[218:221], v[88:91]
	v_mfma_f32_16x16x32_bf16 v[76:79], v[170:173], v[226:229], v[76:79]
	v_mfma_f32_16x16x32_bf16 v[72:75], v[178:181], v[226:229], v[72:75]
	s_setprio 0
	s_setprio 1
	v_mfma_f32_16x16x32_bf16 v[116:119], v[182:185], v[198:201], 0
	v_mfma_f32_16x16x32_bf16 v[112:115], v[190:193], v[198:201], 0
	v_mfma_f32_16x16x32_bf16 v[100:103], v[182:185], v[206:209], 0
	v_mfma_f32_16x16x32_bf16 v[96:99], v[190:193], v[206:209], 0
	v_mfma_f32_16x16x32_bf16 v[84:87], v[182:185], v[214:217], 0
	v_mfma_f32_16x16x32_bf16 v[80:83], v[190:193], v[214:217], 0
	v_mfma_f32_16x16x32_bf16 v[68:71], v[182:185], v[222:225], 0
	v_mfma_f32_16x16x32_bf16 v[64:67], v[190:193], v[222:225], 0
	v_mfma_f32_16x16x32_bf16 v[116:119], v[186:189], v[202:205], v[116:119]
	v_mfma_f32_16x16x32_bf16 v[112:115], v[194:197], v[202:205], v[112:115]
	v_mfma_f32_16x16x32_bf16 v[100:103], v[186:189], v[210:213], v[100:103]
	v_mfma_f32_16x16x32_bf16 v[96:99], v[194:197], v[210:213], v[96:99]
	v_mfma_f32_16x16x32_bf16 v[84:87], v[186:189], v[218:221], v[84:87]
	v_mfma_f32_16x16x32_bf16 v[80:83], v[194:197], v[218:221], v[80:83]
	v_mfma_f32_16x16x32_bf16 v[68:71], v[186:189], v[226:229], v[68:71]
	v_mfma_f32_16x16x32_bf16 v[64:67], v[194:197], v[226:229], v[64:67]
	s_barrier
	s_setprio 0
	s_add_i32 s8, s68, s54
	s_mov_b32 m0, s8
	ds_read_b128 v[198:201], v161 offset:16384
	ds_read_b128 v[202:205], v161 offset:17408
	ds_read_b128 v[206:209], v161 offset:18432
	global_load_lds_dwordx4 v128, s[50:51]
	s_add_i32 m0, s8, 0x2000
	ds_read_b128 v[210:213], v161 offset:19456
	global_load_lds_dwordx4 v130, s[50:51]
	s_add_u32 s50, s50, 0x40000
	s_addc_u32 s51, s51, 0
	s_add_i32 s8, s69, s54
	s_mov_b32 m0, s8
	ds_read_b128 v[214:217], v161 offset:20480
	global_load_lds_dwordx4 v128, s[50:51]
	s_add_i32 m0, s8, 0x2000
	ds_read_b128 v[218:221], v161 offset:21504
	global_load_lds_dwordx4 v130, s[50:51]
	s_mov_b32 m0, s57
	ds_read_b128 v[222:225], v161 offset:22528
	global_load_lds_dwordx4 v134, s[52:53]
	s_mov_b32 m0, s58
	ds_read_b128 v[226:229], v161 offset:23552
	global_load_lds_dwordx4 v132, s[52:53]
	s_waitcnt vmcnt(8)
	s_waitcnt lgkmcnt(0)
	s_setprio 1
	s_barrier
	v_mfma_f32_16x16x32_bf16 v[60:63], v[166:169], v[198:201], 0
	v_mfma_f32_16x16x32_bf16 v[56:59], v[174:177], v[198:201], 0
	v_mfma_f32_16x16x32_bf16 v[44:47], v[166:169], v[206:209], 0
	v_mfma_f32_16x16x32_bf16 v[40:43], v[174:177], v[206:209], 0
	v_mfma_f32_16x16x32_bf16 v[28:31], v[166:169], v[214:217], 0
	v_mfma_f32_16x16x32_bf16 v[24:27], v[174:177], v[214:217], 0
	v_mfma_f32_16x16x32_bf16 v[12:15], v[166:169], v[222:225], 0
	v_mfma_f32_16x16x32_bf16 v[8:11], v[174:177], v[222:225], 0
	v_mfma_f32_16x16x32_bf16 v[60:63], v[170:173], v[202:205], v[60:63]
	v_mfma_f32_16x16x32_bf16 v[56:59], v[178:181], v[202:205], v[56:59]
	v_mfma_f32_16x16x32_bf16 v[44:47], v[170:173], v[210:213], v[44:47]
	v_mfma_f32_16x16x32_bf16 v[40:43], v[178:181], v[210:213], v[40:43]
	v_mfma_f32_16x16x32_bf16 v[28:31], v[170:173], v[218:221], v[28:31]
	v_mfma_f32_16x16x32_bf16 v[24:27], v[178:181], v[218:221], v[24:27]
	v_mfma_f32_16x16x32_bf16 v[12:15], v[170:173], v[226:229], v[12:15]
	v_mfma_f32_16x16x32_bf16 v[8:11], v[178:181], v[226:229], v[8:11]
	s_setprio 0
	s_setprio 1
	v_mfma_f32_16x16x32_bf16 v[52:55], v[182:185], v[198:201], 0
	v_mfma_f32_16x16x32_bf16 v[48:51], v[190:193], v[198:201], 0
	v_mfma_f32_16x16x32_bf16 v[36:39], v[182:185], v[206:209], 0
	v_mfma_f32_16x16x32_bf16 v[32:35], v[190:193], v[206:209], 0
	v_mfma_f32_16x16x32_bf16 v[20:23], v[182:185], v[214:217], 0
	v_mfma_f32_16x16x32_bf16 v[16:19], v[190:193], v[214:217], 0
	v_mfma_f32_16x16x32_bf16 v[4:7], v[182:185], v[222:225], 0
	v_mfma_f32_16x16x32_bf16 v[0:3], v[190:193], v[222:225], 0
	v_mfma_f32_16x16x32_bf16 v[52:55], v[186:189], v[202:205], v[52:55]
	v_mfma_f32_16x16x32_bf16 v[48:51], v[194:197], v[202:205], v[48:51]
	v_mfma_f32_16x16x32_bf16 v[36:39], v[186:189], v[210:213], v[36:39]
	v_mfma_f32_16x16x32_bf16 v[32:35], v[194:197], v[210:213], v[32:35]
	v_mfma_f32_16x16x32_bf16 v[20:23], v[186:189], v[218:221], v[20:23]
	v_mfma_f32_16x16x32_bf16 v[16:19], v[194:197], v[218:221], v[16:19]
	v_mfma_f32_16x16x32_bf16 v[4:7], v[186:189], v[226:229], v[4:7]
	v_mfma_f32_16x16x32_bf16 v[0:3], v[194:197], v[226:229], v[0:3]
	s_barrier
	s_setprio 0
	s_add_i32 s8, 0, 0x18000
	s_add_i32 s82, 0, 0x1c000
	ds_read_b128 v[166:169], v154 offset:32768
	ds_read_b128 v[170:173], v154 offset:33792
	ds_read_b128 v[174:177], v154 offset:34816
	ds_read_b128 v[178:181], v154 offset:35840
	ds_read_b128 v[182:185], v154 offset:49152
	ds_read_b128 v[186:189], v154 offset:50176
	ds_read_b128 v[190:193], v154 offset:51200
	ds_read_b128 v[194:197], v154 offset:52224
	s_add_u32 s50, s52, 0x40000
	s_addc_u32 s51, s53, 0
	s_mov_b32 m0, s59
	ds_read_b128 v[198:201], v161 offset:32768
	ds_read_b128 v[202:205], v161 offset:33792
	ds_read_b128 v[206:209], v161 offset:34816
	ds_read_b128 v[210:213], v161 offset:35840
	ds_read_b128 v[214:217], v161 offset:36864
	ds_read_b128 v[218:221], v161 offset:37888
	ds_read_b128 v[222:225], v161 offset:38912
	global_load_lds_dwordx4 v134, s[50:51]
	s_mov_b32 m0, s60
	ds_read_b128 v[226:229], v161 offset:39936
	global_load_lds_dwordx4 v132, s[50:51]
	s_waitcnt vmcnt(8)
	s_waitcnt lgkmcnt(0)
	s_setprio 1
	s_barrier
	v_mfma_f32_16x16x32_bf16 v[124:127], v[166:169], v[198:201], v[124:127]
	v_mfma_f32_16x16x32_bf16 v[120:123], v[174:177], v[198:201], v[120:123]
	v_mfma_f32_16x16x32_bf16 v[108:111], v[166:169], v[206:209], v[108:111]
	v_mfma_f32_16x16x32_bf16 v[104:107], v[174:177], v[206:209], v[104:107]
	v_mfma_f32_16x16x32_bf16 v[92:95], v[166:169], v[214:217], v[92:95]
	v_mfma_f32_16x16x32_bf16 v[88:91], v[174:177], v[214:217], v[88:91]
	v_mfma_f32_16x16x32_bf16 v[76:79], v[166:169], v[222:225], v[76:79]
	v_mfma_f32_16x16x32_bf16 v[72:75], v[174:177], v[222:225], v[72:75]
	v_mfma_f32_16x16x32_bf16 v[124:127], v[170:173], v[202:205], v[124:127]
	v_mfma_f32_16x16x32_bf16 v[120:123], v[178:181], v[202:205], v[120:123]
	v_mfma_f32_16x16x32_bf16 v[108:111], v[170:173], v[210:213], v[108:111]
	v_mfma_f32_16x16x32_bf16 v[104:107], v[178:181], v[210:213], v[104:107]
	v_mfma_f32_16x16x32_bf16 v[92:95], v[170:173], v[218:221], v[92:95]
	v_mfma_f32_16x16x32_bf16 v[88:91], v[178:181], v[218:221], v[88:91]
	v_mfma_f32_16x16x32_bf16 v[76:79], v[170:173], v[226:229], v[76:79]
	v_mfma_f32_16x16x32_bf16 v[72:75], v[178:181], v[226:229], v[72:75]
	s_setprio 0
	s_setprio 1
	v_mfma_f32_16x16x32_bf16 v[116:119], v[182:185], v[198:201], v[116:119]
	v_mfma_f32_16x16x32_bf16 v[112:115], v[190:193], v[198:201], v[112:115]
	v_mfma_f32_16x16x32_bf16 v[100:103], v[182:185], v[206:209], v[100:103]
	v_mfma_f32_16x16x32_bf16 v[96:99], v[190:193], v[206:209], v[96:99]
	v_mfma_f32_16x16x32_bf16 v[84:87], v[182:185], v[214:217], v[84:87]
	v_mfma_f32_16x16x32_bf16 v[80:83], v[190:193], v[214:217], v[80:83]
	v_mfma_f32_16x16x32_bf16 v[68:71], v[182:185], v[222:225], v[68:71]
	v_mfma_f32_16x16x32_bf16 v[64:67], v[190:193], v[222:225], v[64:67]
	v_mfma_f32_16x16x32_bf16 v[116:119], v[186:189], v[202:205], v[116:119]
	v_mfma_f32_16x16x32_bf16 v[112:115], v[194:197], v[202:205], v[112:115]
	v_mfma_f32_16x16x32_bf16 v[100:103], v[186:189], v[210:213], v[100:103]
	v_mfma_f32_16x16x32_bf16 v[96:99], v[194:197], v[210:213], v[96:99]
	v_mfma_f32_16x16x32_bf16 v[84:87], v[186:189], v[218:221], v[84:87]
	v_mfma_f32_16x16x32_bf16 v[80:83], v[194:197], v[218:221], v[80:83]
	v_mfma_f32_16x16x32_bf16 v[68:71], v[186:189], v[226:229], v[68:71]
	v_mfma_f32_16x16x32_bf16 v[64:67], v[194:197], v[226:229], v[64:67]
	s_barrier
	s_setprio 0
	s_add_i32 s8, s8, s54
	s_mov_b32 m0, s8
	ds_read_b128 v[198:201], v161 offset:49152
	ds_read_b128 v[202:205], v161 offset:50176
	ds_read_b128 v[206:209], v161 offset:51200
	global_load_lds_dwordx4 v128, s[48:49]
	s_add_i32 m0, s8, 0x2000
	ds_read_b128 v[210:213], v161 offset:52224
	global_load_lds_dwordx4 v130, s[48:49]
	s_add_u32 s48, s48, 0x40000
	s_addc_u32 s49, s49, 0
	s_add_i32 s8, s82, s54
	s_mov_b32 m0, s8
	ds_read_b128 v[214:217], v161 offset:53248
	global_load_lds_dwordx4 v128, s[48:49]
	s_add_i32 m0, s8, 0x2000
	ds_read_b128 v[218:221], v161 offset:54272
	global_load_lds_dwordx4 v130, s[48:49]
	s_mov_b32 m0, s65
	ds_read_b128 v[222:225], v161 offset:55296
	global_load_lds_dwordx4 v134, s[46:47]
	s_mov_b32 m0, s66
	ds_read_b128 v[226:229], v161 offset:56320
	global_load_lds_dwordx4 v132, s[46:47]
	s_waitcnt vmcnt(8)
	s_waitcnt lgkmcnt(0)
	s_setprio 1
	s_barrier
	v_mfma_f32_16x16x32_bf16 v[60:63], v[166:169], v[198:201], v[60:63]
	v_mfma_f32_16x16x32_bf16 v[56:59], v[174:177], v[198:201], v[56:59]
	v_mfma_f32_16x16x32_bf16 v[44:47], v[166:169], v[206:209], v[44:47]
	v_mfma_f32_16x16x32_bf16 v[40:43], v[174:177], v[206:209], v[40:43]
	v_mfma_f32_16x16x32_bf16 v[28:31], v[166:169], v[214:217], v[28:31]
	v_mfma_f32_16x16x32_bf16 v[24:27], v[174:177], v[214:217], v[24:27]
	v_mfma_f32_16x16x32_bf16 v[12:15], v[166:169], v[222:225], v[12:15]
	v_mfma_f32_16x16x32_bf16 v[8:11], v[174:177], v[222:225], v[8:11]
	v_mfma_f32_16x16x32_bf16 v[60:63], v[170:173], v[202:205], v[60:63]
	v_mfma_f32_16x16x32_bf16 v[56:59], v[178:181], v[202:205], v[56:59]
	v_mfma_f32_16x16x32_bf16 v[44:47], v[170:173], v[210:213], v[44:47]
	v_mfma_f32_16x16x32_bf16 v[40:43], v[178:181], v[210:213], v[40:43]
	v_mfma_f32_16x16x32_bf16 v[28:31], v[170:173], v[218:221], v[28:31]
	v_mfma_f32_16x16x32_bf16 v[24:27], v[178:181], v[218:221], v[24:27]
	v_mfma_f32_16x16x32_bf16 v[12:15], v[170:173], v[226:229], v[12:15]
	v_mfma_f32_16x16x32_bf16 v[8:11], v[178:181], v[226:229], v[8:11]
	s_setprio 0
	s_setprio 1
	v_mfma_f32_16x16x32_bf16 v[52:55], v[182:185], v[198:201], v[52:55]
	v_mfma_f32_16x16x32_bf16 v[48:51], v[190:193], v[198:201], v[48:51]
	v_mfma_f32_16x16x32_bf16 v[36:39], v[182:185], v[206:209], v[36:39]
	v_mfma_f32_16x16x32_bf16 v[32:35], v[190:193], v[206:209], v[32:35]
	v_mfma_f32_16x16x32_bf16 v[20:23], v[182:185], v[214:217], v[20:23]
	v_mfma_f32_16x16x32_bf16 v[16:19], v[190:193], v[214:217], v[16:19]
	v_mfma_f32_16x16x32_bf16 v[4:7], v[182:185], v[222:225], v[4:7]
	v_mfma_f32_16x16x32_bf16 v[0:3], v[190:193], v[222:225], v[0:3]
	v_mfma_f32_16x16x32_bf16 v[52:55], v[186:189], v[202:205], v[52:55]
	v_mfma_f32_16x16x32_bf16 v[48:51], v[194:197], v[202:205], v[48:51]
	v_mfma_f32_16x16x32_bf16 v[36:39], v[186:189], v[210:213], v[36:39]
	v_mfma_f32_16x16x32_bf16 v[32:35], v[194:197], v[210:213], v[32:35]
	v_mfma_f32_16x16x32_bf16 v[20:23], v[186:189], v[218:221], v[20:23]
	v_mfma_f32_16x16x32_bf16 v[16:19], v[194:197], v[218:221], v[16:19]
	v_mfma_f32_16x16x32_bf16 v[4:7], v[186:189], v[226:229], v[4:7]
	v_mfma_f32_16x16x32_bf16 v[0:3], v[194:197], v[226:229], v[0:3]
	s_barrier
	s_setprio 0
	s_add_u32 s44, s44, 0x100
	s_addc_u32 s45, s45, 0
	s_cmpk_eq_i32 s44, 0x800
	s_cbranch_scc1 .LBB0_813
	s_branch .LBB0_807
.LBB0_806:
	ds_read_b128 v[166:169], v154
	ds_read_b128 v[170:173], v154 offset:1024
	ds_read_b128 v[174:177], v154 offset:2048
	ds_read_b128 v[178:181], v154 offset:3072
	ds_read_b128 v[182:185], v154 offset:16384
	ds_read_b128 v[186:189], v154 offset:17408
	ds_read_b128 v[190:193], v154 offset:18432
	ds_read_b128 v[194:197], v154 offset:19456
	s_add_i32 m0, s57, 0xc000
	ds_read_b128 v[198:201], v161
	ds_read_b128 v[202:205], v161 offset:1024
	ds_read_b128 v[206:209], v161 offset:2048
	ds_read_b128 v[210:213], v161 offset:3072
	ds_read_b128 v[214:217], v161 offset:4096
	ds_read_b128 v[218:221], v161 offset:5120
	ds_read_b128 v[222:225], v161 offset:6144
	global_load_lds_dwordx4 v140, s[100:101]
	s_add_i32 m0, s57, 0xe000
	ds_read_b128 v[226:229], v161 offset:7168
	global_load_lds_dwordx4 v142, s[100:101]
	s_waitcnt vmcnt(8)
	s_waitcnt lgkmcnt(0)
	s_setprio 1
	s_barrier
	v_mfma_f32_16x16x32_bf16 v[124:127], v[166:169], v[198:201], v[124:127]
	v_mfma_f32_16x16x32_bf16 v[120:123], v[174:177], v[198:201], v[120:123]
	v_mfma_f32_16x16x32_bf16 v[108:111], v[166:169], v[206:209], v[108:111]
	v_mfma_f32_16x16x32_bf16 v[104:107], v[174:177], v[206:209], v[104:107]
	v_mfma_f32_16x16x32_bf16 v[92:95], v[166:169], v[214:217], v[92:95]
	v_mfma_f32_16x16x32_bf16 v[88:91], v[174:177], v[214:217], v[88:91]
	v_mfma_f32_16x16x32_bf16 v[76:79], v[166:169], v[222:225], v[76:79]
	v_mfma_f32_16x16x32_bf16 v[72:75], v[174:177], v[222:225], v[72:75]
	v_mfma_f32_16x16x32_bf16 v[124:127], v[170:173], v[202:205], v[124:127]
	v_mfma_f32_16x16x32_bf16 v[120:123], v[178:181], v[202:205], v[120:123]
	v_mfma_f32_16x16x32_bf16 v[108:111], v[170:173], v[210:213], v[108:111]
	v_mfma_f32_16x16x32_bf16 v[104:107], v[178:181], v[210:213], v[104:107]
	v_mfma_f32_16x16x32_bf16 v[92:95], v[170:173], v[218:221], v[92:95]
	v_mfma_f32_16x16x32_bf16 v[88:91], v[178:181], v[218:221], v[88:91]
	v_mfma_f32_16x16x32_bf16 v[76:79], v[170:173], v[226:229], v[76:79]
	v_mfma_f32_16x16x32_bf16 v[72:75], v[178:181], v[226:229], v[72:75]
	s_setprio 0
	s_setprio 1
	v_mfma_f32_16x16x32_bf16 v[116:119], v[182:185], v[198:201], v[116:119]
	v_mfma_f32_16x16x32_bf16 v[112:115], v[190:193], v[198:201], v[112:115]
	v_mfma_f32_16x16x32_bf16 v[100:103], v[182:185], v[206:209], v[100:103]
	v_mfma_f32_16x16x32_bf16 v[96:99], v[190:193], v[206:209], v[96:99]
	v_mfma_f32_16x16x32_bf16 v[84:87], v[182:185], v[214:217], v[84:87]
	v_mfma_f32_16x16x32_bf16 v[80:83], v[190:193], v[214:217], v[80:83]
	v_mfma_f32_16x16x32_bf16 v[68:71], v[182:185], v[222:225], v[68:71]
	v_mfma_f32_16x16x32_bf16 v[64:67], v[190:193], v[222:225], v[64:67]
	v_mfma_f32_16x16x32_bf16 v[116:119], v[186:189], v[202:205], v[116:119]
	v_mfma_f32_16x16x32_bf16 v[112:115], v[194:197], v[202:205], v[112:115]
	v_mfma_f32_16x16x32_bf16 v[100:103], v[186:189], v[210:213], v[100:103]
	v_mfma_f32_16x16x32_bf16 v[96:99], v[194:197], v[210:213], v[96:99]
	v_mfma_f32_16x16x32_bf16 v[84:87], v[186:189], v[218:221], v[84:87]
	v_mfma_f32_16x16x32_bf16 v[80:83], v[194:197], v[218:221], v[80:83]
	v_mfma_f32_16x16x32_bf16 v[68:71], v[186:189], v[226:229], v[68:71]
	v_mfma_f32_16x16x32_bf16 v[64:67], v[194:197], v[226:229], v[64:67]
	s_barrier
	s_setprio 0
	s_add_i32 s8, s68, s54
	s_mov_b32 m0, s8
	ds_read_b128 v[198:201], v161 offset:16384
	ds_read_b128 v[202:205], v161 offset:17408
	ds_read_b128 v[206:209], v161 offset:18432
	global_load_lds_dwordx4 v128, s[50:51]
	s_add_i32 m0, s8, 0x2000
	ds_read_b128 v[210:213], v161 offset:19456
	global_load_lds_dwordx4 v130, s[50:51]
	s_add_u32 s50, s50, 0x40000
	s_addc_u32 s51, s51, 0
	s_add_i32 s8, s69, s54
	s_mov_b32 m0, s8
	ds_read_b128 v[214:217], v161 offset:20480
	global_load_lds_dwordx4 v128, s[50:51]
	s_add_i32 m0, s8, 0x2000
	ds_read_b128 v[218:221], v161 offset:21504
	global_load_lds_dwordx4 v130, s[50:51]
	s_mov_b32 m0, s57
	ds_read_b128 v[222:225], v161 offset:22528
	global_load_lds_dwordx4 v134, s[52:53]
	s_mov_b32 m0, s58
	ds_read_b128 v[226:229], v161 offset:23552
	global_load_lds_dwordx4 v132, s[52:53]
	s_waitcnt vmcnt(8)
	s_waitcnt lgkmcnt(0)
	s_setprio 1
	s_barrier
	v_mfma_f32_16x16x32_bf16 v[60:63], v[166:169], v[198:201], v[60:63]
	v_mfma_f32_16x16x32_bf16 v[56:59], v[174:177], v[198:201], v[56:59]
	v_mfma_f32_16x16x32_bf16 v[44:47], v[166:169], v[206:209], v[44:47]
	v_mfma_f32_16x16x32_bf16 v[40:43], v[174:177], v[206:209], v[40:43]
	v_mfma_f32_16x16x32_bf16 v[28:31], v[166:169], v[214:217], v[28:31]
	v_mfma_f32_16x16x32_bf16 v[24:27], v[174:177], v[214:217], v[24:27]
	v_mfma_f32_16x16x32_bf16 v[12:15], v[166:169], v[222:225], v[12:15]
	v_mfma_f32_16x16x32_bf16 v[8:11], v[174:177], v[222:225], v[8:11]
	v_mfma_f32_16x16x32_bf16 v[60:63], v[170:173], v[202:205], v[60:63]
	v_mfma_f32_16x16x32_bf16 v[56:59], v[178:181], v[202:205], v[56:59]
	v_mfma_f32_16x16x32_bf16 v[44:47], v[170:173], v[210:213], v[44:47]
	v_mfma_f32_16x16x32_bf16 v[40:43], v[178:181], v[210:213], v[40:43]
	v_mfma_f32_16x16x32_bf16 v[28:31], v[170:173], v[218:221], v[28:31]
	v_mfma_f32_16x16x32_bf16 v[24:27], v[178:181], v[218:221], v[24:27]
	v_mfma_f32_16x16x32_bf16 v[12:15], v[170:173], v[226:229], v[12:15]
	v_mfma_f32_16x16x32_bf16 v[8:11], v[178:181], v[226:229], v[8:11]
	s_setprio 0
	s_setprio 1
	v_mfma_f32_16x16x32_bf16 v[52:55], v[182:185], v[198:201], v[52:55]
	v_mfma_f32_16x16x32_bf16 v[48:51], v[190:193], v[198:201], v[48:51]
	v_mfma_f32_16x16x32_bf16 v[36:39], v[182:185], v[206:209], v[36:39]
	v_mfma_f32_16x16x32_bf16 v[32:35], v[190:193], v[206:209], v[32:35]
	v_mfma_f32_16x16x32_bf16 v[20:23], v[182:185], v[214:217], v[20:23]
	v_mfma_f32_16x16x32_bf16 v[16:19], v[190:193], v[214:217], v[16:19]
	v_mfma_f32_16x16x32_bf16 v[4:7], v[182:185], v[222:225], v[4:7]
	v_mfma_f32_16x16x32_bf16 v[0:3], v[190:193], v[222:225], v[0:3]
	v_mfma_f32_16x16x32_bf16 v[52:55], v[186:189], v[202:205], v[52:55]
	v_mfma_f32_16x16x32_bf16 v[48:51], v[194:197], v[202:205], v[48:51]
	v_mfma_f32_16x16x32_bf16 v[36:39], v[186:189], v[210:213], v[36:39]
	v_mfma_f32_16x16x32_bf16 v[32:35], v[194:197], v[210:213], v[32:35]
	v_mfma_f32_16x16x32_bf16 v[20:23], v[186:189], v[218:221], v[20:23]
	v_mfma_f32_16x16x32_bf16 v[16:19], v[194:197], v[218:221], v[16:19]
	v_mfma_f32_16x16x32_bf16 v[4:7], v[186:189], v[226:229], v[4:7]
	v_mfma_f32_16x16x32_bf16 v[0:3], v[194:197], v[226:229], v[0:3]
	s_barrier
	s_setprio 0
	s_add_i32 s8, 0, 0x18000
	s_add_i32 s82, 0, 0x1c000
	ds_read_b128 v[166:169], v154 offset:32768
	ds_read_b128 v[170:173], v154 offset:33792
	ds_read_b128 v[174:177], v154 offset:34816
	ds_read_b128 v[178:181], v154 offset:35840
	ds_read_b128 v[182:185], v154 offset:49152
	ds_read_b128 v[186:189], v154 offset:50176
	ds_read_b128 v[190:193], v154 offset:51200
	ds_read_b128 v[194:197], v154 offset:52224
	s_add_u32 s50, s52, 0x40000
	s_addc_u32 s51, s53, 0
	s_mov_b32 m0, s59
	ds_read_b128 v[198:201], v161 offset:32768
	ds_read_b128 v[202:205], v161 offset:33792
	ds_read_b128 v[206:209], v161 offset:34816
	ds_read_b128 v[210:213], v161 offset:35840
	ds_read_b128 v[214:217], v161 offset:36864
	ds_read_b128 v[218:221], v161 offset:37888
	ds_read_b128 v[222:225], v161 offset:38912
	global_load_lds_dwordx4 v134, s[50:51]
	s_mov_b32 m0, s60
	ds_read_b128 v[226:229], v161 offset:39936
	global_load_lds_dwordx4 v132, s[50:51]
	s_waitcnt vmcnt(8)
	s_waitcnt lgkmcnt(0)
	s_setprio 1
	s_barrier
	v_mfma_f32_16x16x32_bf16 v[124:127], v[166:169], v[198:201], v[124:127]
	v_mfma_f32_16x16x32_bf16 v[120:123], v[174:177], v[198:201], v[120:123]
	v_mfma_f32_16x16x32_bf16 v[108:111], v[166:169], v[206:209], v[108:111]
	v_mfma_f32_16x16x32_bf16 v[104:107], v[174:177], v[206:209], v[104:107]
	v_mfma_f32_16x16x32_bf16 v[92:95], v[166:169], v[214:217], v[92:95]
	v_mfma_f32_16x16x32_bf16 v[88:91], v[174:177], v[214:217], v[88:91]
	v_mfma_f32_16x16x32_bf16 v[76:79], v[166:169], v[222:225], v[76:79]
	v_mfma_f32_16x16x32_bf16 v[72:75], v[174:177], v[222:225], v[72:75]
	v_mfma_f32_16x16x32_bf16 v[124:127], v[170:173], v[202:205], v[124:127]
	v_mfma_f32_16x16x32_bf16 v[120:123], v[178:181], v[202:205], v[120:123]
	v_mfma_f32_16x16x32_bf16 v[108:111], v[170:173], v[210:213], v[108:111]
	v_mfma_f32_16x16x32_bf16 v[104:107], v[178:181], v[210:213], v[104:107]
	v_mfma_f32_16x16x32_bf16 v[92:95], v[170:173], v[218:221], v[92:95]
	v_mfma_f32_16x16x32_bf16 v[88:91], v[178:181], v[218:221], v[88:91]
	v_mfma_f32_16x16x32_bf16 v[76:79], v[170:173], v[226:229], v[76:79]
	v_mfma_f32_16x16x32_bf16 v[72:75], v[178:181], v[226:229], v[72:75]
	s_setprio 0
	s_setprio 1
	v_mfma_f32_16x16x32_bf16 v[116:119], v[182:185], v[198:201], v[116:119]
	v_mfma_f32_16x16x32_bf16 v[112:115], v[190:193], v[198:201], v[112:115]
	v_mfma_f32_16x16x32_bf16 v[100:103], v[182:185], v[206:209], v[100:103]
	v_mfma_f32_16x16x32_bf16 v[96:99], v[190:193], v[206:209], v[96:99]
	v_mfma_f32_16x16x32_bf16 v[84:87], v[182:185], v[214:217], v[84:87]
	v_mfma_f32_16x16x32_bf16 v[80:83], v[190:193], v[214:217], v[80:83]
	v_mfma_f32_16x16x32_bf16 v[68:71], v[182:185], v[222:225], v[68:71]
	v_mfma_f32_16x16x32_bf16 v[64:67], v[190:193], v[222:225], v[64:67]
	v_mfma_f32_16x16x32_bf16 v[116:119], v[186:189], v[202:205], v[116:119]
	v_mfma_f32_16x16x32_bf16 v[112:115], v[194:197], v[202:205], v[112:115]
	v_mfma_f32_16x16x32_bf16 v[100:103], v[186:189], v[210:213], v[100:103]
	v_mfma_f32_16x16x32_bf16 v[96:99], v[194:197], v[210:213], v[96:99]
	v_mfma_f32_16x16x32_bf16 v[84:87], v[186:189], v[218:221], v[84:87]
	v_mfma_f32_16x16x32_bf16 v[80:83], v[194:197], v[218:221], v[80:83]
	v_mfma_f32_16x16x32_bf16 v[68:71], v[186:189], v[226:229], v[68:71]
	v_mfma_f32_16x16x32_bf16 v[64:67], v[194:197], v[226:229], v[64:67]
	s_barrier
	s_setprio 0
	s_add_i32 s8, s8, s54
	s_mov_b32 m0, s8
	ds_read_b128 v[198:201], v161 offset:49152
	ds_read_b128 v[202:205], v161 offset:50176
	ds_read_b128 v[206:209], v161 offset:51200
	global_load_lds_dwordx4 v128, s[48:49]
	s_add_i32 m0, s8, 0x2000
	ds_read_b128 v[210:213], v161 offset:52224
	global_load_lds_dwordx4 v130, s[48:49]
	s_add_u32 s48, s48, 0x40000
	s_addc_u32 s49, s49, 0
	s_add_i32 s8, s82, s54
	s_mov_b32 m0, s8
	ds_read_b128 v[214:217], v161 offset:53248
	global_load_lds_dwordx4 v128, s[48:49]
	s_add_i32 m0, s8, 0x2000
	ds_read_b128 v[218:221], v161 offset:54272
	global_load_lds_dwordx4 v130, s[48:49]
	s_mov_b32 m0, s65
	ds_read_b128 v[222:225], v161 offset:55296
	global_load_lds_dwordx4 v134, s[46:47]
	s_mov_b32 m0, s66
	ds_read_b128 v[226:229], v161 offset:56320
	global_load_lds_dwordx4 v132, s[46:47]
	s_waitcnt vmcnt(8)
	s_waitcnt lgkmcnt(0)
	s_setprio 1
	s_barrier
	v_mfma_f32_16x16x32_bf16 v[60:63], v[166:169], v[198:201], v[60:63]
	v_mfma_f32_16x16x32_bf16 v[56:59], v[174:177], v[198:201], v[56:59]
	v_mfma_f32_16x16x32_bf16 v[44:47], v[166:169], v[206:209], v[44:47]
	v_mfma_f32_16x16x32_bf16 v[40:43], v[174:177], v[206:209], v[40:43]
	v_mfma_f32_16x16x32_bf16 v[28:31], v[166:169], v[214:217], v[28:31]
	v_mfma_f32_16x16x32_bf16 v[24:27], v[174:177], v[214:217], v[24:27]
	v_mfma_f32_16x16x32_bf16 v[12:15], v[166:169], v[222:225], v[12:15]
	v_mfma_f32_16x16x32_bf16 v[8:11], v[174:177], v[222:225], v[8:11]
	v_mfma_f32_16x16x32_bf16 v[60:63], v[170:173], v[202:205], v[60:63]
	v_mfma_f32_16x16x32_bf16 v[56:59], v[178:181], v[202:205], v[56:59]
	v_mfma_f32_16x16x32_bf16 v[44:47], v[170:173], v[210:213], v[44:47]
	v_mfma_f32_16x16x32_bf16 v[40:43], v[178:181], v[210:213], v[40:43]
	v_mfma_f32_16x16x32_bf16 v[28:31], v[170:173], v[218:221], v[28:31]
	v_mfma_f32_16x16x32_bf16 v[24:27], v[178:181], v[218:221], v[24:27]
	v_mfma_f32_16x16x32_bf16 v[12:15], v[170:173], v[226:229], v[12:15]
	v_mfma_f32_16x16x32_bf16 v[8:11], v[178:181], v[226:229], v[8:11]
	s_setprio 0
	s_setprio 1
	v_mfma_f32_16x16x32_bf16 v[52:55], v[182:185], v[198:201], v[52:55]
	v_mfma_f32_16x16x32_bf16 v[48:51], v[190:193], v[198:201], v[48:51]
	v_mfma_f32_16x16x32_bf16 v[36:39], v[182:185], v[206:209], v[36:39]
	v_mfma_f32_16x16x32_bf16 v[32:35], v[190:193], v[206:209], v[32:35]
	v_mfma_f32_16x16x32_bf16 v[20:23], v[182:185], v[214:217], v[20:23]
	v_mfma_f32_16x16x32_bf16 v[16:19], v[190:193], v[214:217], v[16:19]
	v_mfma_f32_16x16x32_bf16 v[4:7], v[182:185], v[222:225], v[4:7]
	v_mfma_f32_16x16x32_bf16 v[0:3], v[190:193], v[222:225], v[0:3]
	v_mfma_f32_16x16x32_bf16 v[52:55], v[186:189], v[202:205], v[52:55]
	v_mfma_f32_16x16x32_bf16 v[48:51], v[194:197], v[202:205], v[48:51]
	v_mfma_f32_16x16x32_bf16 v[36:39], v[186:189], v[210:213], v[36:39]
	v_mfma_f32_16x16x32_bf16 v[32:35], v[194:197], v[210:213], v[32:35]
	v_mfma_f32_16x16x32_bf16 v[20:23], v[186:189], v[218:221], v[20:23]
	v_mfma_f32_16x16x32_bf16 v[16:19], v[194:197], v[218:221], v[16:19]
	v_mfma_f32_16x16x32_bf16 v[4:7], v[186:189], v[226:229], v[4:7]
	v_mfma_f32_16x16x32_bf16 v[0:3], v[194:197], v[226:229], v[0:3]
	s_barrier
	s_setprio 0
	s_add_u32 s44, s44, 0x100
	s_addc_u32 s45, s45, 0
	s_cmpk_eq_i32 s44, 0x800
	s_cbranch_scc1 .LBB0_813

.LBB0_895:
	s_add_u32 s70, s55, s28
	s_addc_u32 s71, s56, s29
	s_add_u32 s72, s57, s30
	s_addc_u32 s73, s58, s31
	s_add_u32 s28, s4, 0x80
	s_addc_u32 s29, s5, 0
	s_add_u32 s30, s20, 0x80
	s_addc_u32 s31, s21, 0
	v_lshl_add_u64 v[128:129], s[26:27], 0, v[148:149]
	v_lshl_add_u64 v[130:131], s[26:27], 0, v[150:151]
	s_mov_b32 s78, 0
	s_mov_b64 s[36:37], 0
	v_add_u32_e32 v220, 0x10000, v165
	s_add_u32 s46, s26, s36
	s_addc_u32 s47, s27, s37
	s_mov_b64 s[100:101], s[46:47]
	s_add_u32 s80, s24, s36
	s_addc_u32 s79, s25, s37
	s_add_u32 s38, s46, 0x180
	s_addc_u32 s39, s47, 0
	s_add_u32 s40, s80, 0x180
	s_addc_u32 s41, s79, 0
	s_add_u32 s46, s46, 0x100
	s_addc_u32 s47, s47, 0
	s_add_u32 s44, s80, 0x100
	s_addc_u32 s45, s79, 0
	s_cmpk_eq_i32 s36, 0x1500
	s_cselect_b32 s38, s28, s38
	s_cselect_b32 s39, s29, s39
	s_cselect_b32 s40, s30, s40
	s_cselect_b32 s41, s31, s41
	s_cselect_b32 s46, s4, s46
	s_cselect_b32 s47, s5, s47
	s_cselect_b32 s44, s20, s44
	s_cselect_b32 s45, s21, s45
	ds_read_b128 v[132:135], v220
	ds_read_b128 v[156:159], v220 offset:1024
	ds_read_b128 v[160:163], v220 offset:2048
	ds_read_b128 v[168:171], v220 offset:3072
	ds_read_b128 v[172:175], v220 offset:16384
	ds_read_b128 v[176:179], v220 offset:17408
	ds_read_b128 v[180:183], v220 offset:18432
	ds_read_b128 v[184:187], v220 offset:19456
	s_add_i32 m0, s51, 0xc000
	ds_read_b128 v[188:191], v166
	ds_read_b128 v[192:195], v166 offset:1024
	ds_read_b128 v[196:199], v166 offset:2048
	ds_read_b128 v[200:203], v166 offset:3072
	ds_read_b128 v[204:207], v166 offset:4096
	ds_read_b128 v[208:211], v166 offset:5120
	ds_read_b128 v[212:215], v166 offset:6144
	global_load_lds_dwordx4 v148, s[100:101]
	s_add_i32 m0, s51, 0xe000
	ds_read_b128 v[216:219], v166 offset:7168
	global_load_lds_dwordx4 v150, s[100:101]
	s_waitcnt vmcnt(8)
	s_waitcnt lgkmcnt(0)
	s_setprio 1
	s_barrier
	v_mfma_f32_16x16x32_bf16 v[124:127], v[132:135], v[188:191], 0
	v_mfma_f32_16x16x32_bf16 v[120:123], v[160:163], v[188:191], 0
	v_mfma_f32_16x16x32_bf16 v[108:111], v[132:135], v[196:199], 0
	v_mfma_f32_16x16x32_bf16 v[104:107], v[160:163], v[196:199], 0
	v_mfma_f32_16x16x32_bf16 v[92:95], v[132:135], v[204:207], 0
	v_mfma_f32_16x16x32_bf16 v[88:91], v[160:163], v[204:207], 0
	v_mfma_f32_16x16x32_bf16 v[76:79], v[132:135], v[212:215], 0
	v_mfma_f32_16x16x32_bf16 v[72:75], v[160:163], v[212:215], 0
	v_mfma_f32_16x16x32_bf16 v[124:127], v[156:159], v[192:195], v[124:127]
	v_mfma_f32_16x16x32_bf16 v[120:123], v[168:171], v[192:195], v[120:123]
	v_mfma_f32_16x16x32_bf16 v[108:111], v[156:159], v[200:203], v[108:111]
	v_mfma_f32_16x16x32_bf16 v[104:107], v[168:171], v[200:203], v[104:107]
	v_mfma_f32_16x16x32_bf16 v[92:95], v[156:159], v[208:211], v[92:95]
	v_mfma_f32_16x16x32_bf16 v[88:91], v[168:171], v[208:211], v[88:91]
	v_mfma_f32_16x16x32_bf16 v[76:79], v[156:159], v[216:219], v[76:79]
	v_mfma_f32_16x16x32_bf16 v[72:75], v[168:171], v[216:219], v[72:75]
	s_setprio 0
	s_setprio 1
	v_mfma_f32_16x16x32_bf16 v[116:119], v[172:175], v[188:191], 0
	v_mfma_f32_16x16x32_bf16 v[112:115], v[180:183], v[188:191], 0
	v_mfma_f32_16x16x32_bf16 v[100:103], v[172:175], v[196:199], 0
	v_mfma_f32_16x16x32_bf16 v[96:99], v[180:183], v[196:199], 0
	v_mfma_f32_16x16x32_bf16 v[84:87], v[172:175], v[204:207], 0
	v_mfma_f32_16x16x32_bf16 v[80:83], v[180:183], v[204:207], 0
	v_mfma_f32_16x16x32_bf16 v[68:71], v[172:175], v[212:215], 0
	v_mfma_f32_16x16x32_bf16 v[64:67], v[180:183], v[212:215], 0
	v_mfma_f32_16x16x32_bf16 v[116:119], v[176:179], v[192:195], v[116:119]
	v_mfma_f32_16x16x32_bf16 v[112:115], v[184:187], v[192:195], v[112:115]
	v_mfma_f32_16x16x32_bf16 v[100:103], v[176:179], v[200:203], v[100:103]
	v_mfma_f32_16x16x32_bf16 v[96:99], v[184:187], v[200:203], v[96:99]
	v_mfma_f32_16x16x32_bf16 v[84:87], v[176:179], v[208:211], v[84:87]
	v_mfma_f32_16x16x32_bf16 v[80:83], v[184:187], v[208:211], v[80:83]
	v_mfma_f32_16x16x32_bf16 v[68:71], v[176:179], v[216:219], v[68:71]
	v_mfma_f32_16x16x32_bf16 v[64:67], v[184:187], v[216:219], v[64:67]
	s_barrier
	s_setprio 0
	s_add_i32 s8, s64, s50
	s_mov_b32 m0, s8
	ds_read_b128 v[188:191], v166 offset:16384
	ds_read_b128 v[192:195], v166 offset:17408
	ds_read_b128 v[196:199], v166 offset:18432
	global_load_lds_dwordx4 v138, s[44:45]
	s_add_i32 m0, s8, 0x2000
	ds_read_b128 v[200:203], v166 offset:19456
	global_load_lds_dwordx4 v142, s[44:45]
	s_add_u32 s44, s44, 0xb0000
	s_addc_u32 s45, s45, 0
	s_add_i32 s8, s65, s50
	s_mov_b32 m0, s8
	ds_read_b128 v[204:207], v166 offset:20480
	global_load_lds_dwordx4 v138, s[44:45]
	s_add_i32 m0, s8, 0x2000
	ds_read_b128 v[208:211], v166 offset:21504
	global_load_lds_dwordx4 v142, s[44:45]
	s_mov_b32 m0, s51
	ds_read_b128 v[212:215], v166 offset:22528
	global_load_lds_dwordx4 v136, s[46:47]
	s_mov_b32 m0, s52
	ds_read_b128 v[216:219], v166 offset:23552
	global_load_lds_dwordx4 v140, s[46:47]
	s_waitcnt vmcnt(8)
	s_waitcnt lgkmcnt(0)
	s_setprio 1
	s_barrier
	v_mfma_f32_16x16x32_bf16 v[60:63], v[132:135], v[188:191], 0
	v_mfma_f32_16x16x32_bf16 v[56:59], v[160:163], v[188:191], 0
	v_mfma_f32_16x16x32_bf16 v[44:47], v[132:135], v[196:199], 0
	v_mfma_f32_16x16x32_bf16 v[40:43], v[160:163], v[196:199], 0
	v_mfma_f32_16x16x32_bf16 v[28:31], v[132:135], v[204:207], 0
	v_mfma_f32_16x16x32_bf16 v[24:27], v[160:163], v[204:207], 0
	v_mfma_f32_16x16x32_bf16 v[12:15], v[132:135], v[212:215], 0
	v_mfma_f32_16x16x32_bf16 v[8:11], v[160:163], v[212:215], 0
	v_mfma_f32_16x16x32_bf16 v[60:63], v[156:159], v[192:195], v[60:63]
	v_mfma_f32_16x16x32_bf16 v[56:59], v[168:171], v[192:195], v[56:59]
	v_mfma_f32_16x16x32_bf16 v[44:47], v[156:159], v[200:203], v[44:47]
	v_mfma_f32_16x16x32_bf16 v[40:43], v[168:171], v[200:203], v[40:43]
	v_mfma_f32_16x16x32_bf16 v[28:31], v[156:159], v[208:211], v[28:31]
	v_mfma_f32_16x16x32_bf16 v[24:27], v[168:171], v[208:211], v[24:27]
	v_mfma_f32_16x16x32_bf16 v[12:15], v[156:159], v[216:219], v[12:15]
	v_mfma_f32_16x16x32_bf16 v[8:11], v[168:171], v[216:219], v[8:11]
	s_setprio 0
	s_setprio 1
	v_mfma_f32_16x16x32_bf16 v[52:55], v[172:175], v[188:191], 0
	v_mfma_f32_16x16x32_bf16 v[48:51], v[180:183], v[188:191], 0
	v_mfma_f32_16x16x32_bf16 v[36:39], v[172:175], v[196:199], 0
	v_mfma_f32_16x16x32_bf16 v[32:35], v[180:183], v[196:199], 0
	v_mfma_f32_16x16x32_bf16 v[20:23], v[172:175], v[204:207], 0
	v_mfma_f32_16x16x32_bf16 v[16:19], v[180:183], v[204:207], 0
	v_mfma_f32_16x16x32_bf16 v[4:7], v[172:175], v[212:215], 0
	v_mfma_f32_16x16x32_bf16 v[0:3], v[180:183], v[212:215], 0
	v_mfma_f32_16x16x32_bf16 v[52:55], v[176:179], v[192:195], v[52:55]
	v_mfma_f32_16x16x32_bf16 v[48:51], v[184:187], v[192:195], v[48:51]
	v_mfma_f32_16x16x32_bf16 v[36:39], v[176:179], v[200:203], v[36:39]
	v_mfma_f32_16x16x32_bf16 v[32:35], v[184:187], v[200:203], v[32:35]
	v_mfma_f32_16x16x32_bf16 v[20:23], v[176:179], v[208:211], v[20:23]
	v_mfma_f32_16x16x32_bf16 v[16:19], v[184:187], v[208:211], v[16:19]
	v_mfma_f32_16x16x32_bf16 v[4:7], v[176:179], v[216:219], v[4:7]
	v_mfma_f32_16x16x32_bf16 v[0:3], v[184:187], v[216:219], v[0:3]
	s_barrier
	s_setprio 0
	s_add_i32 s8, 0, 0x18000
	s_add_i32 s79, 0, 0x1c000
	ds_read_b128 v[132:135], v220 offset:32768
	ds_read_b128 v[156:159], v220 offset:33792
	ds_read_b128 v[160:163], v220 offset:34816
	ds_read_b128 v[168:171], v220 offset:35840
	ds_read_b128 v[172:175], v220 offset:49152
	ds_read_b128 v[176:179], v220 offset:50176
	ds_read_b128 v[180:183], v220 offset:51200
	ds_read_b128 v[184:187], v220 offset:52224
	s_add_u32 s44, s46, 0xb0000
	s_addc_u32 s45, s47, 0
	s_mov_b32 m0, s53
	ds_read_b128 v[188:191], v166 offset:32768
	ds_read_b128 v[192:195], v166 offset:33792
	ds_read_b128 v[196:199], v166 offset:34816
	ds_read_b128 v[200:203], v166 offset:35840
	ds_read_b128 v[204:207], v166 offset:36864
	ds_read_b128 v[208:211], v166 offset:37888
	ds_read_b128 v[212:215], v166 offset:38912
	global_load_lds_dwordx4 v136, s[44:45]
	s_mov_b32 m0, s54
	ds_read_b128 v[216:219], v166 offset:39936
	global_load_lds_dwordx4 v140, s[44:45]
	s_waitcnt vmcnt(8)
	s_waitcnt lgkmcnt(0)
	s_setprio 1
	s_barrier
	v_mfma_f32_16x16x32_bf16 v[124:127], v[132:135], v[188:191], v[124:127]
	v_mfma_f32_16x16x32_bf16 v[120:123], v[160:163], v[188:191], v[120:123]
	v_mfma_f32_16x16x32_bf16 v[108:111], v[132:135], v[196:199], v[108:111]
	v_mfma_f32_16x16x32_bf16 v[104:107], v[160:163], v[196:199], v[104:107]
	v_mfma_f32_16x16x32_bf16 v[92:95], v[132:135], v[204:207], v[92:95]
	v_mfma_f32_16x16x32_bf16 v[88:91], v[160:163], v[204:207], v[88:91]
	v_mfma_f32_16x16x32_bf16 v[76:79], v[132:135], v[212:215], v[76:79]
	v_mfma_f32_16x16x32_bf16 v[72:75], v[160:163], v[212:215], v[72:75]
	v_mfma_f32_16x16x32_bf16 v[124:127], v[156:159], v[192:195], v[124:127]
	v_mfma_f32_16x16x32_bf16 v[120:123], v[168:171], v[192:195], v[120:123]
	v_mfma_f32_16x16x32_bf16 v[108:111], v[156:159], v[200:203], v[108:111]
	v_mfma_f32_16x16x32_bf16 v[104:107], v[168:171], v[200:203], v[104:107]
	v_mfma_f32_16x16x32_bf16 v[92:95], v[156:159], v[208:211], v[92:95]
	v_mfma_f32_16x16x32_bf16 v[88:91], v[168:171], v[208:211], v[88:91]
	v_mfma_f32_16x16x32_bf16 v[76:79], v[156:159], v[216:219], v[76:79]
	v_mfma_f32_16x16x32_bf16 v[72:75], v[168:171], v[216:219], v[72:75]
	s_setprio 0
	s_setprio 1
	v_mfma_f32_16x16x32_bf16 v[116:119], v[172:175], v[188:191], v[116:119]
	v_mfma_f32_16x16x32_bf16 v[112:115], v[180:183], v[188:191], v[112:115]
	v_mfma_f32_16x16x32_bf16 v[100:103], v[172:175], v[196:199], v[100:103]
	v_mfma_f32_16x16x32_bf16 v[96:99], v[180:183], v[196:199], v[96:99]
	v_mfma_f32_16x16x32_bf16 v[84:87], v[172:175], v[204:207], v[84:87]
	v_mfma_f32_16x16x32_bf16 v[80:83], v[180:183], v[204:207], v[80:83]
	v_mfma_f32_16x16x32_bf16 v[68:71], v[172:175], v[212:215], v[68:71]
	v_mfma_f32_16x16x32_bf16 v[64:67], v[180:183], v[212:215], v[64:67]
	v_mfma_f32_16x16x32_bf16 v[116:119], v[176:179], v[192:195], v[116:119]
	v_mfma_f32_16x16x32_bf16 v[112:115], v[184:187], v[192:195], v[112:115]
	v_mfma_f32_16x16x32_bf16 v[100:103], v[176:179], v[200:203], v[100:103]
	v_mfma_f32_16x16x32_bf16 v[96:99], v[184:187], v[200:203], v[96:99]
	v_mfma_f32_16x16x32_bf16 v[84:87], v[176:179], v[208:211], v[84:87]
	v_mfma_f32_16x16x32_bf16 v[80:83], v[184:187], v[208:211], v[80:83]
	v_mfma_f32_16x16x32_bf16 v[68:71], v[176:179], v[216:219], v[68:71]
	v_mfma_f32_16x16x32_bf16 v[64:67], v[184:187], v[216:219], v[64:67]
	s_barrier
	s_setprio 0
	s_add_i32 s8, s8, s50
	s_mov_b32 m0, s8
	ds_read_b128 v[188:191], v166 offset:49152
	ds_read_b128 v[192:195], v166 offset:50176
	ds_read_b128 v[196:199], v166 offset:51200
	global_load_lds_dwordx4 v138, s[40:41]
	s_add_i32 m0, s8, 0x2000
	ds_read_b128 v[200:203], v166 offset:52224
	global_load_lds_dwordx4 v142, s[40:41]
	s_add_u32 s40, s40, 0xb0000
	s_addc_u32 s41, s41, 0
	s_add_i32 s8, s79, s50
	s_mov_b32 m0, s8
	ds_read_b128 v[204:207], v166 offset:53248
	global_load_lds_dwordx4 v138, s[40:41]
	s_add_i32 m0, s8, 0x2000
	ds_read_b128 v[208:211], v166 offset:54272
	global_load_lds_dwordx4 v142, s[40:41]
	s_mov_b32 m0, s60
	ds_read_b128 v[212:215], v166 offset:55296
	global_load_lds_dwordx4 v136, s[38:39]
	s_mov_b32 m0, s61
	ds_read_b128 v[216:219], v166 offset:56320
	global_load_lds_dwordx4 v140, s[38:39]
	s_waitcnt vmcnt(8)
	s_waitcnt lgkmcnt(0)
	s_setprio 1
	s_barrier
	v_mfma_f32_16x16x32_bf16 v[60:63], v[132:135], v[188:191], v[60:63]
	v_mfma_f32_16x16x32_bf16 v[56:59], v[160:163], v[188:191], v[56:59]
	v_mfma_f32_16x16x32_bf16 v[44:47], v[132:135], v[196:199], v[44:47]
	v_mfma_f32_16x16x32_bf16 v[40:43], v[160:163], v[196:199], v[40:43]
	v_mfma_f32_16x16x32_bf16 v[28:31], v[132:135], v[204:207], v[28:31]
	v_mfma_f32_16x16x32_bf16 v[24:27], v[160:163], v[204:207], v[24:27]
	v_mfma_f32_16x16x32_bf16 v[12:15], v[132:135], v[212:215], v[12:15]
	v_mfma_f32_16x16x32_bf16 v[8:11], v[160:163], v[212:215], v[8:11]
	v_mfma_f32_16x16x32_bf16 v[60:63], v[156:159], v[192:195], v[60:63]
	v_mfma_f32_16x16x32_bf16 v[56:59], v[168:171], v[192:195], v[56:59]
	v_mfma_f32_16x16x32_bf16 v[44:47], v[156:159], v[200:203], v[44:47]
	v_mfma_f32_16x16x32_bf16 v[40:43], v[168:171], v[200:203], v[40:43]
	v_mfma_f32_16x16x32_bf16 v[28:31], v[156:159], v[208:211], v[28:31]
	v_mfma_f32_16x16x32_bf16 v[24:27], v[168:171], v[208:211], v[24:27]
	v_mfma_f32_16x16x32_bf16 v[12:15], v[156:159], v[216:219], v[12:15]
	v_mfma_f32_16x16x32_bf16 v[8:11], v[168:171], v[216:219], v[8:11]
	s_setprio 0
	s_setprio 1
	v_mfma_f32_16x16x32_bf16 v[52:55], v[172:175], v[188:191], v[52:55]
	v_mfma_f32_16x16x32_bf16 v[48:51], v[180:183], v[188:191], v[48:51]
	v_mfma_f32_16x16x32_bf16 v[36:39], v[172:175], v[196:199], v[36:39]
	v_mfma_f32_16x16x32_bf16 v[32:35], v[180:183], v[196:199], v[32:35]
	v_mfma_f32_16x16x32_bf16 v[20:23], v[172:175], v[204:207], v[20:23]
	v_mfma_f32_16x16x32_bf16 v[16:19], v[180:183], v[204:207], v[16:19]
	v_mfma_f32_16x16x32_bf16 v[4:7], v[172:175], v[212:215], v[4:7]
	v_mfma_f32_16x16x32_bf16 v[0:3], v[180:183], v[212:215], v[0:3]
	v_mfma_f32_16x16x32_bf16 v[52:55], v[176:179], v[192:195], v[52:55]
	v_mfma_f32_16x16x32_bf16 v[48:51], v[184:187], v[192:195], v[48:51]
	v_mfma_f32_16x16x32_bf16 v[36:39], v[176:179], v[200:203], v[36:39]
	v_mfma_f32_16x16x32_bf16 v[32:35], v[184:187], v[200:203], v[32:35]
	v_mfma_f32_16x16x32_bf16 v[20:23], v[176:179], v[208:211], v[20:23]
	v_mfma_f32_16x16x32_bf16 v[16:19], v[184:187], v[208:211], v[16:19]
	v_mfma_f32_16x16x32_bf16 v[4:7], v[176:179], v[216:219], v[4:7]
	v_mfma_f32_16x16x32_bf16 v[0:3], v[184:187], v[216:219], v[0:3]
	s_barrier
	s_setprio 0
	s_add_u32 s36, s36, 0x100
	s_addc_u32 s37, s37, 0
	s_cmpk_eq_i32 s36, 0x1600
	s_cbranch_scc1 .LBB0_903
	s_branch .LBB0_897
.LBB0_896:
	ds_read_b128 v[132:135], v220
	ds_read_b128 v[156:159], v220 offset:1024
	ds_read_b128 v[160:163], v220 offset:2048
	ds_read_b128 v[168:171], v220 offset:3072
	ds_read_b128 v[172:175], v220 offset:16384
	ds_read_b128 v[176:179], v220 offset:17408
	ds_read_b128 v[180:183], v220 offset:18432
	ds_read_b128 v[184:187], v220 offset:19456
	s_add_i32 m0, s51, 0xc000
	ds_read_b128 v[188:191], v166
	ds_read_b128 v[192:195], v166 offset:1024
	ds_read_b128 v[196:199], v166 offset:2048
	ds_read_b128 v[200:203], v166 offset:3072
	ds_read_b128 v[204:207], v166 offset:4096
	ds_read_b128 v[208:211], v166 offset:5120
	ds_read_b128 v[212:215], v166 offset:6144
	global_load_lds_dwordx4 v148, s[100:101]
	s_add_i32 m0, s51, 0xe000
	ds_read_b128 v[216:219], v166 offset:7168
	global_load_lds_dwordx4 v150, s[100:101]
	s_waitcnt vmcnt(8)
	s_waitcnt lgkmcnt(0)
	s_setprio 1
	s_barrier
	v_mfma_f32_16x16x32_bf16 v[124:127], v[132:135], v[188:191], v[124:127]
	v_mfma_f32_16x16x32_bf16 v[120:123], v[160:163], v[188:191], v[120:123]
	v_mfma_f32_16x16x32_bf16 v[108:111], v[132:135], v[196:199], v[108:111]
	v_mfma_f32_16x16x32_bf16 v[104:107], v[160:163], v[196:199], v[104:107]
	v_mfma_f32_16x16x32_bf16 v[92:95], v[132:135], v[204:207], v[92:95]
	v_mfma_f32_16x16x32_bf16 v[88:91], v[160:163], v[204:207], v[88:91]
	v_mfma_f32_16x16x32_bf16 v[76:79], v[132:135], v[212:215], v[76:79]
	v_mfma_f32_16x16x32_bf16 v[72:75], v[160:163], v[212:215], v[72:75]
	v_mfma_f32_16x16x32_bf16 v[124:127], v[156:159], v[192:195], v[124:127]
	v_mfma_f32_16x16x32_bf16 v[120:123], v[168:171], v[192:195], v[120:123]
	v_mfma_f32_16x16x32_bf16 v[108:111], v[156:159], v[200:203], v[108:111]
	v_mfma_f32_16x16x32_bf16 v[104:107], v[168:171], v[200:203], v[104:107]
	v_mfma_f32_16x16x32_bf16 v[92:95], v[156:159], v[208:211], v[92:95]
	v_mfma_f32_16x16x32_bf16 v[88:91], v[168:171], v[208:211], v[88:91]
	v_mfma_f32_16x16x32_bf16 v[76:79], v[156:159], v[216:219], v[76:79]
	v_mfma_f32_16x16x32_bf16 v[72:75], v[168:171], v[216:219], v[72:75]
	s_setprio 0
	s_setprio 1
	v_mfma_f32_16x16x32_bf16 v[116:119], v[172:175], v[188:191], v[116:119]
	v_mfma_f32_16x16x32_bf16 v[112:115], v[180:183], v[188:191], v[112:115]
	v_mfma_f32_16x16x32_bf16 v[100:103], v[172:175], v[196:199], v[100:103]
	v_mfma_f32_16x16x32_bf16 v[96:99], v[180:183], v[196:199], v[96:99]
	v_mfma_f32_16x16x32_bf16 v[84:87], v[172:175], v[204:207], v[84:87]
	v_mfma_f32_16x16x32_bf16 v[80:83], v[180:183], v[204:207], v[80:83]
	v_mfma_f32_16x16x32_bf16 v[68:71], v[172:175], v[212:215], v[68:71]
	v_mfma_f32_16x16x32_bf16 v[64:67], v[180:183], v[212:215], v[64:67]
	v_mfma_f32_16x16x32_bf16 v[116:119], v[176:179], v[192:195], v[116:119]
	v_mfma_f32_16x16x32_bf16 v[112:115], v[184:187], v[192:195], v[112:115]
	v_mfma_f32_16x16x32_bf16 v[100:103], v[176:179], v[200:203], v[100:103]
	v_mfma_f32_16x16x32_bf16 v[96:99], v[184:187], v[200:203], v[96:99]
	v_mfma_f32_16x16x32_bf16 v[84:87], v[176:179], v[208:211], v[84:87]
	v_mfma_f32_16x16x32_bf16 v[80:83], v[184:187], v[208:211], v[80:83]
	v_mfma_f32_16x16x32_bf16 v[68:71], v[176:179], v[216:219], v[68:71]
	v_mfma_f32_16x16x32_bf16 v[64:67], v[184:187], v[216:219], v[64:67]
	s_barrier
	s_setprio 0
	s_add_i32 s8, s64, s50
	s_mov_b32 m0, s8
	ds_read_b128 v[188:191], v166 offset:16384
	ds_read_b128 v[192:195], v166 offset:17408
	ds_read_b128 v[196:199], v166 offset:18432
	global_load_lds_dwordx4 v138, s[44:45]
	s_add_i32 m0, s8, 0x2000
	ds_read_b128 v[200:203], v166 offset:19456
	global_load_lds_dwordx4 v142, s[44:45]
	s_add_u32 s44, s44, 0xb0000
	s_addc_u32 s45, s45, 0
	s_add_i32 s8, s65, s50
	s_mov_b32 m0, s8
	ds_read_b128 v[204:207], v166 offset:20480
	global_load_lds_dwordx4 v138, s[44:45]
	s_add_i32 m0, s8, 0x2000
	ds_read_b128 v[208:211], v166 offset:21504
	global_load_lds_dwordx4 v142, s[44:45]
	s_mov_b32 m0, s51
	ds_read_b128 v[212:215], v166 offset:22528
	global_load_lds_dwordx4 v136, s[46:47]
	s_mov_b32 m0, s52
	ds_read_b128 v[216:219], v166 offset:23552
	global_load_lds_dwordx4 v140, s[46:47]
	s_waitcnt vmcnt(8)
	s_waitcnt lgkmcnt(0)
	s_setprio 1
	s_barrier
	v_mfma_f32_16x16x32_bf16 v[60:63], v[132:135], v[188:191], v[60:63]
	v_mfma_f32_16x16x32_bf16 v[56:59], v[160:163], v[188:191], v[56:59]
	v_mfma_f32_16x16x32_bf16 v[44:47], v[132:135], v[196:199], v[44:47]
	v_mfma_f32_16x16x32_bf16 v[40:43], v[160:163], v[196:199], v[40:43]
	v_mfma_f32_16x16x32_bf16 v[28:31], v[132:135], v[204:207], v[28:31]
	v_mfma_f32_16x16x32_bf16 v[24:27], v[160:163], v[204:207], v[24:27]
	v_mfma_f32_16x16x32_bf16 v[12:15], v[132:135], v[212:215], v[12:15]
	v_mfma_f32_16x16x32_bf16 v[8:11], v[160:163], v[212:215], v[8:11]
	v_mfma_f32_16x16x32_bf16 v[60:63], v[156:159], v[192:195], v[60:63]
	v_mfma_f32_16x16x32_bf16 v[56:59], v[168:171], v[192:195], v[56:59]
	v_mfma_f32_16x16x32_bf16 v[44:47], v[156:159], v[200:203], v[44:47]
	v_mfma_f32_16x16x32_bf16 v[40:43], v[168:171], v[200:203], v[40:43]
	v_mfma_f32_16x16x32_bf16 v[28:31], v[156:159], v[208:211], v[28:31]
	v_mfma_f32_16x16x32_bf16 v[24:27], v[168:171], v[208:211], v[24:27]
	v_mfma_f32_16x16x32_bf16 v[12:15], v[156:159], v[216:219], v[12:15]
	v_mfma_f32_16x16x32_bf16 v[8:11], v[168:171], v[216:219], v[8:11]
	s_setprio 0
	s_setprio 1
	v_mfma_f32_16x16x32_bf16 v[52:55], v[172:175], v[188:191], v[52:55]
	v_mfma_f32_16x16x32_bf16 v[48:51], v[180:183], v[188:191], v[48:51]
	v_mfma_f32_16x16x32_bf16 v[36:39], v[172:175], v[196:199], v[36:39]
	v_mfma_f32_16x16x32_bf16 v[32:35], v[180:183], v[196:199], v[32:35]
	v_mfma_f32_16x16x32_bf16 v[20:23], v[172:175], v[204:207], v[20:23]
	v_mfma_f32_16x16x32_bf16 v[16:19], v[180:183], v[204:207], v[16:19]
	v_mfma_f32_16x16x32_bf16 v[4:7], v[172:175], v[212:215], v[4:7]
	v_mfma_f32_16x16x32_bf16 v[0:3], v[180:183], v[212:215], v[0:3]
	v_mfma_f32_16x16x32_bf16 v[52:55], v[176:179], v[192:195], v[52:55]
	v_mfma_f32_16x16x32_bf16 v[48:51], v[184:187], v[192:195], v[48:51]
	v_mfma_f32_16x16x32_bf16 v[36:39], v[176:179], v[200:203], v[36:39]
	v_mfma_f32_16x16x32_bf16 v[32:35], v[184:187], v[200:203], v[32:35]
	v_mfma_f32_16x16x32_bf16 v[20:23], v[176:179], v[208:211], v[20:23]
	v_mfma_f32_16x16x32_bf16 v[16:19], v[184:187], v[208:211], v[16:19]
	v_mfma_f32_16x16x32_bf16 v[4:7], v[176:179], v[216:219], v[4:7]
	v_mfma_f32_16x16x32_bf16 v[0:3], v[184:187], v[216:219], v[0:3]
	s_barrier
	s_setprio 0
	s_add_i32 s8, 0, 0x18000
	s_add_i32 s79, 0, 0x1c000
	ds_read_b128 v[132:135], v220 offset:32768
	ds_read_b128 v[156:159], v220 offset:33792
	ds_read_b128 v[160:163], v220 offset:34816
	ds_read_b128 v[168:171], v220 offset:35840
	ds_read_b128 v[172:175], v220 offset:49152
	ds_read_b128 v[176:179], v220 offset:50176
	ds_read_b128 v[180:183], v220 offset:51200
	ds_read_b128 v[184:187], v220 offset:52224
	s_add_u32 s44, s46, 0xb0000
	s_addc_u32 s45, s47, 0
	s_mov_b32 m0, s53
	ds_read_b128 v[188:191], v166 offset:32768
	ds_read_b128 v[192:195], v166 offset:33792
	ds_read_b128 v[196:199], v166 offset:34816
	ds_read_b128 v[200:203], v166 offset:35840
	ds_read_b128 v[204:207], v166 offset:36864
	ds_read_b128 v[208:211], v166 offset:37888
	ds_read_b128 v[212:215], v166 offset:38912
	global_load_lds_dwordx4 v136, s[44:45]
	s_mov_b32 m0, s54
	ds_read_b128 v[216:219], v166 offset:39936
	global_load_lds_dwordx4 v140, s[44:45]
	s_waitcnt vmcnt(8)
	s_waitcnt lgkmcnt(0)
	s_setprio 1
	s_barrier
	v_mfma_f32_16x16x32_bf16 v[124:127], v[132:135], v[188:191], v[124:127]
	v_mfma_f32_16x16x32_bf16 v[120:123], v[160:163], v[188:191], v[120:123]
	v_mfma_f32_16x16x32_bf16 v[108:111], v[132:135], v[196:199], v[108:111]
	v_mfma_f32_16x16x32_bf16 v[104:107], v[160:163], v[196:199], v[104:107]
	v_mfma_f32_16x16x32_bf16 v[92:95], v[132:135], v[204:207], v[92:95]
	v_mfma_f32_16x16x32_bf16 v[88:91], v[160:163], v[204:207], v[88:91]
	v_mfma_f32_16x16x32_bf16 v[76:79], v[132:135], v[212:215], v[76:79]
	v_mfma_f32_16x16x32_bf16 v[72:75], v[160:163], v[212:215], v[72:75]
	v_mfma_f32_16x16x32_bf16 v[124:127], v[156:159], v[192:195], v[124:127]
	v_mfma_f32_16x16x32_bf16 v[120:123], v[168:171], v[192:195], v[120:123]
	v_mfma_f32_16x16x32_bf16 v[108:111], v[156:159], v[200:203], v[108:111]
	v_mfma_f32_16x16x32_bf16 v[104:107], v[168:171], v[200:203], v[104:107]
	v_mfma_f32_16x16x32_bf16 v[92:95], v[156:159], v[208:211], v[92:95]
	v_mfma_f32_16x16x32_bf16 v[88:91], v[168:171], v[208:211], v[88:91]
	v_mfma_f32_16x16x32_bf16 v[76:79], v[156:159], v[216:219], v[76:79]
	v_mfma_f32_16x16x32_bf16 v[72:75], v[168:171], v[216:219], v[72:75]
	s_setprio 0
	s_setprio 1
	v_mfma_f32_16x16x32_bf16 v[116:119], v[172:175], v[188:191], v[116:119]
	v_mfma_f32_16x16x32_bf16 v[112:115], v[180:183], v[188:191], v[112:115]
	v_mfma_f32_16x16x32_bf16 v[100:103], v[172:175], v[196:199], v[100:103]
	v_mfma_f32_16x16x32_bf16 v[96:99], v[180:183], v[196:199], v[96:99]
	v_mfma_f32_16x16x32_bf16 v[84:87], v[172:175], v[204:207], v[84:87]
	v_mfma_f32_16x16x32_bf16 v[80:83], v[180:183], v[204:207], v[80:83]
	v_mfma_f32_16x16x32_bf16 v[68:71], v[172:175], v[212:215], v[68:71]
	v_mfma_f32_16x16x32_bf16 v[64:67], v[180:183], v[212:215], v[64:67]
	v_mfma_f32_16x16x32_bf16 v[116:119], v[176:179], v[192:195], v[116:119]
	v_mfma_f32_16x16x32_bf16 v[112:115], v[184:187], v[192:195], v[112:115]
	v_mfma_f32_16x16x32_bf16 v[100:103], v[176:179], v[200:203], v[100:103]
	v_mfma_f32_16x16x32_bf16 v[96:99], v[184:187], v[200:203], v[96:99]
	v_mfma_f32_16x16x32_bf16 v[84:87], v[176:179], v[208:211], v[84:87]
	v_mfma_f32_16x16x32_bf16 v[80:83], v[184:187], v[208:211], v[80:83]
	v_mfma_f32_16x16x32_bf16 v[68:71], v[176:179], v[216:219], v[68:71]
	v_mfma_f32_16x16x32_bf16 v[64:67], v[184:187], v[216:219], v[64:67]
	s_barrier
	s_setprio 0
	s_add_i32 s8, s8, s50
	s_mov_b32 m0, s8
	ds_read_b128 v[188:191], v166 offset:49152
	ds_read_b128 v[192:195], v166 offset:50176
	ds_read_b128 v[196:199], v166 offset:51200
	global_load_lds_dwordx4 v138, s[40:41]
	s_add_i32 m0, s8, 0x2000
	ds_read_b128 v[200:203], v166 offset:52224
	global_load_lds_dwordx4 v142, s[40:41]
	s_add_u32 s40, s40, 0xb0000
	s_addc_u32 s41, s41, 0
	s_add_i32 s8, s79, s50
	s_mov_b32 m0, s8
	ds_read_b128 v[204:207], v166 offset:53248
	global_load_lds_dwordx4 v138, s[40:41]
	s_add_i32 m0, s8, 0x2000
	ds_read_b128 v[208:211], v166 offset:54272
	global_load_lds_dwordx4 v142, s[40:41]
	s_mov_b32 m0, s60
	ds_read_b128 v[212:215], v166 offset:55296
	global_load_lds_dwordx4 v136, s[38:39]
	s_mov_b32 m0, s61
	ds_read_b128 v[216:219], v166 offset:56320
	global_load_lds_dwordx4 v140, s[38:39]
	s_waitcnt vmcnt(8)
	s_waitcnt lgkmcnt(0)
	s_setprio 1
	s_barrier
	v_mfma_f32_16x16x32_bf16 v[60:63], v[132:135], v[188:191], v[60:63]
	v_mfma_f32_16x16x32_bf16 v[56:59], v[160:163], v[188:191], v[56:59]
	v_mfma_f32_16x16x32_bf16 v[44:47], v[132:135], v[196:199], v[44:47]
	v_mfma_f32_16x16x32_bf16 v[40:43], v[160:163], v[196:199], v[40:43]
	v_mfma_f32_16x16x32_bf16 v[28:31], v[132:135], v[204:207], v[28:31]
	v_mfma_f32_16x16x32_bf16 v[24:27], v[160:163], v[204:207], v[24:27]
	v_mfma_f32_16x16x32_bf16 v[12:15], v[132:135], v[212:215], v[12:15]
	v_mfma_f32_16x16x32_bf16 v[8:11], v[160:163], v[212:215], v[8:11]
	v_mfma_f32_16x16x32_bf16 v[60:63], v[156:159], v[192:195], v[60:63]
	v_mfma_f32_16x16x32_bf16 v[56:59], v[168:171], v[192:195], v[56:59]
	v_mfma_f32_16x16x32_bf16 v[44:47], v[156:159], v[200:203], v[44:47]
	v_mfma_f32_16x16x32_bf16 v[40:43], v[168:171], v[200:203], v[40:43]
	v_mfma_f32_16x16x32_bf16 v[28:31], v[156:159], v[208:211], v[28:31]
	v_mfma_f32_16x16x32_bf16 v[24:27], v[168:171], v[208:211], v[24:27]
	v_mfma_f32_16x16x32_bf16 v[12:15], v[156:159], v[216:219], v[12:15]
	v_mfma_f32_16x16x32_bf16 v[8:11], v[168:171], v[216:219], v[8:11]
	s_setprio 0
	s_setprio 1
	v_mfma_f32_16x16x32_bf16 v[52:55], v[172:175], v[188:191], v[52:55]
	v_mfma_f32_16x16x32_bf16 v[48:51], v[180:183], v[188:191], v[48:51]
	v_mfma_f32_16x16x32_bf16 v[36:39], v[172:175], v[196:199], v[36:39]
	v_mfma_f32_16x16x32_bf16 v[32:35], v[180:183], v[196:199], v[32:35]
	v_mfma_f32_16x16x32_bf16 v[20:23], v[172:175], v[204:207], v[20:23]
	v_mfma_f32_16x16x32_bf16 v[16:19], v[180:183], v[204:207], v[16:19]
	v_mfma_f32_16x16x32_bf16 v[4:7], v[172:175], v[212:215], v[4:7]
	v_mfma_f32_16x16x32_bf16 v[0:3], v[180:183], v[212:215], v[0:3]
	v_mfma_f32_16x16x32_bf16 v[52:55], v[176:179], v[192:195], v[52:55]
	v_mfma_f32_16x16x32_bf16 v[48:51], v[184:187], v[192:195], v[48:51]
	v_mfma_f32_16x16x32_bf16 v[36:39], v[176:179], v[200:203], v[36:39]
	v_mfma_f32_16x16x32_bf16 v[32:35], v[184:187], v[200:203], v[32:35]
	v_mfma_f32_16x16x32_bf16 v[20:23], v[176:179], v[208:211], v[20:23]
	v_mfma_f32_16x16x32_bf16 v[16:19], v[184:187], v[208:211], v[16:19]
	v_mfma_f32_16x16x32_bf16 v[4:7], v[176:179], v[216:219], v[4:7]
	v_mfma_f32_16x16x32_bf16 v[0:3], v[184:187], v[216:219], v[0:3]
	s_barrier
	s_setprio 0
	s_add_u32 s36, s36, 0x100
	s_addc_u32 s37, s37, 0
	s_cmpk_eq_i32 s36, 0x1600
	s_cbranch_scc1 .LBB0_903

.LBB0_1017:
	s_add_u32 s65, s54, s6
	s_addc_u32 s66, s55, s7
	s_add_u32 s67, s56, s8
	s_addc_u32 s68, s57, s9
	s_ashr_i32 s19, s18, 31
	s_lshl_b64 s[6:7], s[18:19], 19
	s_add_u32 s20, s34, s6
	s_addc_u32 s21, s35, s7
	s_and_b64 s[8:9], s[0:1], exec
	s_cselect_b32 s19, s21, s29
	s_cselect_b32 s69, s20, s28
	s_ashr_i32 s17, s16, 31
	s_lshl_b64 s[8:9], s[16:17], 19
	s_add_u32 s22, s48, s8
	s_addc_u32 s23, s49, s9
	s_and_b64 s[30:31], s[0:1], exec
	s_cselect_b32 s17, s23, s27
	s_cselect_b32 s70, s22, s26
	s_add_u32 s30, s69, 0x80
	s_addc_u32 s31, s19, 0
	s_add_u32 s36, s70, 0x80
	s_addc_u32 s37, s17, 0
	v_lshl_add_u64 v[128:129], s[28:29], 0, v[196:197]
	v_lshl_add_u64 v[130:131], s[28:29], 0, v[198:199]
	s_mov_b32 s71, 0
	s_mov_b64 s[38:39], 0
	v_add_u32_e32 v216, 0x10000, v220
	s_add_u32 s46, s28, s38
	s_addc_u32 s47, s29, s39
	s_mov_b64 s[100:101], s[46:47]
	s_add_u32 s73, s26, s38
	s_addc_u32 s72, s27, s39
	s_add_u32 s40, s46, 0x180
	s_addc_u32 s41, s47, 0
	s_add_u32 s42, s73, 0x180
	s_addc_u32 s43, s72, 0
	s_add_u32 s46, s46, 0x100
	s_addc_u32 s47, s47, 0
	s_add_u32 s44, s73, 0x100
	s_addc_u32 s45, s72, 0
	s_cmpk_eq_i32 s38, 0x700
	s_cselect_b32 s40, s30, s40
	s_cselect_b32 s41, s31, s41
	s_cselect_b32 s42, s36, s42
	s_cselect_b32 s43, s37, s43
	s_cselect_b32 s46, s69, s46
	s_cselect_b32 s47, s19, s47
	s_cselect_b32 s44, s70, s44
	s_cselect_b32 s45, s17, s45
	ds_read_b128 v[132:135], v216
	ds_read_b128 v[136:139], v216 offset:1024
	ds_read_b128 v[140:143], v216 offset:2048
	ds_read_b128 v[144:147], v216 offset:3072
	ds_read_b128 v[148:151], v216 offset:16384
	ds_read_b128 v[152:155], v216 offset:17408
	ds_read_b128 v[156:159], v216 offset:18432
	ds_read_b128 v[160:163], v216 offset:19456
	s_add_i32 m0, s25, 0xc000
	ds_read_b128 v[164:167], v221
	ds_read_b128 v[168:171], v221 offset:1024
	ds_read_b128 v[172:175], v221 offset:2048
	ds_read_b128 v[176:179], v221 offset:3072
	ds_read_b128 v[180:183], v221 offset:4096
	ds_read_b128 v[204:207], v221 offset:5120
	ds_read_b128 v[208:211], v221 offset:6144
	global_load_lds_dwordx4 v196, s[100:101]
	s_add_i32 m0, s25, 0xe000
	ds_read_b128 v[212:215], v221 offset:7168
	global_load_lds_dwordx4 v198, s[100:101]
	s_waitcnt vmcnt(8)
	s_waitcnt lgkmcnt(0)
	s_setprio 1
	s_barrier
	v_mfma_f32_16x16x32_bf16 v[124:127], v[132:135], v[164:167], 0
	v_mfma_f32_16x16x32_bf16 v[120:123], v[140:143], v[164:167], 0
	v_mfma_f32_16x16x32_bf16 v[108:111], v[132:135], v[172:175], 0
	v_mfma_f32_16x16x32_bf16 v[104:107], v[140:143], v[172:175], 0
	v_mfma_f32_16x16x32_bf16 v[92:95], v[132:135], v[180:183], 0
	v_mfma_f32_16x16x32_bf16 v[88:91], v[140:143], v[180:183], 0
	v_mfma_f32_16x16x32_bf16 v[76:79], v[132:135], v[208:211], 0
	v_mfma_f32_16x16x32_bf16 v[72:75], v[140:143], v[208:211], 0
	v_mfma_f32_16x16x32_bf16 v[124:127], v[136:139], v[168:171], v[124:127]
	v_mfma_f32_16x16x32_bf16 v[120:123], v[144:147], v[168:171], v[120:123]
	v_mfma_f32_16x16x32_bf16 v[108:111], v[136:139], v[176:179], v[108:111]
	v_mfma_f32_16x16x32_bf16 v[104:107], v[144:147], v[176:179], v[104:107]
	v_mfma_f32_16x16x32_bf16 v[92:95], v[136:139], v[204:207], v[92:95]
	v_mfma_f32_16x16x32_bf16 v[88:91], v[144:147], v[204:207], v[88:91]
	v_mfma_f32_16x16x32_bf16 v[76:79], v[136:139], v[212:215], v[76:79]
	v_mfma_f32_16x16x32_bf16 v[72:75], v[144:147], v[212:215], v[72:75]
	s_setprio 0
	s_setprio 1
	v_mfma_f32_16x16x32_bf16 v[116:119], v[148:151], v[164:167], 0
	v_mfma_f32_16x16x32_bf16 v[112:115], v[156:159], v[164:167], 0
	v_mfma_f32_16x16x32_bf16 v[100:103], v[148:151], v[172:175], 0
	v_mfma_f32_16x16x32_bf16 v[96:99], v[156:159], v[172:175], 0
	v_mfma_f32_16x16x32_bf16 v[84:87], v[148:151], v[180:183], 0
	v_mfma_f32_16x16x32_bf16 v[80:83], v[156:159], v[180:183], 0
	v_mfma_f32_16x16x32_bf16 v[68:71], v[148:151], v[208:211], 0
	v_mfma_f32_16x16x32_bf16 v[64:67], v[156:159], v[208:211], 0
	v_mfma_f32_16x16x32_bf16 v[116:119], v[152:155], v[168:171], v[116:119]
	v_mfma_f32_16x16x32_bf16 v[112:115], v[160:163], v[168:171], v[112:115]
	v_mfma_f32_16x16x32_bf16 v[100:103], v[152:155], v[176:179], v[100:103]
	v_mfma_f32_16x16x32_bf16 v[96:99], v[160:163], v[176:179], v[96:99]
	v_mfma_f32_16x16x32_bf16 v[84:87], v[152:155], v[204:207], v[84:87]
	v_mfma_f32_16x16x32_bf16 v[80:83], v[160:163], v[204:207], v[80:83]
	v_mfma_f32_16x16x32_bf16 v[68:71], v[152:155], v[212:215], v[68:71]
	v_mfma_f32_16x16x32_bf16 v[64:67], v[160:163], v[212:215], v[64:67]
	s_barrier
	s_setprio 0
	s_add_i32 s10, s61, s50
	s_mov_b32 m0, s10
	ds_read_b128 v[164:167], v221 offset:16384
	ds_read_b128 v[168:171], v221 offset:17408
	ds_read_b128 v[172:175], v221 offset:18432
	global_load_lds_dwordx4 v186, s[44:45]
	s_add_i32 m0, s10, 0x2000
	ds_read_b128 v[176:179], v221 offset:19456
	global_load_lds_dwordx4 v190, s[44:45]
	s_add_u32 s44, s44, 0x40000
	s_addc_u32 s45, s45, 0
	s_add_i32 s10, s62, s50
	s_mov_b32 m0, s10
	ds_read_b128 v[180:183], v221 offset:20480
	global_load_lds_dwordx4 v186, s[44:45]
	s_add_i32 m0, s10, 0x2000
	ds_read_b128 v[204:207], v221 offset:21504
	global_load_lds_dwordx4 v190, s[44:45]
	s_mov_b32 m0, s25
	ds_read_b128 v[208:211], v221 offset:22528
	global_load_lds_dwordx4 v184, s[46:47]
	s_mov_b32 m0, s51
	ds_read_b128 v[212:215], v221 offset:23552
	global_load_lds_dwordx4 v188, s[46:47]
	s_waitcnt vmcnt(8)
	s_waitcnt lgkmcnt(0)
	s_setprio 1
	s_barrier
	v_mfma_f32_16x16x32_bf16 v[60:63], v[132:135], v[164:167], 0
	v_mfma_f32_16x16x32_bf16 v[56:59], v[140:143], v[164:167], 0
	v_mfma_f32_16x16x32_bf16 v[44:47], v[132:135], v[172:175], 0
	v_mfma_f32_16x16x32_bf16 v[40:43], v[140:143], v[172:175], 0
	v_mfma_f32_16x16x32_bf16 v[28:31], v[132:135], v[180:183], 0
	v_mfma_f32_16x16x32_bf16 v[24:27], v[140:143], v[180:183], 0
	v_mfma_f32_16x16x32_bf16 v[12:15], v[132:135], v[208:211], 0
	v_mfma_f32_16x16x32_bf16 v[8:11], v[140:143], v[208:211], 0
	v_mfma_f32_16x16x32_bf16 v[60:63], v[136:139], v[168:171], v[60:63]
	v_mfma_f32_16x16x32_bf16 v[56:59], v[144:147], v[168:171], v[56:59]
	v_mfma_f32_16x16x32_bf16 v[44:47], v[136:139], v[176:179], v[44:47]
	v_mfma_f32_16x16x32_bf16 v[40:43], v[144:147], v[176:179], v[40:43]
	v_mfma_f32_16x16x32_bf16 v[28:31], v[136:139], v[204:207], v[28:31]
	v_mfma_f32_16x16x32_bf16 v[24:27], v[144:147], v[204:207], v[24:27]
	v_mfma_f32_16x16x32_bf16 v[12:15], v[136:139], v[212:215], v[12:15]
	v_mfma_f32_16x16x32_bf16 v[8:11], v[144:147], v[212:215], v[8:11]
	s_setprio 0
	s_setprio 1
	v_mfma_f32_16x16x32_bf16 v[52:55], v[148:151], v[164:167], 0
	v_mfma_f32_16x16x32_bf16 v[48:51], v[156:159], v[164:167], 0
	v_mfma_f32_16x16x32_bf16 v[36:39], v[148:151], v[172:175], 0
	v_mfma_f32_16x16x32_bf16 v[32:35], v[156:159], v[172:175], 0
	v_mfma_f32_16x16x32_bf16 v[20:23], v[148:151], v[180:183], 0
	v_mfma_f32_16x16x32_bf16 v[16:19], v[156:159], v[180:183], 0
	v_mfma_f32_16x16x32_bf16 v[4:7], v[148:151], v[208:211], 0
	v_mfma_f32_16x16x32_bf16 v[0:3], v[156:159], v[208:211], 0
	v_mfma_f32_16x16x32_bf16 v[52:55], v[152:155], v[168:171], v[52:55]
	v_mfma_f32_16x16x32_bf16 v[48:51], v[160:163], v[168:171], v[48:51]
	v_mfma_f32_16x16x32_bf16 v[36:39], v[152:155], v[176:179], v[36:39]
	v_mfma_f32_16x16x32_bf16 v[32:35], v[160:163], v[176:179], v[32:35]
	v_mfma_f32_16x16x32_bf16 v[20:23], v[152:155], v[204:207], v[20:23]
	v_mfma_f32_16x16x32_bf16 v[16:19], v[160:163], v[204:207], v[16:19]
	v_mfma_f32_16x16x32_bf16 v[4:7], v[152:155], v[212:215], v[4:7]
	v_mfma_f32_16x16x32_bf16 v[0:3], v[160:163], v[212:215], v[0:3]
	s_barrier
	s_setprio 0
	s_add_i32 s10, 0, 0x18000
	s_add_i32 s72, 0, 0x1c000
	ds_read_b128 v[132:135], v216 offset:32768
	ds_read_b128 v[136:139], v216 offset:33792
	ds_read_b128 v[140:143], v216 offset:34816
	ds_read_b128 v[144:147], v216 offset:35840
	ds_read_b128 v[148:151], v216 offset:49152
	ds_read_b128 v[152:155], v216 offset:50176
	ds_read_b128 v[156:159], v216 offset:51200
	ds_read_b128 v[160:163], v216 offset:52224
	s_add_u32 s44, s46, 0x40000
	s_addc_u32 s45, s47, 0
	s_mov_b32 m0, s52
	ds_read_b128 v[164:167], v221 offset:32768
	ds_read_b128 v[168:171], v221 offset:33792
	ds_read_b128 v[172:175], v221 offset:34816
	ds_read_b128 v[176:179], v221 offset:35840
	ds_read_b128 v[180:183], v221 offset:36864
	ds_read_b128 v[204:207], v221 offset:37888
	ds_read_b128 v[208:211], v221 offset:38912
	global_load_lds_dwordx4 v184, s[44:45]
	s_mov_b32 m0, s53
	ds_read_b128 v[212:215], v221 offset:39936
	global_load_lds_dwordx4 v188, s[44:45]
	s_waitcnt vmcnt(8)
	s_waitcnt lgkmcnt(0)
	s_setprio 1
	s_barrier
	v_mfma_f32_16x16x32_bf16 v[124:127], v[132:135], v[164:167], v[124:127]
	v_mfma_f32_16x16x32_bf16 v[120:123], v[140:143], v[164:167], v[120:123]
	v_mfma_f32_16x16x32_bf16 v[108:111], v[132:135], v[172:175], v[108:111]
	v_mfma_f32_16x16x32_bf16 v[104:107], v[140:143], v[172:175], v[104:107]
	v_mfma_f32_16x16x32_bf16 v[92:95], v[132:135], v[180:183], v[92:95]
	v_mfma_f32_16x16x32_bf16 v[88:91], v[140:143], v[180:183], v[88:91]
	v_mfma_f32_16x16x32_bf16 v[76:79], v[132:135], v[208:211], v[76:79]
	v_mfma_f32_16x16x32_bf16 v[72:75], v[140:143], v[208:211], v[72:75]
	v_mfma_f32_16x16x32_bf16 v[124:127], v[136:139], v[168:171], v[124:127]
	v_mfma_f32_16x16x32_bf16 v[120:123], v[144:147], v[168:171], v[120:123]
	v_mfma_f32_16x16x32_bf16 v[108:111], v[136:139], v[176:179], v[108:111]
	v_mfma_f32_16x16x32_bf16 v[104:107], v[144:147], v[176:179], v[104:107]
	v_mfma_f32_16x16x32_bf16 v[92:95], v[136:139], v[204:207], v[92:95]
	v_mfma_f32_16x16x32_bf16 v[88:91], v[144:147], v[204:207], v[88:91]
	v_mfma_f32_16x16x32_bf16 v[76:79], v[136:139], v[212:215], v[76:79]
	v_mfma_f32_16x16x32_bf16 v[72:75], v[144:147], v[212:215], v[72:75]
	s_setprio 0
	s_setprio 1
	v_mfma_f32_16x16x32_bf16 v[116:119], v[148:151], v[164:167], v[116:119]
	v_mfma_f32_16x16x32_bf16 v[112:115], v[156:159], v[164:167], v[112:115]
	v_mfma_f32_16x16x32_bf16 v[100:103], v[148:151], v[172:175], v[100:103]
	v_mfma_f32_16x16x32_bf16 v[96:99], v[156:159], v[172:175], v[96:99]
	v_mfma_f32_16x16x32_bf16 v[84:87], v[148:151], v[180:183], v[84:87]
	v_mfma_f32_16x16x32_bf16 v[80:83], v[156:159], v[180:183], v[80:83]
	v_mfma_f32_16x16x32_bf16 v[68:71], v[148:151], v[208:211], v[68:71]
	v_mfma_f32_16x16x32_bf16 v[64:67], v[156:159], v[208:211], v[64:67]
	v_mfma_f32_16x16x32_bf16 v[116:119], v[152:155], v[168:171], v[116:119]
	v_mfma_f32_16x16x32_bf16 v[112:115], v[160:163], v[168:171], v[112:115]
	v_mfma_f32_16x16x32_bf16 v[100:103], v[152:155], v[176:179], v[100:103]
	v_mfma_f32_16x16x32_bf16 v[96:99], v[160:163], v[176:179], v[96:99]
	v_mfma_f32_16x16x32_bf16 v[84:87], v[152:155], v[204:207], v[84:87]
	v_mfma_f32_16x16x32_bf16 v[80:83], v[160:163], v[204:207], v[80:83]
	v_mfma_f32_16x16x32_bf16 v[68:71], v[152:155], v[212:215], v[68:71]
	v_mfma_f32_16x16x32_bf16 v[64:67], v[160:163], v[212:215], v[64:67]
	s_barrier
	s_setprio 0
	s_add_i32 s10, s10, s50
	s_mov_b32 m0, s10
	ds_read_b128 v[164:167], v221 offset:49152
	ds_read_b128 v[168:171], v221 offset:50176
	ds_read_b128 v[172:175], v221 offset:51200
	global_load_lds_dwordx4 v186, s[42:43]
	s_add_i32 m0, s10, 0x2000
	ds_read_b128 v[176:179], v221 offset:52224
	global_load_lds_dwordx4 v190, s[42:43]
	s_add_u32 s42, s42, 0x40000
	s_addc_u32 s43, s43, 0
	s_add_i32 s10, s72, s50
	s_mov_b32 m0, s10
	ds_read_b128 v[180:183], v221 offset:53248
	global_load_lds_dwordx4 v186, s[42:43]
	s_add_i32 m0, s10, 0x2000
	ds_read_b128 v[204:207], v221 offset:54272
	global_load_lds_dwordx4 v190, s[42:43]
	s_mov_b32 m0, s58
	ds_read_b128 v[208:211], v221 offset:55296
	global_load_lds_dwordx4 v184, s[40:41]
	s_mov_b32 m0, s59
	ds_read_b128 v[212:215], v221 offset:56320
	global_load_lds_dwordx4 v188, s[40:41]
	s_waitcnt vmcnt(8)
	s_waitcnt lgkmcnt(0)
	s_setprio 1
	s_barrier
	v_mfma_f32_16x16x32_bf16 v[60:63], v[132:135], v[164:167], v[60:63]
	v_mfma_f32_16x16x32_bf16 v[56:59], v[140:143], v[164:167], v[56:59]
	v_mfma_f32_16x16x32_bf16 v[44:47], v[132:135], v[172:175], v[44:47]
	v_mfma_f32_16x16x32_bf16 v[40:43], v[140:143], v[172:175], v[40:43]
	v_mfma_f32_16x16x32_bf16 v[28:31], v[132:135], v[180:183], v[28:31]
	v_mfma_f32_16x16x32_bf16 v[24:27], v[140:143], v[180:183], v[24:27]
	v_mfma_f32_16x16x32_bf16 v[12:15], v[132:135], v[208:211], v[12:15]
	v_mfma_f32_16x16x32_bf16 v[8:11], v[140:143], v[208:211], v[8:11]
	v_mfma_f32_16x16x32_bf16 v[60:63], v[136:139], v[168:171], v[60:63]
	v_mfma_f32_16x16x32_bf16 v[56:59], v[144:147], v[168:171], v[56:59]
	v_mfma_f32_16x16x32_bf16 v[44:47], v[136:139], v[176:179], v[44:47]
	v_mfma_f32_16x16x32_bf16 v[40:43], v[144:147], v[176:179], v[40:43]
	v_mfma_f32_16x16x32_bf16 v[28:31], v[136:139], v[204:207], v[28:31]
	v_mfma_f32_16x16x32_bf16 v[24:27], v[144:147], v[204:207], v[24:27]
	v_mfma_f32_16x16x32_bf16 v[12:15], v[136:139], v[212:215], v[12:15]
	v_mfma_f32_16x16x32_bf16 v[8:11], v[144:147], v[212:215], v[8:11]
	s_setprio 0
	s_setprio 1
	v_mfma_f32_16x16x32_bf16 v[52:55], v[148:151], v[164:167], v[52:55]
	v_mfma_f32_16x16x32_bf16 v[48:51], v[156:159], v[164:167], v[48:51]
	v_mfma_f32_16x16x32_bf16 v[36:39], v[148:151], v[172:175], v[36:39]
	v_mfma_f32_16x16x32_bf16 v[32:35], v[156:159], v[172:175], v[32:35]
	v_mfma_f32_16x16x32_bf16 v[20:23], v[148:151], v[180:183], v[20:23]
	v_mfma_f32_16x16x32_bf16 v[16:19], v[156:159], v[180:183], v[16:19]
	v_mfma_f32_16x16x32_bf16 v[4:7], v[148:151], v[208:211], v[4:7]
	v_mfma_f32_16x16x32_bf16 v[0:3], v[156:159], v[208:211], v[0:3]
	v_mfma_f32_16x16x32_bf16 v[52:55], v[152:155], v[168:171], v[52:55]
	v_mfma_f32_16x16x32_bf16 v[48:51], v[160:163], v[168:171], v[48:51]
	v_mfma_f32_16x16x32_bf16 v[36:39], v[152:155], v[176:179], v[36:39]
	v_mfma_f32_16x16x32_bf16 v[32:35], v[160:163], v[176:179], v[32:35]
	v_mfma_f32_16x16x32_bf16 v[20:23], v[152:155], v[204:207], v[20:23]
	v_mfma_f32_16x16x32_bf16 v[16:19], v[160:163], v[204:207], v[16:19]
	v_mfma_f32_16x16x32_bf16 v[4:7], v[152:155], v[212:215], v[4:7]
	v_mfma_f32_16x16x32_bf16 v[0:3], v[160:163], v[212:215], v[0:3]
	s_barrier
	s_setprio 0
	s_add_u32 s38, s38, 0x100
	s_addc_u32 s39, s39, 0
	s_cmpk_eq_i32 s38, 0x800
	s_cbranch_scc1 .LBB0_1025
	s_branch .LBB0_1019
.LBB0_1018:
	ds_read_b128 v[132:135], v216
	ds_read_b128 v[136:139], v216 offset:1024
	ds_read_b128 v[140:143], v216 offset:2048
	ds_read_b128 v[144:147], v216 offset:3072
	ds_read_b128 v[148:151], v216 offset:16384
	ds_read_b128 v[152:155], v216 offset:17408
	ds_read_b128 v[156:159], v216 offset:18432
	ds_read_b128 v[160:163], v216 offset:19456
	s_add_i32 m0, s25, 0xc000
	ds_read_b128 v[164:167], v221
	ds_read_b128 v[168:171], v221 offset:1024
	ds_read_b128 v[172:175], v221 offset:2048
	ds_read_b128 v[176:179], v221 offset:3072
	ds_read_b128 v[180:183], v221 offset:4096
	ds_read_b128 v[204:207], v221 offset:5120
	ds_read_b128 v[208:211], v221 offset:6144
	global_load_lds_dwordx4 v196, s[100:101]
	s_add_i32 m0, s25, 0xe000
	ds_read_b128 v[212:215], v221 offset:7168
	global_load_lds_dwordx4 v198, s[100:101]
	s_waitcnt vmcnt(8)
	s_waitcnt lgkmcnt(0)
	s_setprio 1
	s_barrier
	v_mfma_f32_16x16x32_bf16 v[124:127], v[132:135], v[164:167], v[124:127]
	v_mfma_f32_16x16x32_bf16 v[120:123], v[140:143], v[164:167], v[120:123]
	v_mfma_f32_16x16x32_bf16 v[108:111], v[132:135], v[172:175], v[108:111]
	v_mfma_f32_16x16x32_bf16 v[104:107], v[140:143], v[172:175], v[104:107]
	v_mfma_f32_16x16x32_bf16 v[92:95], v[132:135], v[180:183], v[92:95]
	v_mfma_f32_16x16x32_bf16 v[88:91], v[140:143], v[180:183], v[88:91]
	v_mfma_f32_16x16x32_bf16 v[76:79], v[132:135], v[208:211], v[76:79]
	v_mfma_f32_16x16x32_bf16 v[72:75], v[140:143], v[208:211], v[72:75]
	v_mfma_f32_16x16x32_bf16 v[124:127], v[136:139], v[168:171], v[124:127]
	v_mfma_f32_16x16x32_bf16 v[120:123], v[144:147], v[168:171], v[120:123]
	v_mfma_f32_16x16x32_bf16 v[108:111], v[136:139], v[176:179], v[108:111]
	v_mfma_f32_16x16x32_bf16 v[104:107], v[144:147], v[176:179], v[104:107]
	v_mfma_f32_16x16x32_bf16 v[92:95], v[136:139], v[204:207], v[92:95]
	v_mfma_f32_16x16x32_bf16 v[88:91], v[144:147], v[204:207], v[88:91]
	v_mfma_f32_16x16x32_bf16 v[76:79], v[136:139], v[212:215], v[76:79]
	v_mfma_f32_16x16x32_bf16 v[72:75], v[144:147], v[212:215], v[72:75]
	s_setprio 0
	s_setprio 1
	v_mfma_f32_16x16x32_bf16 v[116:119], v[148:151], v[164:167], v[116:119]
	v_mfma_f32_16x16x32_bf16 v[112:115], v[156:159], v[164:167], v[112:115]
	v_mfma_f32_16x16x32_bf16 v[100:103], v[148:151], v[172:175], v[100:103]
	v_mfma_f32_16x16x32_bf16 v[96:99], v[156:159], v[172:175], v[96:99]
	v_mfma_f32_16x16x32_bf16 v[84:87], v[148:151], v[180:183], v[84:87]
	v_mfma_f32_16x16x32_bf16 v[80:83], v[156:159], v[180:183], v[80:83]
	v_mfma_f32_16x16x32_bf16 v[68:71], v[148:151], v[208:211], v[68:71]
	v_mfma_f32_16x16x32_bf16 v[64:67], v[156:159], v[208:211], v[64:67]
	v_mfma_f32_16x16x32_bf16 v[116:119], v[152:155], v[168:171], v[116:119]
	v_mfma_f32_16x16x32_bf16 v[112:115], v[160:163], v[168:171], v[112:115]
	v_mfma_f32_16x16x32_bf16 v[100:103], v[152:155], v[176:179], v[100:103]
	v_mfma_f32_16x16x32_bf16 v[96:99], v[160:163], v[176:179], v[96:99]
	v_mfma_f32_16x16x32_bf16 v[84:87], v[152:155], v[204:207], v[84:87]
	v_mfma_f32_16x16x32_bf16 v[80:83], v[160:163], v[204:207], v[80:83]
	v_mfma_f32_16x16x32_bf16 v[68:71], v[152:155], v[212:215], v[68:71]
	v_mfma_f32_16x16x32_bf16 v[64:67], v[160:163], v[212:215], v[64:67]
	s_barrier
	s_setprio 0
	s_add_i32 s10, s61, s50
	s_mov_b32 m0, s10
	ds_read_b128 v[164:167], v221 offset:16384
	ds_read_b128 v[168:171], v221 offset:17408
	ds_read_b128 v[172:175], v221 offset:18432
	global_load_lds_dwordx4 v186, s[44:45]
	s_add_i32 m0, s10, 0x2000
	ds_read_b128 v[176:179], v221 offset:19456
	global_load_lds_dwordx4 v190, s[44:45]
	s_add_u32 s44, s44, 0x40000
	s_addc_u32 s45, s45, 0
	s_add_i32 s10, s62, s50
	s_mov_b32 m0, s10
	ds_read_b128 v[180:183], v221 offset:20480
	global_load_lds_dwordx4 v186, s[44:45]
	s_add_i32 m0, s10, 0x2000
	ds_read_b128 v[204:207], v221 offset:21504
	global_load_lds_dwordx4 v190, s[44:45]
	s_mov_b32 m0, s25
	ds_read_b128 v[208:211], v221 offset:22528
	global_load_lds_dwordx4 v184, s[46:47]
	s_mov_b32 m0, s51
	ds_read_b128 v[212:215], v221 offset:23552
	global_load_lds_dwordx4 v188, s[46:47]
	s_waitcnt vmcnt(8)
	s_waitcnt lgkmcnt(0)
	s_setprio 1
	s_barrier
	v_mfma_f32_16x16x32_bf16 v[60:63], v[132:135], v[164:167], v[60:63]
	v_mfma_f32_16x16x32_bf16 v[56:59], v[140:143], v[164:167], v[56:59]
	v_mfma_f32_16x16x32_bf16 v[44:47], v[132:135], v[172:175], v[44:47]
	v_mfma_f32_16x16x32_bf16 v[40:43], v[140:143], v[172:175], v[40:43]
	v_mfma_f32_16x16x32_bf16 v[28:31], v[132:135], v[180:183], v[28:31]
	v_mfma_f32_16x16x32_bf16 v[24:27], v[140:143], v[180:183], v[24:27]
	v_mfma_f32_16x16x32_bf16 v[12:15], v[132:135], v[208:211], v[12:15]
	v_mfma_f32_16x16x32_bf16 v[8:11], v[140:143], v[208:211], v[8:11]
	v_mfma_f32_16x16x32_bf16 v[60:63], v[136:139], v[168:171], v[60:63]
	v_mfma_f32_16x16x32_bf16 v[56:59], v[144:147], v[168:171], v[56:59]
	v_mfma_f32_16x16x32_bf16 v[44:47], v[136:139], v[176:179], v[44:47]
	v_mfma_f32_16x16x32_bf16 v[40:43], v[144:147], v[176:179], v[40:43]
	v_mfma_f32_16x16x32_bf16 v[28:31], v[136:139], v[204:207], v[28:31]
	v_mfma_f32_16x16x32_bf16 v[24:27], v[144:147], v[204:207], v[24:27]
	v_mfma_f32_16x16x32_bf16 v[12:15], v[136:139], v[212:215], v[12:15]
	v_mfma_f32_16x16x32_bf16 v[8:11], v[144:147], v[212:215], v[8:11]
	s_setprio 0
	s_setprio 1
	v_mfma_f32_16x16x32_bf16 v[52:55], v[148:151], v[164:167], v[52:55]
	v_mfma_f32_16x16x32_bf16 v[48:51], v[156:159], v[164:167], v[48:51]
	v_mfma_f32_16x16x32_bf16 v[36:39], v[148:151], v[172:175], v[36:39]
	v_mfma_f32_16x16x32_bf16 v[32:35], v[156:159], v[172:175], v[32:35]
	v_mfma_f32_16x16x32_bf16 v[20:23], v[148:151], v[180:183], v[20:23]
	v_mfma_f32_16x16x32_bf16 v[16:19], v[156:159], v[180:183], v[16:19]
	v_mfma_f32_16x16x32_bf16 v[4:7], v[148:151], v[208:211], v[4:7]
	v_mfma_f32_16x16x32_bf16 v[0:3], v[156:159], v[208:211], v[0:3]
	v_mfma_f32_16x16x32_bf16 v[52:55], v[152:155], v[168:171], v[52:55]
	v_mfma_f32_16x16x32_bf16 v[48:51], v[160:163], v[168:171], v[48:51]
	v_mfma_f32_16x16x32_bf16 v[36:39], v[152:155], v[176:179], v[36:39]
	v_mfma_f32_16x16x32_bf16 v[32:35], v[160:163], v[176:179], v[32:35]
	v_mfma_f32_16x16x32_bf16 v[20:23], v[152:155], v[204:207], v[20:23]
	v_mfma_f32_16x16x32_bf16 v[16:19], v[160:163], v[204:207], v[16:19]
	v_mfma_f32_16x16x32_bf16 v[4:7], v[152:155], v[212:215], v[4:7]
	v_mfma_f32_16x16x32_bf16 v[0:3], v[160:163], v[212:215], v[0:3]
	s_barrier
	s_setprio 0
	s_add_i32 s10, 0, 0x18000
	s_add_i32 s72, 0, 0x1c000
	ds_read_b128 v[132:135], v216 offset:32768
	ds_read_b128 v[136:139], v216 offset:33792
	ds_read_b128 v[140:143], v216 offset:34816
	ds_read_b128 v[144:147], v216 offset:35840
	ds_read_b128 v[148:151], v216 offset:49152
	ds_read_b128 v[152:155], v216 offset:50176
	ds_read_b128 v[156:159], v216 offset:51200
	ds_read_b128 v[160:163], v216 offset:52224
	s_add_u32 s44, s46, 0x40000
	s_addc_u32 s45, s47, 0
	s_mov_b32 m0, s52
	ds_read_b128 v[164:167], v221 offset:32768
	ds_read_b128 v[168:171], v221 offset:33792
	ds_read_b128 v[172:175], v221 offset:34816
	ds_read_b128 v[176:179], v221 offset:35840
	ds_read_b128 v[180:183], v221 offset:36864
	ds_read_b128 v[204:207], v221 offset:37888
	ds_read_b128 v[208:211], v221 offset:38912
	global_load_lds_dwordx4 v184, s[44:45]
	s_mov_b32 m0, s53
	ds_read_b128 v[212:215], v221 offset:39936
	global_load_lds_dwordx4 v188, s[44:45]
	s_waitcnt vmcnt(8)
	s_waitcnt lgkmcnt(0)
	s_setprio 1
	s_barrier
	v_mfma_f32_16x16x32_bf16 v[124:127], v[132:135], v[164:167], v[124:127]
	v_mfma_f32_16x16x32_bf16 v[120:123], v[140:143], v[164:167], v[120:123]
	v_mfma_f32_16x16x32_bf16 v[108:111], v[132:135], v[172:175], v[108:111]
	v_mfma_f32_16x16x32_bf16 v[104:107], v[140:143], v[172:175], v[104:107]
	v_mfma_f32_16x16x32_bf16 v[92:95], v[132:135], v[180:183], v[92:95]
	v_mfma_f32_16x16x32_bf16 v[88:91], v[140:143], v[180:183], v[88:91]
	v_mfma_f32_16x16x32_bf16 v[76:79], v[132:135], v[208:211], v[76:79]
	v_mfma_f32_16x16x32_bf16 v[72:75], v[140:143], v[208:211], v[72:75]
	v_mfma_f32_16x16x32_bf16 v[124:127], v[136:139], v[168:171], v[124:127]
	v_mfma_f32_16x16x32_bf16 v[120:123], v[144:147], v[168:171], v[120:123]
	v_mfma_f32_16x16x32_bf16 v[108:111], v[136:139], v[176:179], v[108:111]
	v_mfma_f32_16x16x32_bf16 v[104:107], v[144:147], v[176:179], v[104:107]
	v_mfma_f32_16x16x32_bf16 v[92:95], v[136:139], v[204:207], v[92:95]
	v_mfma_f32_16x16x32_bf16 v[88:91], v[144:147], v[204:207], v[88:91]
	v_mfma_f32_16x16x32_bf16 v[76:79], v[136:139], v[212:215], v[76:79]
	v_mfma_f32_16x16x32_bf16 v[72:75], v[144:147], v[212:215], v[72:75]
	s_setprio 0
	s_setprio 1
	v_mfma_f32_16x16x32_bf16 v[116:119], v[148:151], v[164:167], v[116:119]
	v_mfma_f32_16x16x32_bf16 v[112:115], v[156:159], v[164:167], v[112:115]
	v_mfma_f32_16x16x32_bf16 v[100:103], v[148:151], v[172:175], v[100:103]
	v_mfma_f32_16x16x32_bf16 v[96:99], v[156:159], v[172:175], v[96:99]
	v_mfma_f32_16x16x32_bf16 v[84:87], v[148:151], v[180:183], v[84:87]
	v_mfma_f32_16x16x32_bf16 v[80:83], v[156:159], v[180:183], v[80:83]
	v_mfma_f32_16x16x32_bf16 v[68:71], v[148:151], v[208:211], v[68:71]
	v_mfma_f32_16x16x32_bf16 v[64:67], v[156:159], v[208:211], v[64:67]
	v_mfma_f32_16x16x32_bf16 v[116:119], v[152:155], v[168:171], v[116:119]
	v_mfma_f32_16x16x32_bf16 v[112:115], v[160:163], v[168:171], v[112:115]
	v_mfma_f32_16x16x32_bf16 v[100:103], v[152:155], v[176:179], v[100:103]
	v_mfma_f32_16x16x32_bf16 v[96:99], v[160:163], v[176:179], v[96:99]
	v_mfma_f32_16x16x32_bf16 v[84:87], v[152:155], v[204:207], v[84:87]
	v_mfma_f32_16x16x32_bf16 v[80:83], v[160:163], v[204:207], v[80:83]
	v_mfma_f32_16x16x32_bf16 v[68:71], v[152:155], v[212:215], v[68:71]
	v_mfma_f32_16x16x32_bf16 v[64:67], v[160:163], v[212:215], v[64:67]
	s_barrier
	s_setprio 0
	s_add_i32 s10, s10, s50
	s_mov_b32 m0, s10
	ds_read_b128 v[164:167], v221 offset:49152
	ds_read_b128 v[168:171], v221 offset:50176
	ds_read_b128 v[172:175], v221 offset:51200
	global_load_lds_dwordx4 v186, s[42:43]
	s_add_i32 m0, s10, 0x2000
	ds_read_b128 v[176:179], v221 offset:52224
	global_load_lds_dwordx4 v190, s[42:43]
	s_add_u32 s42, s42, 0x40000
	s_addc_u32 s43, s43, 0
	s_add_i32 s10, s72, s50
	s_mov_b32 m0, s10
	ds_read_b128 v[180:183], v221 offset:53248
	global_load_lds_dwordx4 v186, s[42:43]
	s_add_i32 m0, s10, 0x2000
	ds_read_b128 v[204:207], v221 offset:54272
	global_load_lds_dwordx4 v190, s[42:43]
	s_mov_b32 m0, s58
	ds_read_b128 v[208:211], v221 offset:55296
	global_load_lds_dwordx4 v184, s[40:41]
	s_mov_b32 m0, s59
	ds_read_b128 v[212:215], v221 offset:56320
	global_load_lds_dwordx4 v188, s[40:41]
	s_waitcnt vmcnt(8)
	s_waitcnt lgkmcnt(0)
	s_setprio 1
	s_barrier
	v_mfma_f32_16x16x32_bf16 v[60:63], v[132:135], v[164:167], v[60:63]
	v_mfma_f32_16x16x32_bf16 v[56:59], v[140:143], v[164:167], v[56:59]
	v_mfma_f32_16x16x32_bf16 v[44:47], v[132:135], v[172:175], v[44:47]
	v_mfma_f32_16x16x32_bf16 v[40:43], v[140:143], v[172:175], v[40:43]
	v_mfma_f32_16x16x32_bf16 v[28:31], v[132:135], v[180:183], v[28:31]
	v_mfma_f32_16x16x32_bf16 v[24:27], v[140:143], v[180:183], v[24:27]
	v_mfma_f32_16x16x32_bf16 v[12:15], v[132:135], v[208:211], v[12:15]
	v_mfma_f32_16x16x32_bf16 v[8:11], v[140:143], v[208:211], v[8:11]
	v_mfma_f32_16x16x32_bf16 v[60:63], v[136:139], v[168:171], v[60:63]
	v_mfma_f32_16x16x32_bf16 v[56:59], v[144:147], v[168:171], v[56:59]
	v_mfma_f32_16x16x32_bf16 v[44:47], v[136:139], v[176:179], v[44:47]
	v_mfma_f32_16x16x32_bf16 v[40:43], v[144:147], v[176:179], v[40:43]
	v_mfma_f32_16x16x32_bf16 v[28:31], v[136:139], v[204:207], v[28:31]
	v_mfma_f32_16x16x32_bf16 v[24:27], v[144:147], v[204:207], v[24:27]
	v_mfma_f32_16x16x32_bf16 v[12:15], v[136:139], v[212:215], v[12:15]
	v_mfma_f32_16x16x32_bf16 v[8:11], v[144:147], v[212:215], v[8:11]
	s_setprio 0
	s_setprio 1
	v_mfma_f32_16x16x32_bf16 v[52:55], v[148:151], v[164:167], v[52:55]
	v_mfma_f32_16x16x32_bf16 v[48:51], v[156:159], v[164:167], v[48:51]
	v_mfma_f32_16x16x32_bf16 v[36:39], v[148:151], v[172:175], v[36:39]
	v_mfma_f32_16x16x32_bf16 v[32:35], v[156:159], v[172:175], v[32:35]
	v_mfma_f32_16x16x32_bf16 v[20:23], v[148:151], v[180:183], v[20:23]
	v_mfma_f32_16x16x32_bf16 v[16:19], v[156:159], v[180:183], v[16:19]
	v_mfma_f32_16x16x32_bf16 v[4:7], v[148:151], v[208:211], v[4:7]
	v_mfma_f32_16x16x32_bf16 v[0:3], v[156:159], v[208:211], v[0:3]
	v_mfma_f32_16x16x32_bf16 v[52:55], v[152:155], v[168:171], v[52:55]
	v_mfma_f32_16x16x32_bf16 v[48:51], v[160:163], v[168:171], v[48:51]
	v_mfma_f32_16x16x32_bf16 v[36:39], v[152:155], v[176:179], v[36:39]
	v_mfma_f32_16x16x32_bf16 v[32:35], v[160:163], v[176:179], v[32:35]
	v_mfma_f32_16x16x32_bf16 v[20:23], v[152:155], v[204:207], v[20:23]
	v_mfma_f32_16x16x32_bf16 v[16:19], v[160:163], v[204:207], v[16:19]
	v_mfma_f32_16x16x32_bf16 v[4:7], v[152:155], v[212:215], v[4:7]
	v_mfma_f32_16x16x32_bf16 v[0:3], v[160:163], v[212:215], v[0:3]
	s_barrier
	s_setprio 0
	s_add_u32 s38, s38, 0x100
	s_addc_u32 s39, s39, 0
	s_cmpk_eq_i32 s38, 0x800
	s_cbranch_scc1 .LBB0_1025
